# phase-split k-loops (load phase / 16-MFMA phase x2 per k-step, waves 4-7 one phase behind, setprio on MFMA clusters) on all seven GEMM loops
# speedup vs baseline: 1.0355x; 1.0130x over previous
; __device__ __forceinline__ int otid() { int t = threadIdx.x; asm volatile("" : "+v"(t)); return t; }
; #define GEMM_WAITV(n) asm volatile("s_waitcnt vmcnt(" #n ")" ::: "memory")
; template <bool SWAP>
; __device__ __forceinline__ void gemm_main(f32x4 (&acc)[8][4], const TP& t, int nk, char* lds) {
;   const u16* a0 = t.a0; const u16* a1 = t.a1; const u16* b0 = t.b0; const u16* b1 = t.b1;
;   const int tid = otid(), lane = tid & 63, wave = tid >> 6;
;   const int wm = wave >> 2, wn = wave & 3, lr = lane & 15, lq = lane >> 4;
;   const int ldoff = wave * 2048 + lane * 16;
;   const int sw = (lq ^ ((0 - (lr >> 2)) & 3)) << 4;
;   const int aoff = (wm * 128 + lr) * 64 + sw, boff = T_ASTAGE + (wn * 64 + lr) * 64 + sw;
;     ...
; #pragma unroll 1
;   for (int kt = 0; kt < nk - 3; ++kt) {
;     GEMM_WAITV(8);
;     GEMM_STEP(kt, true)
; __device__ __forceinline__ void zero_acc(f32x4 (&acc)[8][4]) {
; #pragma unroll
;   for (int i = 0; i < 8; ++i)
; #pragma unroll
;     for (int j = 0; j < 4; ++j) acc[i][j] = (f32x4){0.f, 0.f, 0.f, 0.f};
.LBB0_385:
	s_mov_b64 s[34:35], -1
	s_andn2_b64 vcc, exec, s[36:37]
	v_lshl_add_u64 v[128:129], v[158:159], 0, s[20:21]
	v_lshl_add_u64 v[130:131], v[156:157], 0, s[20:21]
	v_lshl_add_u64 v[132:133], v[146:147], 0, s[20:21]
	v_lshl_add_u64 v[134:135], v[160:161], 0, s[20:21]
	s_cbranch_vccz .LBB0_401
	v_mov_b32_e32 v0, v153
	v_lshl_add_u64 v[136:137], v[158:159], 0, s[20:21]
	v_lshlrev_b32_e32 v3, 2, v0
	v_and_b32_e32 v3, 48, v3
	v_sub_u32_e32 v3, 0, v3
	v_and_b32_e32 v164, 15, v0
	v_lshlrev_b32_e32 v1, 5, v0
	v_lshlrev_b32_e32 v2, 4, v0
	v_bitop3_b32 v165, v0, 48, v3 bitop3:0x48
	v_ashrrev_i32_e32 v166, 1, v0
	v_lshlrev_b32_e32 v0, 6, v0
	v_and_b32_e32 v1, 0xfffff800, v1
	v_and_b32_e32 v2, 0x3f0, v2
	v_and_or_b32 v3, v166, s41, v164
	v_and_b32_e32 v167, 0x33c0, v0
	v_mov_b32_e32 v0, 0
	v_lshl_or_b32 v168, v3, 6, v165
	v_or_b32_e32 v170, v167, v165
	v_add3_u32 v171, 0, v1, v2
	v_lshl_add_u64 v[138:139], v[156:157], 0, s[20:21]
	v_lshl_add_u64 v[140:141], v[146:147], 0, s[20:21]
	v_lshl_add_u64 v[142:143], v[160:161], 0, s[20:21]
	s_mov_b32 s34, 0x18000
	v_mov_b32_e32 v1, v0
	v_mov_b32_e32 v2, v0
	v_mov_b32_e32 v3, v0
	v_mov_b32_e32 v4, v0
	v_mov_b32_e32 v5, v0
	v_mov_b32_e32 v6, v0
	v_mov_b32_e32 v7, v0
	v_mov_b32_e32 v8, v0
	v_mov_b32_e32 v9, v0
	v_mov_b32_e32 v10, v0
	v_mov_b32_e32 v11, v0
	v_mov_b32_e32 v12, v0
	v_mov_b32_e32 v13, v0
	v_mov_b32_e32 v14, v0
	v_mov_b32_e32 v15, v0
	v_mov_b32_e32 v16, v0
	v_mov_b32_e32 v17, v0
	v_mov_b32_e32 v18, v0
	v_mov_b32_e32 v19, v0
	v_mov_b32_e32 v20, v0
	v_mov_b32_e32 v21, v0
	v_mov_b32_e32 v22, v0
	v_mov_b32_e32 v23, v0
	v_mov_b32_e32 v24, v0
	v_mov_b32_e32 v25, v0
	v_mov_b32_e32 v26, v0
	v_mov_b32_e32 v27, v0
	v_mov_b32_e32 v28, v0
	v_mov_b32_e32 v29, v0
	v_mov_b32_e32 v30, v0
	v_mov_b32_e32 v31, v0
	v_mov_b32_e32 v32, v0
	v_mov_b32_e32 v33, v0
	v_mov_b32_e32 v34, v0
	v_mov_b32_e32 v35, v0
	v_mov_b32_e32 v36, v0
	v_mov_b32_e32 v37, v0
	v_mov_b32_e32 v38, v0
	v_mov_b32_e32 v39, v0
	v_mov_b32_e32 v40, v0
	v_mov_b32_e32 v41, v0
	v_mov_b32_e32 v42, v0
	v_mov_b32_e32 v43, v0
	v_mov_b32_e32 v44, v0
	v_mov_b32_e32 v45, v0
	v_mov_b32_e32 v46, v0
	v_mov_b32_e32 v47, v0
	v_mov_b32_e32 v48, v0
	v_mov_b32_e32 v49, v0
	v_mov_b32_e32 v50, v0
	v_mov_b32_e32 v51, v0
	v_mov_b32_e32 v52, v0
	v_mov_b32_e32 v53, v0
	v_mov_b32_e32 v54, v0
	v_mov_b32_e32 v55, v0
	v_mov_b32_e32 v56, v0
	v_mov_b32_e32 v57, v0
	v_mov_b32_e32 v58, v0
	v_mov_b32_e32 v59, v0
	v_mov_b32_e32 v60, v0
	v_mov_b32_e32 v61, v0
	v_mov_b32_e32 v62, v0
	v_mov_b32_e32 v63, v0
	v_mov_b32_e32 v64, v0
	v_mov_b32_e32 v65, v0
	v_mov_b32_e32 v66, v0
	v_mov_b32_e32 v67, v0
	v_mov_b32_e32 v68, v0
	v_mov_b32_e32 v69, v0
	v_mov_b32_e32 v70, v0
	v_mov_b32_e32 v71, v0
	v_mov_b32_e32 v72, v0
	v_mov_b32_e32 v73, v0
	v_mov_b32_e32 v74, v0
	v_mov_b32_e32 v75, v0
	v_mov_b32_e32 v76, v0
	v_mov_b32_e32 v77, v0
	v_mov_b32_e32 v78, v0
	v_mov_b32_e32 v79, v0
	v_mov_b32_e32 v80, v0
	v_mov_b32_e32 v81, v0
	v_mov_b32_e32 v82, v0
	v_mov_b32_e32 v83, v0
	v_mov_b32_e32 v84, v0
	v_mov_b32_e32 v85, v0
	v_mov_b32_e32 v86, v0
	v_mov_b32_e32 v87, v0
	v_mov_b32_e32 v88, v0
	v_mov_b32_e32 v89, v0
	v_mov_b32_e32 v90, v0
	v_mov_b32_e32 v91, v0
	v_mov_b32_e32 v92, v0
	v_mov_b32_e32 v93, v0
	v_mov_b32_e32 v94, v0
	v_mov_b32_e32 v95, v0
	v_mov_b32_e32 v96, v0
	v_mov_b32_e32 v97, v0
	v_mov_b32_e32 v98, v0
	v_mov_b32_e32 v99, v0
	v_mov_b32_e32 v100, v0
	v_mov_b32_e32 v101, v0
	v_mov_b32_e32 v102, v0
	v_mov_b32_e32 v103, v0
	v_mov_b32_e32 v104, v0
	v_mov_b32_e32 v105, v0
	v_mov_b32_e32 v106, v0
	v_mov_b32_e32 v107, v0
	v_mov_b32_e32 v108, v0
	v_mov_b32_e32 v109, v0
	v_mov_b32_e32 v110, v0
	v_mov_b32_e32 v111, v0
	v_mov_b32_e32 v112, v0
	v_mov_b32_e32 v113, v0
	v_mov_b32_e32 v114, v0
	v_mov_b32_e32 v115, v0
	v_mov_b32_e32 v116, v0
	v_mov_b32_e32 v117, v0
	v_mov_b32_e32 v118, v0
	v_mov_b32_e32 v119, v0
	v_mov_b32_e32 v120, v0
	v_mov_b32_e32 v121, v0
	v_mov_b32_e32 v122, v0
	v_mov_b32_e32 v123, v0
	v_mov_b32_e32 v124, v0
	v_mov_b32_e32 v125, v0
	v_mov_b32_e32 v126, v0
	v_mov_b32_e32 v127, v0
	v_readfirstlane_b32 s98, v171
	s_waitcnt vmcnt(8)
	s_barrier
	s_cmp_lt_u32 s98, 0x2000
	s_cbranch_scc1 .Lp2a_top
	s_barrier
.Lp2a_top:
	s_add_i32 s35, s34, 0xfffe8000
	s_and_b32 s35, s35, 0x18000
	v_add_u32_e32 v235, s35, v168
	v_add_u32_e32 v236, s35, v170
	ds_read_b128 v[184:187], v235
	ds_read_b128 v[156:159], v236 offset:16384
	ds_read_b128 v[172:175], v236 offset:17408
	ds_read_b128 v[176:179], v236 offset:18432
	ds_read_b128 v[180:183], v236 offset:19456
	ds_read_b128 v[188:191], v235 offset:1024
	ds_read_b128 v[192:195], v235 offset:2048
	ds_read_b128 v[198:201], v235 offset:3072
	s_and_b32 s99, s34, 0x18000
	s_add_i32 s99, s99, s98
	s_mov_b32 m0, s99
	s_nop 0
	global_load_lds_dwordx4 v[136:137], off
	s_add_i32 m0, s99, 0x400
	s_nop 0
	global_load_lds_dwordx4 v[138:139], off
	s_waitcnt lgkmcnt(0)
	s_barrier
	s_setprio 1
	v_mfma_f32_16x16x32_bf16 v[124:127], v[184:187], v[156:159], v[124:127]
	v_mfma_f32_16x16x32_bf16 v[120:123], v[184:187], v[172:175], v[120:123]
	v_mfma_f32_16x16x32_bf16 v[116:119], v[184:187], v[176:179], v[116:119]
	v_mfma_f32_16x16x32_bf16 v[112:115], v[184:187], v[180:183], v[112:115]
	v_mfma_f32_16x16x32_bf16 v[108:111], v[188:191], v[156:159], v[108:111]
	v_mfma_f32_16x16x32_bf16 v[104:107], v[188:191], v[172:175], v[104:107]
	v_mfma_f32_16x16x32_bf16 v[100:103], v[188:191], v[176:179], v[100:103]
	v_mfma_f32_16x16x32_bf16 v[96:99], v[188:191], v[180:183], v[96:99]
	v_mfma_f32_16x16x32_bf16 v[92:95], v[192:195], v[156:159], v[92:95]
	v_mfma_f32_16x16x32_bf16 v[88:91], v[192:195], v[172:175], v[88:91]
	v_mfma_f32_16x16x32_bf16 v[84:87], v[192:195], v[176:179], v[84:87]
	v_mfma_f32_16x16x32_bf16 v[80:83], v[192:195], v[180:183], v[80:83]
	v_mfma_f32_16x16x32_bf16 v[76:79], v[198:201], v[156:159], v[76:79]
	v_mfma_f32_16x16x32_bf16 v[72:75], v[198:201], v[172:175], v[72:75]
	v_mfma_f32_16x16x32_bf16 v[68:71], v[198:201], v[176:179], v[68:71]
	v_mfma_f32_16x16x32_bf16 v[64:67], v[198:201], v[180:183], v[64:67]
	s_setprio 0
	s_barrier
; #define GEMM_WAITV(n) asm volatile("s_waitcnt vmcnt(" #n ")" ::: "memory")
; template <bool SWAP>
; __device__ __forceinline__ void gemm_main(f32x4 (&acc)[8][4], const TP& t, int nk, char* lds) {
;     ...
; #pragma unroll 1
;   for (int kt = 0; kt < nk - 3; ++kt) {
;     GEMM_WAITV(8);
;     GEMM_STEP(kt, true)
;   }
; #pragma unroll 1
;   for (int kt = nk - 3; kt < nk; ++kt) {
;     const int rem = nk - kt;
;     if (rem == 3) GEMM_WAITV(8); else if (rem == 2) GEMM_WAITV(4); else GEMM_WAITV(0);
;     GEMM_STEP(kt, false)
;   }
	ds_read_b128 v[184:187], v235 offset:4096
	ds_read_b128 v[188:191], v235 offset:5120
	ds_read_b128 v[192:195], v235 offset:6144
	ds_read_b128 v[198:201], v235 offset:7168
	s_add_i32 m0, s99, 0x4000
	s_nop 0
	global_load_lds_dwordx4 v[140:141], off
	s_add_i32 m0, s99, 0x4400
	s_nop 0
	global_load_lds_dwordx4 v[142:143], off
	v_lshl_add_u64 v[136:137], v[136:137], 0, 64
	v_lshl_add_u64 v[138:139], v[138:139], 0, 64
	v_lshl_add_u64 v[140:141], v[140:141], 0, 64
	v_lshl_add_u64 v[142:143], v[142:143], 0, 64
	s_add_i32 s34, s34, 0x8000
	s_waitcnt vmcnt(8)
	s_waitcnt lgkmcnt(0)
	s_barrier
	s_setprio 1
	v_mfma_f32_16x16x32_bf16 v[60:63], v[184:187], v[156:159], v[60:63]
	v_mfma_f32_16x16x32_bf16 v[56:59], v[184:187], v[172:175], v[56:59]
	v_mfma_f32_16x16x32_bf16 v[52:55], v[184:187], v[176:179], v[52:55]
	v_mfma_f32_16x16x32_bf16 v[48:51], v[184:187], v[180:183], v[48:51]
	v_mfma_f32_16x16x32_bf16 v[44:47], v[188:191], v[156:159], v[44:47]
	v_mfma_f32_16x16x32_bf16 v[40:43], v[188:191], v[172:175], v[40:43]
	v_mfma_f32_16x16x32_bf16 v[36:39], v[188:191], v[176:179], v[36:39]
	v_mfma_f32_16x16x32_bf16 v[32:35], v[188:191], v[180:183], v[32:35]
	v_mfma_f32_16x16x32_bf16 v[28:31], v[192:195], v[156:159], v[28:31]
	v_mfma_f32_16x16x32_bf16 v[24:27], v[192:195], v[172:175], v[24:27]
	v_mfma_f32_16x16x32_bf16 v[20:23], v[192:195], v[176:179], v[20:23]
	v_mfma_f32_16x16x32_bf16 v[16:19], v[192:195], v[180:183], v[16:19]
	v_mfma_f32_16x16x32_bf16 v[12:15], v[198:201], v[156:159], v[12:15]
	v_mfma_f32_16x16x32_bf16 v[8:11], v[198:201], v[172:175], v[8:11]
	v_mfma_f32_16x16x32_bf16 v[4:7], v[198:201], v[176:179], v[4:7]
	v_mfma_f32_16x16x32_bf16 v[0:3], v[198:201], v[180:183], v[0:3]
	s_setprio 0
	s_barrier
	s_cmp_lg_u32 s34, 0x100000
	s_cbranch_scc1 .Lp2a_top
	v_add_u32_e32 v235, 0x8000, v168
	v_add_u32_e32 v236, 0x8000, v170
	ds_read_b128 v[184:187], v235
	ds_read_b128 v[156:159], v236 offset:16384
	ds_read_b128 v[172:175], v236 offset:17408
	ds_read_b128 v[176:179], v236 offset:18432
	ds_read_b128 v[180:183], v236 offset:19456
	ds_read_b128 v[188:191], v235 offset:1024
	ds_read_b128 v[192:195], v235 offset:2048
	ds_read_b128 v[198:201], v235 offset:3072
	s_waitcnt lgkmcnt(0)
	s_barrier
	s_setprio 1
	v_mfma_f32_16x16x32_bf16 v[124:127], v[184:187], v[156:159], v[124:127]
	v_mfma_f32_16x16x32_bf16 v[120:123], v[184:187], v[172:175], v[120:123]
	v_mfma_f32_16x16x32_bf16 v[116:119], v[184:187], v[176:179], v[116:119]
	v_mfma_f32_16x16x32_bf16 v[112:115], v[184:187], v[180:183], v[112:115]
	v_mfma_f32_16x16x32_bf16 v[108:111], v[188:191], v[156:159], v[108:111]
	v_mfma_f32_16x16x32_bf16 v[104:107], v[188:191], v[172:175], v[104:107]
	v_mfma_f32_16x16x32_bf16 v[100:103], v[188:191], v[176:179], v[100:103]
	v_mfma_f32_16x16x32_bf16 v[96:99], v[188:191], v[180:183], v[96:99]
	v_mfma_f32_16x16x32_bf16 v[92:95], v[192:195], v[156:159], v[92:95]
	v_mfma_f32_16x16x32_bf16 v[88:91], v[192:195], v[172:175], v[88:91]
	v_mfma_f32_16x16x32_bf16 v[84:87], v[192:195], v[176:179], v[84:87]
	v_mfma_f32_16x16x32_bf16 v[80:83], v[192:195], v[180:183], v[80:83]
	v_mfma_f32_16x16x32_bf16 v[76:79], v[198:201], v[156:159], v[76:79]
	v_mfma_f32_16x16x32_bf16 v[72:75], v[198:201], v[172:175], v[72:75]
	v_mfma_f32_16x16x32_bf16 v[68:71], v[198:201], v[176:179], v[68:71]
	v_mfma_f32_16x16x32_bf16 v[64:67], v[198:201], v[180:183], v[64:67]
	s_setprio 0
	s_barrier
	ds_read_b128 v[184:187], v235 offset:4096
	ds_read_b128 v[188:191], v235 offset:5120
	ds_read_b128 v[192:195], v235 offset:6144
	ds_read_b128 v[198:201], v235 offset:7168
	s_waitcnt vmcnt(4)
	s_waitcnt lgkmcnt(0)
	s_barrier
	s_setprio 1
	v_mfma_f32_16x16x32_bf16 v[60:63], v[184:187], v[156:159], v[60:63]
	v_mfma_f32_16x16x32_bf16 v[56:59], v[184:187], v[172:175], v[56:59]
	v_mfma_f32_16x16x32_bf16 v[52:55], v[184:187], v[176:179], v[52:55]
	v_mfma_f32_16x16x32_bf16 v[48:51], v[184:187], v[180:183], v[48:51]
	v_mfma_f32_16x16x32_bf16 v[44:47], v[188:191], v[156:159], v[44:47]
	v_mfma_f32_16x16x32_bf16 v[40:43], v[188:191], v[172:175], v[40:43]
	v_mfma_f32_16x16x32_bf16 v[36:39], v[188:191], v[176:179], v[36:39]
	v_mfma_f32_16x16x32_bf16 v[32:35], v[188:191], v[180:183], v[32:35]
	v_mfma_f32_16x16x32_bf16 v[28:31], v[192:195], v[156:159], v[28:31]
	v_mfma_f32_16x16x32_bf16 v[24:27], v[192:195], v[172:175], v[24:27]
	v_mfma_f32_16x16x32_bf16 v[20:23], v[192:195], v[176:179], v[20:23]
	v_mfma_f32_16x16x32_bf16 v[16:19], v[192:195], v[180:183], v[16:19]
	v_mfma_f32_16x16x32_bf16 v[12:15], v[198:201], v[156:159], v[12:15]
	v_mfma_f32_16x16x32_bf16 v[8:11], v[198:201], v[172:175], v[8:11]
	v_mfma_f32_16x16x32_bf16 v[4:7], v[198:201], v[176:179], v[4:7]
	v_mfma_f32_16x16x32_bf16 v[0:3], v[198:201], v[180:183], v[0:3]
	s_setprio 0
	s_barrier
	v_add_u32_e32 v235, 0x10000, v168
	v_add_u32_e32 v236, 0x10000, v170
	ds_read_b128 v[184:187], v235
	ds_read_b128 v[156:159], v236 offset:16384
	ds_read_b128 v[172:175], v236 offset:17408
	ds_read_b128 v[176:179], v236 offset:18432
	ds_read_b128 v[180:183], v236 offset:19456
	ds_read_b128 v[188:191], v235 offset:1024
	ds_read_b128 v[192:195], v235 offset:2048
	ds_read_b128 v[198:201], v235 offset:3072
	s_waitcnt lgkmcnt(0)
	s_barrier
; #define GEMM_WAITV(n) asm volatile("s_waitcnt vmcnt(" #n ")" ::: "memory")
; template <bool SWAP>
; __device__ __forceinline__ void gemm_main(f32x4 (&acc)[8][4], const TP& t, int nk, char* lds) {
;     ...
; #pragma unroll 1
;   for (int kt = nk - 3; kt < nk; ++kt) {
;     const int rem = nk - kt;
;     if (rem == 3) GEMM_WAITV(8); else if (rem == 2) GEMM_WAITV(4); else GEMM_WAITV(0);
;     GEMM_STEP(kt, false)
;   }
;   __builtin_amdgcn_s_barrier();
	s_setprio 1
	v_mfma_f32_16x16x32_bf16 v[124:127], v[184:187], v[156:159], v[124:127]
	v_mfma_f32_16x16x32_bf16 v[120:123], v[184:187], v[172:175], v[120:123]
	v_mfma_f32_16x16x32_bf16 v[116:119], v[184:187], v[176:179], v[116:119]
	v_mfma_f32_16x16x32_bf16 v[112:115], v[184:187], v[180:183], v[112:115]
	v_mfma_f32_16x16x32_bf16 v[108:111], v[188:191], v[156:159], v[108:111]
	v_mfma_f32_16x16x32_bf16 v[104:107], v[188:191], v[172:175], v[104:107]
	v_mfma_f32_16x16x32_bf16 v[100:103], v[188:191], v[176:179], v[100:103]
	v_mfma_f32_16x16x32_bf16 v[96:99], v[188:191], v[180:183], v[96:99]
	v_mfma_f32_16x16x32_bf16 v[92:95], v[192:195], v[156:159], v[92:95]
	v_mfma_f32_16x16x32_bf16 v[88:91], v[192:195], v[172:175], v[88:91]
	v_mfma_f32_16x16x32_bf16 v[84:87], v[192:195], v[176:179], v[84:87]
	v_mfma_f32_16x16x32_bf16 v[80:83], v[192:195], v[180:183], v[80:83]
	v_mfma_f32_16x16x32_bf16 v[76:79], v[198:201], v[156:159], v[76:79]
	v_mfma_f32_16x16x32_bf16 v[72:75], v[198:201], v[172:175], v[72:75]
	v_mfma_f32_16x16x32_bf16 v[68:71], v[198:201], v[176:179], v[68:71]
	v_mfma_f32_16x16x32_bf16 v[64:67], v[198:201], v[180:183], v[64:67]
	s_setprio 0
	s_barrier
	ds_read_b128 v[184:187], v235 offset:4096
	ds_read_b128 v[188:191], v235 offset:5120
	ds_read_b128 v[192:195], v235 offset:6144
	ds_read_b128 v[198:201], v235 offset:7168
	s_waitcnt vmcnt(0)
	s_waitcnt lgkmcnt(0)
	s_barrier
	s_setprio 1
	v_mfma_f32_16x16x32_bf16 v[60:63], v[184:187], v[156:159], v[60:63]
	v_mfma_f32_16x16x32_bf16 v[56:59], v[184:187], v[172:175], v[56:59]
	v_mfma_f32_16x16x32_bf16 v[52:55], v[184:187], v[176:179], v[52:55]
	v_mfma_f32_16x16x32_bf16 v[48:51], v[184:187], v[180:183], v[48:51]
	v_mfma_f32_16x16x32_bf16 v[44:47], v[188:191], v[156:159], v[44:47]
	v_mfma_f32_16x16x32_bf16 v[40:43], v[188:191], v[172:175], v[40:43]
	v_mfma_f32_16x16x32_bf16 v[36:39], v[188:191], v[176:179], v[36:39]
	v_mfma_f32_16x16x32_bf16 v[32:35], v[188:191], v[180:183], v[32:35]
	v_mfma_f32_16x16x32_bf16 v[28:31], v[192:195], v[156:159], v[28:31]
	v_mfma_f32_16x16x32_bf16 v[24:27], v[192:195], v[172:175], v[24:27]
	v_mfma_f32_16x16x32_bf16 v[20:23], v[192:195], v[176:179], v[20:23]
	v_mfma_f32_16x16x32_bf16 v[16:19], v[192:195], v[180:183], v[16:19]
	v_mfma_f32_16x16x32_bf16 v[12:15], v[198:201], v[156:159], v[12:15]
	v_mfma_f32_16x16x32_bf16 v[8:11], v[198:201], v[172:175], v[8:11]
	v_mfma_f32_16x16x32_bf16 v[4:7], v[198:201], v[176:179], v[4:7]
	v_mfma_f32_16x16x32_bf16 v[0:3], v[198:201], v[180:183], v[0:3]
	s_setprio 0
	s_barrier
	v_add_u32_e32 v235, 0x18000, v168
	v_add_u32_e32 v236, 0x18000, v170
	ds_read_b128 v[184:187], v235
	ds_read_b128 v[156:159], v236 offset:16384
	ds_read_b128 v[172:175], v236 offset:17408
	ds_read_b128 v[176:179], v236 offset:18432
	ds_read_b128 v[180:183], v236 offset:19456
	ds_read_b128 v[188:191], v235 offset:1024
	ds_read_b128 v[192:195], v235 offset:2048
	ds_read_b128 v[198:201], v235 offset:3072
	s_waitcnt lgkmcnt(0)
	s_barrier
	s_setprio 1
	v_mfma_f32_16x16x32_bf16 v[124:127], v[184:187], v[156:159], v[124:127]
	v_mfma_f32_16x16x32_bf16 v[120:123], v[184:187], v[172:175], v[120:123]
	v_mfma_f32_16x16x32_bf16 v[116:119], v[184:187], v[176:179], v[116:119]
	v_mfma_f32_16x16x32_bf16 v[112:115], v[184:187], v[180:183], v[112:115]
	v_mfma_f32_16x16x32_bf16 v[108:111], v[188:191], v[156:159], v[108:111]
	v_mfma_f32_16x16x32_bf16 v[104:107], v[188:191], v[172:175], v[104:107]
	v_mfma_f32_16x16x32_bf16 v[100:103], v[188:191], v[176:179], v[100:103]
	v_mfma_f32_16x16x32_bf16 v[96:99], v[188:191], v[180:183], v[96:99]
	v_mfma_f32_16x16x32_bf16 v[92:95], v[192:195], v[156:159], v[92:95]
	v_mfma_f32_16x16x32_bf16 v[88:91], v[192:195], v[172:175], v[88:91]
	v_mfma_f32_16x16x32_bf16 v[84:87], v[192:195], v[176:179], v[84:87]
	v_mfma_f32_16x16x32_bf16 v[80:83], v[192:195], v[180:183], v[80:83]
	v_mfma_f32_16x16x32_bf16 v[76:79], v[198:201], v[156:159], v[76:79]
	v_mfma_f32_16x16x32_bf16 v[72:75], v[198:201], v[172:175], v[72:75]
	v_mfma_f32_16x16x32_bf16 v[68:71], v[198:201], v[176:179], v[68:71]
	v_mfma_f32_16x16x32_bf16 v[64:67], v[198:201], v[180:183], v[64:67]
	s_setprio 0
	s_barrier
	ds_read_b128 v[184:187], v235 offset:4096
	ds_read_b128 v[188:191], v235 offset:5120
	ds_read_b128 v[192:195], v235 offset:6144
	ds_read_b128 v[198:201], v235 offset:7168
	s_waitcnt lgkmcnt(0)
	s_barrier
	s_setprio 1
	v_mfma_f32_16x16x32_bf16 v[60:63], v[184:187], v[156:159], v[60:63]
	v_mfma_f32_16x16x32_bf16 v[56:59], v[184:187], v[172:175], v[56:59]
	v_mfma_f32_16x16x32_bf16 v[52:55], v[184:187], v[176:179], v[52:55]
	v_mfma_f32_16x16x32_bf16 v[48:51], v[184:187], v[180:183], v[48:51]
	v_mfma_f32_16x16x32_bf16 v[44:47], v[188:191], v[156:159], v[44:47]
	v_mfma_f32_16x16x32_bf16 v[40:43], v[188:191], v[172:175], v[40:43]
	v_mfma_f32_16x16x32_bf16 v[36:39], v[188:191], v[176:179], v[36:39]
	v_mfma_f32_16x16x32_bf16 v[32:35], v[188:191], v[180:183], v[32:35]
	v_mfma_f32_16x16x32_bf16 v[28:31], v[192:195], v[156:159], v[28:31]
	v_mfma_f32_16x16x32_bf16 v[24:27], v[192:195], v[172:175], v[24:27]
	v_mfma_f32_16x16x32_bf16 v[20:23], v[192:195], v[176:179], v[20:23]
	v_mfma_f32_16x16x32_bf16 v[16:19], v[192:195], v[180:183], v[16:19]
	v_mfma_f32_16x16x32_bf16 v[12:15], v[198:201], v[156:159], v[12:15]
	v_mfma_f32_16x16x32_bf16 v[8:11], v[198:201], v[172:175], v[8:11]
	v_mfma_f32_16x16x32_bf16 v[4:7], v[198:201], v[176:179], v[4:7]
	v_mfma_f32_16x16x32_bf16 v[0:3], v[198:201], v[180:183], v[0:3]
	s_setprio 0
	s_barrier
	s_cmp_ge_u32 s98, 0x2000
	s_cbranch_scc1 .Lp2a_done
	s_barrier
.Lp2a_done:
	s_nop 7

; __device__ __forceinline__ int otid() { int t = threadIdx.x; asm volatile("" : "+v"(t)); return t; }
; #define GEMM_WAITV(n) asm volatile("s_waitcnt vmcnt(" #n ")" ::: "memory")
; template <bool SWAP>
; __device__ __forceinline__ void gemm_main(f32x4 (&acc)[8][4], const TP& t, int nk, char* lds) {
;   const u16* a0 = t.a0; const u16* a1 = t.a1; const u16* b0 = t.b0; const u16* b1 = t.b1;
;   const int tid = otid(), lane = tid & 63, wave = tid >> 6;
;   const int wm = wave >> 2, wn = wave & 3, lr = lane & 15, lq = lane >> 4;
;   const int ldoff = wave * 2048 + lane * 16;
;   const int sw = (lq ^ ((0 - (lr >> 2)) & 3)) << 4;
;   const int aoff = (wm * 128 + lr) * 64 + sw, boff = T_ASTAGE + (wn * 64 + lr) * 64 + sw;
;     ...
; #pragma unroll 1
;   for (int kt = 0; kt < nk - 3; ++kt) {
;     GEMM_WAITV(8);
;     GEMM_STEP(kt, true)
; __device__ __forceinline__ void zero_acc(f32x4 (&acc)[8][4]) {
; #pragma unroll
;   for (int i = 0; i < 8; ++i)
; #pragma unroll
;     for (int j = 0; j < 4; ++j) acc[i][j] = (f32x4){0.f, 0.f, 0.f, 0.f};
.LBB0_401:
	s_and_b64 vcc, exec, s[34:35]
	s_cbranch_vccz .LBB0_417
	s_nop 2
	v_mov_b32_e32 v0, v153
	s_mov_b32 s34, 0x18000
	v_lshlrev_b32_e32 v3, 2, v0
	v_and_b32_e32 v3, 48, v3
	v_sub_u32_e32 v3, 0, v3
	v_and_b32_e32 v136, 15, v0
	v_lshlrev_b32_e32 v1, 5, v0
	v_lshlrev_b32_e32 v2, 4, v0
	v_bitop3_b32 v137, v0, 48, v3 bitop3:0x48
	v_ashrrev_i32_e32 v138, 1, v0
	v_lshlrev_b32_e32 v0, 6, v0
	v_and_b32_e32 v1, 0xfffff800, v1
	v_and_b32_e32 v2, 0x3f0, v2
	v_and_or_b32 v3, v138, s41, v136
	v_and_b32_e32 v139, 0x33c0, v0
	v_mov_b32_e32 v0, 0
	v_lshl_or_b32 v140, v3, 6, v137
	v_or_b32_e32 v141, v139, v137
	v_add3_u32 v142, 0, v1, v2
	v_mov_b32_e32 v1, v0
	v_mov_b32_e32 v2, v0
	v_mov_b32_e32 v3, v0
	v_mov_b32_e32 v4, v0
	v_mov_b32_e32 v5, v0
	v_mov_b32_e32 v6, v0
	v_mov_b32_e32 v7, v0
	v_mov_b32_e32 v8, v0
	v_mov_b32_e32 v9, v0
	v_mov_b32_e32 v10, v0
	v_mov_b32_e32 v11, v0
	v_mov_b32_e32 v12, v0
	v_mov_b32_e32 v13, v0
	v_mov_b32_e32 v14, v0
	v_mov_b32_e32 v15, v0
	v_mov_b32_e32 v16, v0
	v_mov_b32_e32 v17, v0
	v_mov_b32_e32 v18, v0
	v_mov_b32_e32 v19, v0
	v_mov_b32_e32 v20, v0
	v_mov_b32_e32 v21, v0
	v_mov_b32_e32 v22, v0
	v_mov_b32_e32 v23, v0
	v_mov_b32_e32 v24, v0
	v_mov_b32_e32 v25, v0
	v_mov_b32_e32 v26, v0
	v_mov_b32_e32 v27, v0
	v_mov_b32_e32 v28, v0
	v_mov_b32_e32 v29, v0
	v_mov_b32_e32 v30, v0
	v_mov_b32_e32 v31, v0
	v_mov_b32_e32 v32, v0
	v_mov_b32_e32 v33, v0
	v_mov_b32_e32 v34, v0
	v_mov_b32_e32 v35, v0
	v_mov_b32_e32 v36, v0
	v_mov_b32_e32 v37, v0
	v_mov_b32_e32 v38, v0
	v_mov_b32_e32 v39, v0
	v_mov_b32_e32 v40, v0
	v_mov_b32_e32 v41, v0
	v_mov_b32_e32 v42, v0
	v_mov_b32_e32 v43, v0
	v_mov_b32_e32 v44, v0
	v_mov_b32_e32 v45, v0
	v_mov_b32_e32 v46, v0
	v_mov_b32_e32 v47, v0
	v_mov_b32_e32 v48, v0
	v_mov_b32_e32 v49, v0
	v_mov_b32_e32 v50, v0
	v_mov_b32_e32 v51, v0
	v_mov_b32_e32 v52, v0
	v_mov_b32_e32 v53, v0
	v_mov_b32_e32 v54, v0
	v_mov_b32_e32 v55, v0
	v_mov_b32_e32 v56, v0
	v_mov_b32_e32 v57, v0
	v_mov_b32_e32 v58, v0
	v_mov_b32_e32 v59, v0
	v_mov_b32_e32 v60, v0
	v_mov_b32_e32 v61, v0
	v_mov_b32_e32 v62, v0
	v_mov_b32_e32 v63, v0
	v_mov_b32_e32 v64, v0
	v_mov_b32_e32 v65, v0
	v_mov_b32_e32 v66, v0
	v_mov_b32_e32 v67, v0
	v_mov_b32_e32 v68, v0
	v_mov_b32_e32 v69, v0
	v_mov_b32_e32 v70, v0
	v_mov_b32_e32 v71, v0
	v_mov_b32_e32 v72, v0
	v_mov_b32_e32 v73, v0
	v_mov_b32_e32 v74, v0
	v_mov_b32_e32 v75, v0
	v_mov_b32_e32 v76, v0
	v_mov_b32_e32 v77, v0
	v_mov_b32_e32 v78, v0
	v_mov_b32_e32 v79, v0
	v_mov_b32_e32 v80, v0
	v_mov_b32_e32 v81, v0
	v_mov_b32_e32 v82, v0
	v_mov_b32_e32 v83, v0
	v_mov_b32_e32 v84, v0
	v_mov_b32_e32 v85, v0
	v_mov_b32_e32 v86, v0
	v_mov_b32_e32 v87, v0
	v_mov_b32_e32 v88, v0
	v_mov_b32_e32 v89, v0
	v_mov_b32_e32 v90, v0
	v_mov_b32_e32 v91, v0
	v_mov_b32_e32 v92, v0
	v_mov_b32_e32 v93, v0
	v_mov_b32_e32 v94, v0
	v_mov_b32_e32 v95, v0
	v_mov_b32_e32 v96, v0
	v_mov_b32_e32 v97, v0
	v_mov_b32_e32 v98, v0
	v_mov_b32_e32 v99, v0
	v_mov_b32_e32 v100, v0
	v_mov_b32_e32 v101, v0
	v_mov_b32_e32 v102, v0
	v_mov_b32_e32 v103, v0
	v_mov_b32_e32 v104, v0
	v_mov_b32_e32 v105, v0
	v_mov_b32_e32 v106, v0
	v_mov_b32_e32 v107, v0
	v_mov_b32_e32 v108, v0
	v_mov_b32_e32 v109, v0
	v_mov_b32_e32 v110, v0
	v_mov_b32_e32 v111, v0
	v_mov_b32_e32 v112, v0
	v_mov_b32_e32 v113, v0
	v_mov_b32_e32 v114, v0
	v_mov_b32_e32 v115, v0
	v_mov_b32_e32 v116, v0
	v_mov_b32_e32 v117, v0
	v_mov_b32_e32 v118, v0
	v_mov_b32_e32 v119, v0
	v_mov_b32_e32 v120, v0
	v_mov_b32_e32 v121, v0
	v_mov_b32_e32 v122, v0
	v_mov_b32_e32 v123, v0
	v_mov_b32_e32 v124, v0
	v_mov_b32_e32 v125, v0
	v_mov_b32_e32 v126, v0
	v_mov_b32_e32 v127, v0
	v_readfirstlane_b32 s98, v142
	s_waitcnt vmcnt(8)
	s_barrier
	s_cmp_lt_u32 s98, 0x2000
	s_cbranch_scc1 .Lp2b_top
	s_barrier
.Lp2b_top:
	s_add_i32 s35, s34, 0xfffe8000
	s_and_b32 s35, s35, 0x18000
	v_add_u32_e32 v235, s35, v140
	v_add_u32_e32 v236, s35, v141
	ds_read_b128 v[178:181], v235
	ds_read_b128 v[156:159], v236 offset:16384
	ds_read_b128 v[164:167], v236 offset:17408
	ds_read_b128 v[170:173], v236 offset:18432
	ds_read_b128 v[174:177], v236 offset:19456
	ds_read_b128 v[182:185], v235 offset:1024
	ds_read_b128 v[186:189], v235 offset:2048
	ds_read_b128 v[190:193], v235 offset:3072
	s_and_b32 s99, s34, 0x18000
	s_add_i32 s99, s99, s98
	s_mov_b32 m0, s99
	s_nop 0
	global_load_lds_dwordx4 v[128:129], off
	s_add_i32 m0, s99, 0x400
	s_nop 0
	global_load_lds_dwordx4 v[130:131], off
	s_waitcnt lgkmcnt(0)
	s_barrier
	s_setprio 1
	v_mfma_f32_16x16x32_bf16 v[124:127], v[156:159], v[178:181], v[124:127]
	v_mfma_f32_16x16x32_bf16 v[120:123], v[164:167], v[178:181], v[120:123]
	v_mfma_f32_16x16x32_bf16 v[116:119], v[170:173], v[178:181], v[116:119]
	v_mfma_f32_16x16x32_bf16 v[112:115], v[174:177], v[178:181], v[112:115]
	v_mfma_f32_16x16x32_bf16 v[108:111], v[156:159], v[182:185], v[108:111]
	v_mfma_f32_16x16x32_bf16 v[104:107], v[164:167], v[182:185], v[104:107]
	v_mfma_f32_16x16x32_bf16 v[100:103], v[170:173], v[182:185], v[100:103]
	v_mfma_f32_16x16x32_bf16 v[96:99], v[174:177], v[182:185], v[96:99]
	v_mfma_f32_16x16x32_bf16 v[92:95], v[156:159], v[186:189], v[92:95]
	v_mfma_f32_16x16x32_bf16 v[88:91], v[164:167], v[186:189], v[88:91]
	v_mfma_f32_16x16x32_bf16 v[84:87], v[170:173], v[186:189], v[84:87]
	v_mfma_f32_16x16x32_bf16 v[80:83], v[174:177], v[186:189], v[80:83]
	v_mfma_f32_16x16x32_bf16 v[76:79], v[156:159], v[190:193], v[76:79]
	v_mfma_f32_16x16x32_bf16 v[72:75], v[164:167], v[190:193], v[72:75]
	v_mfma_f32_16x16x32_bf16 v[68:71], v[170:173], v[190:193], v[68:71]
	v_mfma_f32_16x16x32_bf16 v[64:67], v[174:177], v[190:193], v[64:67]
	s_setprio 0
	s_barrier
; #define GEMM_WAITV(n) asm volatile("s_waitcnt vmcnt(" #n ")" ::: "memory")
; template <bool SWAP>
; __device__ __forceinline__ void gemm_main(f32x4 (&acc)[8][4], const TP& t, int nk, char* lds) {
;     ...
; #pragma unroll 1
;   for (int kt = 0; kt < nk - 3; ++kt) {
;     GEMM_WAITV(8);
;     GEMM_STEP(kt, true)
;   }
; #pragma unroll 1
;   for (int kt = nk - 3; kt < nk; ++kt) {
;     const int rem = nk - kt;
;     if (rem == 3) GEMM_WAITV(8); else if (rem == 2) GEMM_WAITV(4); else GEMM_WAITV(0);
;     GEMM_STEP(kt, false)
;   }
	ds_read_b128 v[178:181], v235 offset:4096
	ds_read_b128 v[182:185], v235 offset:5120
	ds_read_b128 v[186:189], v235 offset:6144
	ds_read_b128 v[190:193], v235 offset:7168
	s_add_i32 m0, s99, 0x4000
	s_nop 0
	global_load_lds_dwordx4 v[132:133], off
	s_add_i32 m0, s99, 0x4400
	s_nop 0
	global_load_lds_dwordx4 v[134:135], off
	v_lshl_add_u64 v[128:129], v[128:129], 0, 64
	v_lshl_add_u64 v[130:131], v[130:131], 0, 64
	v_lshl_add_u64 v[132:133], v[132:133], 0, 64
	v_lshl_add_u64 v[134:135], v[134:135], 0, 64
	s_add_i32 s34, s34, 0x8000
	s_waitcnt vmcnt(8)
	s_waitcnt lgkmcnt(0)
	s_barrier
	s_setprio 1
	v_mfma_f32_16x16x32_bf16 v[60:63], v[156:159], v[178:181], v[60:63]
	v_mfma_f32_16x16x32_bf16 v[56:59], v[164:167], v[178:181], v[56:59]
	v_mfma_f32_16x16x32_bf16 v[52:55], v[170:173], v[178:181], v[52:55]
	v_mfma_f32_16x16x32_bf16 v[48:51], v[174:177], v[178:181], v[48:51]
	v_mfma_f32_16x16x32_bf16 v[44:47], v[156:159], v[182:185], v[44:47]
	v_mfma_f32_16x16x32_bf16 v[40:43], v[164:167], v[182:185], v[40:43]
	v_mfma_f32_16x16x32_bf16 v[36:39], v[170:173], v[182:185], v[36:39]
	v_mfma_f32_16x16x32_bf16 v[32:35], v[174:177], v[182:185], v[32:35]
	v_mfma_f32_16x16x32_bf16 v[28:31], v[156:159], v[186:189], v[28:31]
	v_mfma_f32_16x16x32_bf16 v[24:27], v[164:167], v[186:189], v[24:27]
	v_mfma_f32_16x16x32_bf16 v[20:23], v[170:173], v[186:189], v[20:23]
	v_mfma_f32_16x16x32_bf16 v[16:19], v[174:177], v[186:189], v[16:19]
	v_mfma_f32_16x16x32_bf16 v[12:15], v[156:159], v[190:193], v[12:15]
	v_mfma_f32_16x16x32_bf16 v[8:11], v[164:167], v[190:193], v[8:11]
	v_mfma_f32_16x16x32_bf16 v[4:7], v[170:173], v[190:193], v[4:7]
	v_mfma_f32_16x16x32_bf16 v[0:3], v[174:177], v[190:193], v[0:3]
	s_setprio 0
	s_barrier
	s_cmp_lg_u32 s34, 0x100000
	s_cbranch_scc1 .Lp2b_top
	v_add_u32_e32 v235, 0x8000, v140
	v_add_u32_e32 v236, 0x8000, v141
	ds_read_b128 v[178:181], v235
	ds_read_b128 v[156:159], v236 offset:16384
	ds_read_b128 v[164:167], v236 offset:17408
	ds_read_b128 v[170:173], v236 offset:18432
	ds_read_b128 v[174:177], v236 offset:19456
	ds_read_b128 v[182:185], v235 offset:1024
	ds_read_b128 v[186:189], v235 offset:2048
	ds_read_b128 v[190:193], v235 offset:3072
	s_waitcnt lgkmcnt(0)
	s_barrier
	s_setprio 1
	v_mfma_f32_16x16x32_bf16 v[124:127], v[156:159], v[178:181], v[124:127]
	v_mfma_f32_16x16x32_bf16 v[120:123], v[164:167], v[178:181], v[120:123]
	v_mfma_f32_16x16x32_bf16 v[116:119], v[170:173], v[178:181], v[116:119]
	v_mfma_f32_16x16x32_bf16 v[112:115], v[174:177], v[178:181], v[112:115]
	v_mfma_f32_16x16x32_bf16 v[108:111], v[156:159], v[182:185], v[108:111]
	v_mfma_f32_16x16x32_bf16 v[104:107], v[164:167], v[182:185], v[104:107]
	v_mfma_f32_16x16x32_bf16 v[100:103], v[170:173], v[182:185], v[100:103]
	v_mfma_f32_16x16x32_bf16 v[96:99], v[174:177], v[182:185], v[96:99]
	v_mfma_f32_16x16x32_bf16 v[92:95], v[156:159], v[186:189], v[92:95]
	v_mfma_f32_16x16x32_bf16 v[88:91], v[164:167], v[186:189], v[88:91]
	v_mfma_f32_16x16x32_bf16 v[84:87], v[170:173], v[186:189], v[84:87]
	v_mfma_f32_16x16x32_bf16 v[80:83], v[174:177], v[186:189], v[80:83]
	v_mfma_f32_16x16x32_bf16 v[76:79], v[156:159], v[190:193], v[76:79]
	v_mfma_f32_16x16x32_bf16 v[72:75], v[164:167], v[190:193], v[72:75]
	v_mfma_f32_16x16x32_bf16 v[68:71], v[170:173], v[190:193], v[68:71]
	v_mfma_f32_16x16x32_bf16 v[64:67], v[174:177], v[190:193], v[64:67]
	s_setprio 0
	s_barrier
	ds_read_b128 v[178:181], v235 offset:4096
	ds_read_b128 v[182:185], v235 offset:5120
	ds_read_b128 v[186:189], v235 offset:6144
	ds_read_b128 v[190:193], v235 offset:7168
	s_waitcnt vmcnt(4)
	s_waitcnt lgkmcnt(0)
	s_barrier
	s_setprio 1
	v_mfma_f32_16x16x32_bf16 v[60:63], v[156:159], v[178:181], v[60:63]
	v_mfma_f32_16x16x32_bf16 v[56:59], v[164:167], v[178:181], v[56:59]
	v_mfma_f32_16x16x32_bf16 v[52:55], v[170:173], v[178:181], v[52:55]
	v_mfma_f32_16x16x32_bf16 v[48:51], v[174:177], v[178:181], v[48:51]
	v_mfma_f32_16x16x32_bf16 v[44:47], v[156:159], v[182:185], v[44:47]
	v_mfma_f32_16x16x32_bf16 v[40:43], v[164:167], v[182:185], v[40:43]
	v_mfma_f32_16x16x32_bf16 v[36:39], v[170:173], v[182:185], v[36:39]
	v_mfma_f32_16x16x32_bf16 v[32:35], v[174:177], v[182:185], v[32:35]
	v_mfma_f32_16x16x32_bf16 v[28:31], v[156:159], v[186:189], v[28:31]
	v_mfma_f32_16x16x32_bf16 v[24:27], v[164:167], v[186:189], v[24:27]
	v_mfma_f32_16x16x32_bf16 v[20:23], v[170:173], v[186:189], v[20:23]
	v_mfma_f32_16x16x32_bf16 v[16:19], v[174:177], v[186:189], v[16:19]
	v_mfma_f32_16x16x32_bf16 v[12:15], v[156:159], v[190:193], v[12:15]
	v_mfma_f32_16x16x32_bf16 v[8:11], v[164:167], v[190:193], v[8:11]
	v_mfma_f32_16x16x32_bf16 v[4:7], v[170:173], v[190:193], v[4:7]
	v_mfma_f32_16x16x32_bf16 v[0:3], v[174:177], v[190:193], v[0:3]
	s_setprio 0
	s_barrier
	v_add_u32_e32 v235, 0x10000, v140
	v_add_u32_e32 v236, 0x10000, v141
	ds_read_b128 v[178:181], v235
	ds_read_b128 v[156:159], v236 offset:16384
	ds_read_b128 v[164:167], v236 offset:17408
	ds_read_b128 v[170:173], v236 offset:18432
	ds_read_b128 v[174:177], v236 offset:19456
	ds_read_b128 v[182:185], v235 offset:1024
	ds_read_b128 v[186:189], v235 offset:2048
	ds_read_b128 v[190:193], v235 offset:3072
	s_waitcnt lgkmcnt(0)
	s_barrier
; #define GEMM_WAITV(n) asm volatile("s_waitcnt vmcnt(" #n ")" ::: "memory")
; template <bool SWAP>
; __device__ __forceinline__ void gemm_main(f32x4 (&acc)[8][4], const TP& t, int nk, char* lds) {
;     ...
; #pragma unroll 1
;   for (int kt = nk - 3; kt < nk; ++kt) {
;     const int rem = nk - kt;
;     if (rem == 3) GEMM_WAITV(8); else if (rem == 2) GEMM_WAITV(4); else GEMM_WAITV(0);
;     GEMM_STEP(kt, false)
;   }
;   __builtin_amdgcn_s_barrier();
	s_setprio 1
	v_mfma_f32_16x16x32_bf16 v[124:127], v[156:159], v[178:181], v[124:127]
	v_mfma_f32_16x16x32_bf16 v[120:123], v[164:167], v[178:181], v[120:123]
	v_mfma_f32_16x16x32_bf16 v[116:119], v[170:173], v[178:181], v[116:119]
	v_mfma_f32_16x16x32_bf16 v[112:115], v[174:177], v[178:181], v[112:115]
	v_mfma_f32_16x16x32_bf16 v[108:111], v[156:159], v[182:185], v[108:111]
	v_mfma_f32_16x16x32_bf16 v[104:107], v[164:167], v[182:185], v[104:107]
	v_mfma_f32_16x16x32_bf16 v[100:103], v[170:173], v[182:185], v[100:103]
	v_mfma_f32_16x16x32_bf16 v[96:99], v[174:177], v[182:185], v[96:99]
	v_mfma_f32_16x16x32_bf16 v[92:95], v[156:159], v[186:189], v[92:95]
	v_mfma_f32_16x16x32_bf16 v[88:91], v[164:167], v[186:189], v[88:91]
	v_mfma_f32_16x16x32_bf16 v[84:87], v[170:173], v[186:189], v[84:87]
	v_mfma_f32_16x16x32_bf16 v[80:83], v[174:177], v[186:189], v[80:83]
	v_mfma_f32_16x16x32_bf16 v[76:79], v[156:159], v[190:193], v[76:79]
	v_mfma_f32_16x16x32_bf16 v[72:75], v[164:167], v[190:193], v[72:75]
	v_mfma_f32_16x16x32_bf16 v[68:71], v[170:173], v[190:193], v[68:71]
	v_mfma_f32_16x16x32_bf16 v[64:67], v[174:177], v[190:193], v[64:67]
	s_setprio 0
	s_barrier
	ds_read_b128 v[178:181], v235 offset:4096
	ds_read_b128 v[182:185], v235 offset:5120
	ds_read_b128 v[186:189], v235 offset:6144
	ds_read_b128 v[190:193], v235 offset:7168
	s_waitcnt vmcnt(0)
	s_waitcnt lgkmcnt(0)
	s_barrier
	s_setprio 1
	v_mfma_f32_16x16x32_bf16 v[60:63], v[156:159], v[178:181], v[60:63]
	v_mfma_f32_16x16x32_bf16 v[56:59], v[164:167], v[178:181], v[56:59]
	v_mfma_f32_16x16x32_bf16 v[52:55], v[170:173], v[178:181], v[52:55]
	v_mfma_f32_16x16x32_bf16 v[48:51], v[174:177], v[178:181], v[48:51]
	v_mfma_f32_16x16x32_bf16 v[44:47], v[156:159], v[182:185], v[44:47]
	v_mfma_f32_16x16x32_bf16 v[40:43], v[164:167], v[182:185], v[40:43]
	v_mfma_f32_16x16x32_bf16 v[36:39], v[170:173], v[182:185], v[36:39]
	v_mfma_f32_16x16x32_bf16 v[32:35], v[174:177], v[182:185], v[32:35]
	v_mfma_f32_16x16x32_bf16 v[28:31], v[156:159], v[186:189], v[28:31]
	v_mfma_f32_16x16x32_bf16 v[24:27], v[164:167], v[186:189], v[24:27]
	v_mfma_f32_16x16x32_bf16 v[20:23], v[170:173], v[186:189], v[20:23]
	v_mfma_f32_16x16x32_bf16 v[16:19], v[174:177], v[186:189], v[16:19]
	v_mfma_f32_16x16x32_bf16 v[12:15], v[156:159], v[190:193], v[12:15]
	v_mfma_f32_16x16x32_bf16 v[8:11], v[164:167], v[190:193], v[8:11]
	v_mfma_f32_16x16x32_bf16 v[4:7], v[170:173], v[190:193], v[4:7]
	v_mfma_f32_16x16x32_bf16 v[0:3], v[174:177], v[190:193], v[0:3]
	s_setprio 0
	s_barrier
	v_add_u32_e32 v235, 0x18000, v140
	v_add_u32_e32 v236, 0x18000, v141
	ds_read_b128 v[178:181], v235
	ds_read_b128 v[156:159], v236 offset:16384
	ds_read_b128 v[164:167], v236 offset:17408
	ds_read_b128 v[170:173], v236 offset:18432
	ds_read_b128 v[174:177], v236 offset:19456
	ds_read_b128 v[182:185], v235 offset:1024
	ds_read_b128 v[186:189], v235 offset:2048
	ds_read_b128 v[190:193], v235 offset:3072
	s_waitcnt lgkmcnt(0)
	s_barrier
	s_setprio 1
	v_mfma_f32_16x16x32_bf16 v[124:127], v[156:159], v[178:181], v[124:127]
	v_mfma_f32_16x16x32_bf16 v[120:123], v[164:167], v[178:181], v[120:123]
	v_mfma_f32_16x16x32_bf16 v[116:119], v[170:173], v[178:181], v[116:119]
	v_mfma_f32_16x16x32_bf16 v[112:115], v[174:177], v[178:181], v[112:115]
	v_mfma_f32_16x16x32_bf16 v[108:111], v[156:159], v[182:185], v[108:111]
	v_mfma_f32_16x16x32_bf16 v[104:107], v[164:167], v[182:185], v[104:107]
	v_mfma_f32_16x16x32_bf16 v[100:103], v[170:173], v[182:185], v[100:103]
	v_mfma_f32_16x16x32_bf16 v[96:99], v[174:177], v[182:185], v[96:99]
	v_mfma_f32_16x16x32_bf16 v[92:95], v[156:159], v[186:189], v[92:95]
	v_mfma_f32_16x16x32_bf16 v[88:91], v[164:167], v[186:189], v[88:91]
	v_mfma_f32_16x16x32_bf16 v[84:87], v[170:173], v[186:189], v[84:87]
	v_mfma_f32_16x16x32_bf16 v[80:83], v[174:177], v[186:189], v[80:83]
	v_mfma_f32_16x16x32_bf16 v[76:79], v[156:159], v[190:193], v[76:79]
	v_mfma_f32_16x16x32_bf16 v[72:75], v[164:167], v[190:193], v[72:75]
	v_mfma_f32_16x16x32_bf16 v[68:71], v[170:173], v[190:193], v[68:71]
	v_mfma_f32_16x16x32_bf16 v[64:67], v[174:177], v[190:193], v[64:67]
	s_setprio 0
	s_barrier
	ds_read_b128 v[178:181], v235 offset:4096
	ds_read_b128 v[182:185], v235 offset:5120
	ds_read_b128 v[186:189], v235 offset:6144
	ds_read_b128 v[190:193], v235 offset:7168
	s_waitcnt lgkmcnt(0)
	s_barrier
	s_setprio 1
	v_mfma_f32_16x16x32_bf16 v[60:63], v[156:159], v[178:181], v[60:63]
	v_mfma_f32_16x16x32_bf16 v[56:59], v[164:167], v[178:181], v[56:59]
	v_mfma_f32_16x16x32_bf16 v[52:55], v[170:173], v[178:181], v[52:55]
	v_mfma_f32_16x16x32_bf16 v[48:51], v[174:177], v[178:181], v[48:51]
	v_mfma_f32_16x16x32_bf16 v[44:47], v[156:159], v[182:185], v[44:47]
	v_mfma_f32_16x16x32_bf16 v[40:43], v[164:167], v[182:185], v[40:43]
	v_mfma_f32_16x16x32_bf16 v[36:39], v[170:173], v[182:185], v[36:39]
	v_mfma_f32_16x16x32_bf16 v[32:35], v[174:177], v[182:185], v[32:35]
	v_mfma_f32_16x16x32_bf16 v[28:31], v[156:159], v[186:189], v[28:31]
	v_mfma_f32_16x16x32_bf16 v[24:27], v[164:167], v[186:189], v[24:27]
	v_mfma_f32_16x16x32_bf16 v[20:23], v[170:173], v[186:189], v[20:23]
	v_mfma_f32_16x16x32_bf16 v[16:19], v[174:177], v[186:189], v[16:19]
	v_mfma_f32_16x16x32_bf16 v[12:15], v[156:159], v[190:193], v[12:15]
	v_mfma_f32_16x16x32_bf16 v[8:11], v[164:167], v[190:193], v[8:11]
	v_mfma_f32_16x16x32_bf16 v[4:7], v[170:173], v[190:193], v[4:7]
	v_mfma_f32_16x16x32_bf16 v[0:3], v[174:177], v[190:193], v[0:3]
	s_setprio 0
	s_barrier
	s_cmp_ge_u32 s98, 0x2000
	s_cbranch_scc1 .Lp2b_done
	s_barrier

; __device__ __forceinline__ int otid() { int t = threadIdx.x; asm volatile("" : "+v"(t)); return t; }
; #define GEMM_WAITV(n) asm volatile("s_waitcnt vmcnt(" #n ")" ::: "memory")
; template <bool SWAP>
; __device__ __forceinline__ void gemm_main(f32x4 (&acc)[8][4], const TP& t, int nk, char* lds) {
;   const u16* a0 = t.a0; const u16* a1 = t.a1; const u16* b0 = t.b0; const u16* b1 = t.b1;
;   const int tid = otid(), lane = tid & 63, wave = tid >> 6;
;   const int wm = wave >> 2, wn = wave & 3, lr = lane & 15, lq = lane >> 4;
;   const int ldoff = wave * 2048 + lane * 16;
;   const int sw = (lq ^ ((0 - (lr >> 2)) & 3)) << 4;
;   const int aoff = (wm * 128 + lr) * 64 + sw, boff = T_ASTAGE + (wn * 64 + lr) * 64 + sw;
;     ...
; #pragma unroll 1
;   for (int kt = 0; kt < nk - 3; ++kt) {
;     GEMM_WAITV(8);
;     GEMM_STEP(kt, true)
; __device__ __forceinline__ void merge_phase(const Params& p, int first, int step, int n, char* lds) {
;     ...
;     f32x4 acc[8][4];
;     zero_acc(acc);
;     gemm_main<true>(acc, cur, 16, lds);
.LBB0_845:
	v_mov_b32_e32 v0, v153
	v_mov_b32_e32 v8, 0
	v_lshlrev_b32_e32 v3, 2, v0
	v_and_b32_e32 v3, 48, v3
	v_sub_u32_e32 v3, 0, v3
	v_and_b32_e32 v136, 15, v0
	v_lshlrev_b32_e32 v1, 5, v0
	v_lshlrev_b32_e32 v2, 4, v0
	v_bitop3_b32 v137, v0, 48, v3 bitop3:0x48
	v_ashrrev_i32_e32 v138, 1, v0
	v_lshlrev_b32_e32 v0, 6, v0
	v_and_b32_e32 v1, 0xfffff800, v1
	v_and_b32_e32 v2, 0x3f0, v2
	v_and_or_b32 v3, v138, s68, v136
	v_and_b32_e32 v139, 0x33c0, v0
	v_lshl_or_b32 v140, v3, 6, v137
	v_or_b32_e32 v141, v139, v137
	v_add3_u32 v142, 0, v1, v2
	v_lshl_add_u64 v[128:129], v[158:159], 0, s[40:41]
	v_lshl_add_u64 v[130:131], v[162:163], 0, s[40:41]
	v_lshl_add_u64 v[132:133], v[160:161], 0, s[40:41]
	v_lshl_add_u64 v[134:135], v[164:165], 0, s[40:41]
	s_mov_b32 s46, 0x18000
	v_mov_b32_e32 v9, v8
	v_mov_b32_e32 v10, v8
	v_mov_b32_e32 v11, v8
	v_mov_b32_e32 v24, v8
	v_mov_b32_e32 v25, v8
	v_mov_b32_e32 v26, v8
	v_mov_b32_e32 v27, v8
	v_mov_b32_e32 v32, v8
	v_mov_b32_e32 v33, v8
	v_mov_b32_e32 v34, v8
	v_mov_b32_e32 v35, v8
	v_mov_b32_e32 v36, v8
	v_mov_b32_e32 v37, v8
	v_mov_b32_e32 v38, v8
	v_mov_b32_e32 v39, v8
	v_mov_b32_e32 v44, v8
	v_mov_b32_e32 v45, v8
	v_mov_b32_e32 v46, v8
	v_mov_b32_e32 v47, v8
	v_mov_b32_e32 v60, v8
	v_mov_b32_e32 v61, v8
	v_mov_b32_e32 v62, v8
	v_mov_b32_e32 v63, v8
	v_mov_b32_e32 v64, v8
	v_mov_b32_e32 v65, v8
	v_mov_b32_e32 v66, v8
	v_mov_b32_e32 v67, v8
	v_mov_b32_e32 v84, v8
	v_mov_b32_e32 v85, v8
	v_mov_b32_e32 v86, v8
	v_mov_b32_e32 v87, v8
	v_mov_b32_e32 v88, v8
	v_mov_b32_e32 v89, v8
	v_mov_b32_e32 v90, v8
	v_mov_b32_e32 v91, v8
	v_mov_b32_e32 v92, v8
	v_mov_b32_e32 v93, v8
	v_mov_b32_e32 v94, v8
	v_mov_b32_e32 v95, v8
	v_mov_b32_e32 v112, v8
	v_mov_b32_e32 v113, v8
	v_mov_b32_e32 v114, v8
	v_mov_b32_e32 v115, v8
	v_mov_b32_e32 v124, v8
	v_mov_b32_e32 v125, v8
	v_mov_b32_e32 v126, v8
	v_mov_b32_e32 v127, v8
	v_mov_b32_e32 v116, v8
	v_mov_b32_e32 v117, v8
	v_mov_b32_e32 v118, v8
	v_mov_b32_e32 v119, v8
	v_mov_b32_e32 v120, v8
	v_mov_b32_e32 v121, v8
	v_mov_b32_e32 v122, v8
	v_mov_b32_e32 v123, v8
	v_mov_b32_e32 v108, v8
	v_mov_b32_e32 v109, v8
	v_mov_b32_e32 v110, v8
	v_mov_b32_e32 v111, v8
	v_mov_b32_e32 v104, v8
	v_mov_b32_e32 v105, v8
	v_mov_b32_e32 v106, v8
	v_mov_b32_e32 v107, v8
	v_mov_b32_e32 v96, v8
	v_mov_b32_e32 v97, v8
	v_mov_b32_e32 v98, v8
	v_mov_b32_e32 v99, v8
	v_mov_b32_e32 v100, v8
	v_mov_b32_e32 v101, v8
	v_mov_b32_e32 v102, v8
	v_mov_b32_e32 v103, v8
	v_mov_b32_e32 v80, v8
	v_mov_b32_e32 v81, v8
	v_mov_b32_e32 v82, v8
	v_mov_b32_e32 v83, v8
	v_mov_b32_e32 v76, v8
	v_mov_b32_e32 v77, v8
	v_mov_b32_e32 v78, v8
	v_mov_b32_e32 v79, v8
	v_mov_b32_e32 v68, v8
	v_mov_b32_e32 v69, v8
	v_mov_b32_e32 v70, v8
	v_mov_b32_e32 v71, v8
	v_mov_b32_e32 v72, v8
	v_mov_b32_e32 v73, v8
	v_mov_b32_e32 v74, v8
	v_mov_b32_e32 v75, v8
	v_mov_b32_e32 v56, v8
	v_mov_b32_e32 v57, v8
	v_mov_b32_e32 v58, v8
	v_mov_b32_e32 v59, v8
	v_mov_b32_e32 v52, v8
	v_mov_b32_e32 v53, v8
	v_mov_b32_e32 v54, v8
	v_mov_b32_e32 v55, v8
	v_mov_b32_e32 v40, v8
	v_mov_b32_e32 v41, v8
	v_mov_b32_e32 v42, v8
	v_mov_b32_e32 v43, v8
	v_mov_b32_e32 v48, v8
	v_mov_b32_e32 v49, v8
	v_mov_b32_e32 v50, v8
	v_mov_b32_e32 v51, v8
	v_mov_b32_e32 v28, v8
	v_mov_b32_e32 v29, v8
	v_mov_b32_e32 v30, v8
	v_mov_b32_e32 v31, v8
	v_mov_b32_e32 v20, v8
	v_mov_b32_e32 v21, v8
	v_mov_b32_e32 v22, v8
	v_mov_b32_e32 v23, v8
	v_mov_b32_e32 v12, v8
	v_mov_b32_e32 v13, v8
	v_mov_b32_e32 v14, v8
	v_mov_b32_e32 v15, v8
	v_mov_b32_e32 v16, v8
	v_mov_b32_e32 v17, v8
	v_mov_b32_e32 v18, v8
	v_mov_b32_e32 v19, v8
	v_mov_b32_e32 v4, v8
	v_mov_b32_e32 v5, v8
	v_mov_b32_e32 v6, v8
	v_mov_b32_e32 v7, v8
	v_mov_b32_e32 v0, v8
	v_mov_b32_e32 v1, v8
	v_mov_b32_e32 v2, v8
	v_mov_b32_e32 v3, v8
	v_readfirstlane_b32 s98, v142
	s_waitcnt vmcnt(8)
	s_barrier
	s_cmp_lt_u32 s98, 0x2000
	s_cbranch_scc1 .Lmg1_top
	s_barrier
.Lmg1_top:
	s_add_i32 s47, s46, 0xfffe8000
	s_and_b32 s47, s47, 0x18000
	v_add_u32_e32 v235, s47, v140
	v_add_u32_e32 v236, s47, v141
	ds_read_b128 v[174:177], v235
	ds_read_b128 v[144:147], v236 offset:16384
	ds_read_b128 v[158:161], v236 offset:17408
	ds_read_b128 v[162:165], v236 offset:18432
	ds_read_b128 v[170:173], v236 offset:19456
	ds_read_b128 v[178:181], v235 offset:1024
	ds_read_b128 v[182:185], v235 offset:2048
	ds_read_b128 v[186:189], v235 offset:3072
	s_and_b32 s99, s46, 0x18000
	s_add_i32 s99, s99, s98
	s_mov_b32 m0, s99
	s_nop 0
	global_load_lds_dwordx4 v[128:129], off
	s_add_i32 m0, s99, 0x400
	s_nop 0
	global_load_lds_dwordx4 v[130:131], off
	s_waitcnt lgkmcnt(0)
	s_barrier
	s_setprio 1
	v_mfma_f32_16x16x32_bf16 v[0:3], v[144:147], v[174:177], v[0:3]
	v_mfma_f32_16x16x32_bf16 v[4:7], v[158:161], v[174:177], v[4:7]
	v_mfma_f32_16x16x32_bf16 v[16:19], v[162:165], v[174:177], v[16:19]
	v_mfma_f32_16x16x32_bf16 v[12:15], v[170:173], v[174:177], v[12:15]
	v_mfma_f32_16x16x32_bf16 v[20:23], v[144:147], v[178:181], v[20:23]
	v_mfma_f32_16x16x32_bf16 v[28:31], v[158:161], v[178:181], v[28:31]
	v_mfma_f32_16x16x32_bf16 v[48:51], v[162:165], v[178:181], v[48:51]
	v_mfma_f32_16x16x32_bf16 v[40:43], v[170:173], v[178:181], v[40:43]
	v_mfma_f32_16x16x32_bf16 v[52:55], v[144:147], v[182:185], v[52:55]
	v_mfma_f32_16x16x32_bf16 v[56:59], v[158:161], v[182:185], v[56:59]
	v_mfma_f32_16x16x32_bf16 v[72:75], v[162:165], v[182:185], v[72:75]
	v_mfma_f32_16x16x32_bf16 v[68:71], v[170:173], v[182:185], v[68:71]
	v_mfma_f32_16x16x32_bf16 v[76:79], v[144:147], v[186:189], v[76:79]
	v_mfma_f32_16x16x32_bf16 v[80:83], v[158:161], v[186:189], v[80:83]
	v_mfma_f32_16x16x32_bf16 v[100:103], v[162:165], v[186:189], v[100:103]
	v_mfma_f32_16x16x32_bf16 v[96:99], v[170:173], v[186:189], v[96:99]
	s_setprio 0
	s_barrier
; #define GEMM_WAITV(n) asm volatile("s_waitcnt vmcnt(" #n ")" ::: "memory")
; template <bool SWAP>
; __device__ __forceinline__ void gemm_main(f32x4 (&acc)[8][4], const TP& t, int nk, char* lds) {
;     ...
; #pragma unroll 1
;   for (int kt = 0; kt < nk - 3; ++kt) {
;     GEMM_WAITV(8);
;     GEMM_STEP(kt, true)
;   }
	ds_read_b128 v[174:177], v235 offset:4096
	ds_read_b128 v[178:181], v235 offset:5120
	ds_read_b128 v[182:185], v235 offset:6144
	ds_read_b128 v[186:189], v235 offset:7168
	s_add_i32 m0, s99, 0x4000
	s_nop 0
	global_load_lds_dwordx4 v[132:133], off
	s_add_i32 m0, s99, 0x4400
	s_nop 0
	global_load_lds_dwordx4 v[134:135], off
	v_lshl_add_u64 v[128:129], v[128:129], 0, 64
	v_lshl_add_u64 v[130:131], v[130:131], 0, 64
	v_lshl_add_u64 v[132:133], v[132:133], 0, 64
	v_lshl_add_u64 v[134:135], v[134:135], 0, 64
	s_add_i32 s46, s46, 0x8000
	s_waitcnt vmcnt(8)
	s_waitcnt lgkmcnt(0)
	s_barrier
	s_setprio 1
	v_mfma_f32_16x16x32_bf16 v[104:107], v[144:147], v[174:177], v[104:107]
	v_mfma_f32_16x16x32_bf16 v[108:111], v[158:161], v[174:177], v[108:111]
	v_mfma_f32_16x16x32_bf16 v[120:123], v[162:165], v[174:177], v[120:123]
	v_mfma_f32_16x16x32_bf16 v[116:119], v[170:173], v[174:177], v[116:119]
	v_mfma_f32_16x16x32_bf16 v[124:127], v[144:147], v[178:181], v[124:127]
	v_mfma_f32_16x16x32_bf16 v[112:115], v[158:161], v[178:181], v[112:115]
	v_mfma_f32_16x16x32_bf16 v[92:95], v[162:165], v[178:181], v[92:95]
	v_mfma_f32_16x16x32_bf16 v[88:91], v[170:173], v[178:181], v[88:91]
	v_mfma_f32_16x16x32_bf16 v[84:87], v[144:147], v[182:185], v[84:87]
	v_mfma_f32_16x16x32_bf16 v[64:67], v[158:161], v[182:185], v[64:67]
	v_mfma_f32_16x16x32_bf16 v[60:63], v[162:165], v[182:185], v[60:63]
	v_mfma_f32_16x16x32_bf16 v[44:47], v[170:173], v[182:185], v[44:47]
	v_mfma_f32_16x16x32_bf16 v[36:39], v[144:147], v[186:189], v[36:39]
	v_mfma_f32_16x16x32_bf16 v[32:35], v[158:161], v[186:189], v[32:35]
	v_mfma_f32_16x16x32_bf16 v[24:27], v[162:165], v[186:189], v[24:27]
	v_mfma_f32_16x16x32_bf16 v[8:11], v[170:173], v[186:189], v[8:11]
	s_setprio 0
	s_barrier
	s_cmp_lg_u32 s46, 0x80000
	s_cbranch_scc1 .Lmg1_top
	v_add_u32_e32 v235, 0x8000, v140
	v_add_u32_e32 v236, 0x8000, v141
	ds_read_b128 v[174:177], v235
	ds_read_b128 v[144:147], v236 offset:16384
	ds_read_b128 v[158:161], v236 offset:17408
	ds_read_b128 v[162:165], v236 offset:18432
	ds_read_b128 v[170:173], v236 offset:19456
	ds_read_b128 v[178:181], v235 offset:1024
	ds_read_b128 v[182:185], v235 offset:2048
	ds_read_b128 v[186:189], v235 offset:3072
	s_waitcnt lgkmcnt(0)
	s_barrier
	s_setprio 1
	v_mfma_f32_16x16x32_bf16 v[0:3], v[144:147], v[174:177], v[0:3]
	v_mfma_f32_16x16x32_bf16 v[4:7], v[158:161], v[174:177], v[4:7]
	v_mfma_f32_16x16x32_bf16 v[16:19], v[162:165], v[174:177], v[16:19]
	v_mfma_f32_16x16x32_bf16 v[12:15], v[170:173], v[174:177], v[12:15]
	v_mfma_f32_16x16x32_bf16 v[20:23], v[144:147], v[178:181], v[20:23]
	v_mfma_f32_16x16x32_bf16 v[28:31], v[158:161], v[178:181], v[28:31]
	v_mfma_f32_16x16x32_bf16 v[48:51], v[162:165], v[178:181], v[48:51]
	v_mfma_f32_16x16x32_bf16 v[40:43], v[170:173], v[178:181], v[40:43]
	v_mfma_f32_16x16x32_bf16 v[52:55], v[144:147], v[182:185], v[52:55]
	v_mfma_f32_16x16x32_bf16 v[56:59], v[158:161], v[182:185], v[56:59]
	v_mfma_f32_16x16x32_bf16 v[72:75], v[162:165], v[182:185], v[72:75]
	v_mfma_f32_16x16x32_bf16 v[68:71], v[170:173], v[182:185], v[68:71]
	v_mfma_f32_16x16x32_bf16 v[76:79], v[144:147], v[186:189], v[76:79]
	v_mfma_f32_16x16x32_bf16 v[80:83], v[158:161], v[186:189], v[80:83]
	v_mfma_f32_16x16x32_bf16 v[100:103], v[162:165], v[186:189], v[100:103]
	v_mfma_f32_16x16x32_bf16 v[96:99], v[170:173], v[186:189], v[96:99]
	s_setprio 0
	s_barrier
	ds_read_b128 v[174:177], v235 offset:4096
	ds_read_b128 v[178:181], v235 offset:5120
	ds_read_b128 v[182:185], v235 offset:6144
	ds_read_b128 v[186:189], v235 offset:7168
	s_waitcnt vmcnt(4)
	s_waitcnt lgkmcnt(0)
	s_barrier
	s_setprio 1
	v_mfma_f32_16x16x32_bf16 v[104:107], v[144:147], v[174:177], v[104:107]
	v_mfma_f32_16x16x32_bf16 v[108:111], v[158:161], v[174:177], v[108:111]
	v_mfma_f32_16x16x32_bf16 v[120:123], v[162:165], v[174:177], v[120:123]
	v_mfma_f32_16x16x32_bf16 v[116:119], v[170:173], v[174:177], v[116:119]
	v_mfma_f32_16x16x32_bf16 v[124:127], v[144:147], v[178:181], v[124:127]
	v_mfma_f32_16x16x32_bf16 v[112:115], v[158:161], v[178:181], v[112:115]
	v_mfma_f32_16x16x32_bf16 v[92:95], v[162:165], v[178:181], v[92:95]
	v_mfma_f32_16x16x32_bf16 v[88:91], v[170:173], v[178:181], v[88:91]
	v_mfma_f32_16x16x32_bf16 v[84:87], v[144:147], v[182:185], v[84:87]
	v_mfma_f32_16x16x32_bf16 v[64:67], v[158:161], v[182:185], v[64:67]
	v_mfma_f32_16x16x32_bf16 v[60:63], v[162:165], v[182:185], v[60:63]
	v_mfma_f32_16x16x32_bf16 v[44:47], v[170:173], v[182:185], v[44:47]
	v_mfma_f32_16x16x32_bf16 v[36:39], v[144:147], v[186:189], v[36:39]
	v_mfma_f32_16x16x32_bf16 v[32:35], v[158:161], v[186:189], v[32:35]
	v_mfma_f32_16x16x32_bf16 v[24:27], v[162:165], v[186:189], v[24:27]
	v_mfma_f32_16x16x32_bf16 v[8:11], v[170:173], v[186:189], v[8:11]
	s_setprio 0
	s_barrier
	v_add_u32_e32 v235, 0x10000, v140
	v_add_u32_e32 v236, 0x10000, v141
	ds_read_b128 v[174:177], v235
	ds_read_b128 v[144:147], v236 offset:16384
	ds_read_b128 v[158:161], v236 offset:17408
	ds_read_b128 v[162:165], v236 offset:18432
	ds_read_b128 v[170:173], v236 offset:19456
	ds_read_b128 v[178:181], v235 offset:1024
	ds_read_b128 v[182:185], v235 offset:2048
	ds_read_b128 v[186:189], v235 offset:3072
	s_waitcnt lgkmcnt(0)
	s_barrier
; #define GEMM_WAITV(n) asm volatile("s_waitcnt vmcnt(" #n ")" ::: "memory")
; template <bool SWAP>
; __device__ __forceinline__ void gemm_main(f32x4 (&acc)[8][4], const TP& t, int nk, char* lds) {
;     ...
; #pragma unroll 1
;   for (int kt = nk - 3; kt < nk; ++kt) {
;     const int rem = nk - kt;
;     if (rem == 3) GEMM_WAITV(8); else if (rem == 2) GEMM_WAITV(4); else GEMM_WAITV(0);
;     GEMM_STEP(kt, false)
;   }
;   __builtin_amdgcn_s_barrier();
	s_setprio 1
	v_mfma_f32_16x16x32_bf16 v[0:3], v[144:147], v[174:177], v[0:3]
	v_mfma_f32_16x16x32_bf16 v[4:7], v[158:161], v[174:177], v[4:7]
	v_mfma_f32_16x16x32_bf16 v[16:19], v[162:165], v[174:177], v[16:19]
	v_mfma_f32_16x16x32_bf16 v[12:15], v[170:173], v[174:177], v[12:15]
	v_mfma_f32_16x16x32_bf16 v[20:23], v[144:147], v[178:181], v[20:23]
	v_mfma_f32_16x16x32_bf16 v[28:31], v[158:161], v[178:181], v[28:31]
	v_mfma_f32_16x16x32_bf16 v[48:51], v[162:165], v[178:181], v[48:51]
	v_mfma_f32_16x16x32_bf16 v[40:43], v[170:173], v[178:181], v[40:43]
	v_mfma_f32_16x16x32_bf16 v[52:55], v[144:147], v[182:185], v[52:55]
	v_mfma_f32_16x16x32_bf16 v[56:59], v[158:161], v[182:185], v[56:59]
	v_mfma_f32_16x16x32_bf16 v[72:75], v[162:165], v[182:185], v[72:75]
	v_mfma_f32_16x16x32_bf16 v[68:71], v[170:173], v[182:185], v[68:71]
	v_mfma_f32_16x16x32_bf16 v[76:79], v[144:147], v[186:189], v[76:79]
	v_mfma_f32_16x16x32_bf16 v[80:83], v[158:161], v[186:189], v[80:83]
	v_mfma_f32_16x16x32_bf16 v[100:103], v[162:165], v[186:189], v[100:103]
	v_mfma_f32_16x16x32_bf16 v[96:99], v[170:173], v[186:189], v[96:99]
	s_setprio 0
	s_barrier
	ds_read_b128 v[174:177], v235 offset:4096
	ds_read_b128 v[178:181], v235 offset:5120
	ds_read_b128 v[182:185], v235 offset:6144
	ds_read_b128 v[186:189], v235 offset:7168
	s_waitcnt vmcnt(0)
	s_waitcnt lgkmcnt(0)
	s_barrier
	s_setprio 1
	v_mfma_f32_16x16x32_bf16 v[104:107], v[144:147], v[174:177], v[104:107]
	v_mfma_f32_16x16x32_bf16 v[108:111], v[158:161], v[174:177], v[108:111]
	v_mfma_f32_16x16x32_bf16 v[120:123], v[162:165], v[174:177], v[120:123]
	v_mfma_f32_16x16x32_bf16 v[116:119], v[170:173], v[174:177], v[116:119]
	v_mfma_f32_16x16x32_bf16 v[124:127], v[144:147], v[178:181], v[124:127]
	v_mfma_f32_16x16x32_bf16 v[112:115], v[158:161], v[178:181], v[112:115]
	v_mfma_f32_16x16x32_bf16 v[92:95], v[162:165], v[178:181], v[92:95]
	v_mfma_f32_16x16x32_bf16 v[88:91], v[170:173], v[178:181], v[88:91]
	v_mfma_f32_16x16x32_bf16 v[84:87], v[144:147], v[182:185], v[84:87]
	v_mfma_f32_16x16x32_bf16 v[64:67], v[158:161], v[182:185], v[64:67]
	v_mfma_f32_16x16x32_bf16 v[60:63], v[162:165], v[182:185], v[60:63]
	v_mfma_f32_16x16x32_bf16 v[44:47], v[170:173], v[182:185], v[44:47]
	v_mfma_f32_16x16x32_bf16 v[36:39], v[144:147], v[186:189], v[36:39]
	v_mfma_f32_16x16x32_bf16 v[32:35], v[158:161], v[186:189], v[32:35]
	v_mfma_f32_16x16x32_bf16 v[24:27], v[162:165], v[186:189], v[24:27]
	v_mfma_f32_16x16x32_bf16 v[8:11], v[170:173], v[186:189], v[8:11]
	s_setprio 0
	s_barrier
	v_add_u32_e32 v235, 0x18000, v140
	v_add_u32_e32 v236, 0x18000, v141
	ds_read_b128 v[174:177], v235
	ds_read_b128 v[144:147], v236 offset:16384
	ds_read_b128 v[158:161], v236 offset:17408
	ds_read_b128 v[162:165], v236 offset:18432
	ds_read_b128 v[170:173], v236 offset:19456
	ds_read_b128 v[178:181], v235 offset:1024
	ds_read_b128 v[182:185], v235 offset:2048
	ds_read_b128 v[186:189], v235 offset:3072
	s_waitcnt lgkmcnt(0)
	s_barrier
	s_setprio 1
	v_mfma_f32_16x16x32_bf16 v[0:3], v[144:147], v[174:177], v[0:3]
	v_mfma_f32_16x16x32_bf16 v[4:7], v[158:161], v[174:177], v[4:7]
	v_mfma_f32_16x16x32_bf16 v[16:19], v[162:165], v[174:177], v[16:19]
	v_mfma_f32_16x16x32_bf16 v[12:15], v[170:173], v[174:177], v[12:15]
	v_mfma_f32_16x16x32_bf16 v[20:23], v[144:147], v[178:181], v[20:23]
	v_mfma_f32_16x16x32_bf16 v[28:31], v[158:161], v[178:181], v[28:31]
	v_mfma_f32_16x16x32_bf16 v[48:51], v[162:165], v[178:181], v[48:51]
	v_mfma_f32_16x16x32_bf16 v[40:43], v[170:173], v[178:181], v[40:43]
	v_mfma_f32_16x16x32_bf16 v[52:55], v[144:147], v[182:185], v[52:55]
	v_mfma_f32_16x16x32_bf16 v[56:59], v[158:161], v[182:185], v[56:59]
	v_mfma_f32_16x16x32_bf16 v[72:75], v[162:165], v[182:185], v[72:75]
	v_mfma_f32_16x16x32_bf16 v[68:71], v[170:173], v[182:185], v[68:71]
	v_mfma_f32_16x16x32_bf16 v[76:79], v[144:147], v[186:189], v[76:79]
	v_mfma_f32_16x16x32_bf16 v[80:83], v[158:161], v[186:189], v[80:83]
	v_mfma_f32_16x16x32_bf16 v[100:103], v[162:165], v[186:189], v[100:103]
	v_mfma_f32_16x16x32_bf16 v[96:99], v[170:173], v[186:189], v[96:99]
	s_setprio 0
	s_barrier
	ds_read_b128 v[174:177], v235 offset:4096
	ds_read_b128 v[178:181], v235 offset:5120
	ds_read_b128 v[182:185], v235 offset:6144
	ds_read_b128 v[186:189], v235 offset:7168
	s_waitcnt lgkmcnt(0)
	s_barrier
	s_setprio 1
	v_mfma_f32_16x16x32_bf16 v[104:107], v[144:147], v[174:177], v[104:107]
	v_mfma_f32_16x16x32_bf16 v[108:111], v[158:161], v[174:177], v[108:111]
	v_mfma_f32_16x16x32_bf16 v[120:123], v[162:165], v[174:177], v[120:123]
	v_mfma_f32_16x16x32_bf16 v[116:119], v[170:173], v[174:177], v[116:119]
	v_mfma_f32_16x16x32_bf16 v[124:127], v[144:147], v[178:181], v[124:127]
	v_mfma_f32_16x16x32_bf16 v[112:115], v[158:161], v[178:181], v[112:115]
	v_mfma_f32_16x16x32_bf16 v[92:95], v[162:165], v[178:181], v[92:95]
	v_mfma_f32_16x16x32_bf16 v[88:91], v[170:173], v[178:181], v[88:91]
	v_mfma_f32_16x16x32_bf16 v[84:87], v[144:147], v[182:185], v[84:87]
	v_mfma_f32_16x16x32_bf16 v[64:67], v[158:161], v[182:185], v[64:67]
	v_mfma_f32_16x16x32_bf16 v[60:63], v[162:165], v[182:185], v[60:63]
	v_mfma_f32_16x16x32_bf16 v[44:47], v[170:173], v[182:185], v[44:47]
	v_mfma_f32_16x16x32_bf16 v[36:39], v[144:147], v[186:189], v[36:39]
	v_mfma_f32_16x16x32_bf16 v[32:35], v[158:161], v[186:189], v[32:35]
	v_mfma_f32_16x16x32_bf16 v[24:27], v[162:165], v[186:189], v[24:27]
	v_mfma_f32_16x16x32_bf16 v[8:11], v[170:173], v[186:189], v[8:11]
	s_setprio 0
	s_barrier
	s_cmp_ge_u32 s98, 0x2000
	s_cbranch_scc1 .Lmg1_done
	s_barrier

; __device__ __forceinline__ int trow(int j) { const int t = otid(); return ((t >> 6) * 2 + j) * 16 + ((t & 63) >> 2); }
; __device__ __forceinline__ int tkc() { const int l = otid() & 63; return ((l & 3) ^ ((0 - (l >> 4)) & 3)) * 8; }
; __device__ __forceinline__ int perm_row(int R) { return (R & ~63) | (((R >> 2) & 3) * 16 + ((R >> 4) & 3) * 4 + (R & 3)); }
; __device__ __forceinline__ TP merge_ptrs(const Params& p, int mt, int nt, int br) {
;   TP t;
;   t.a0 = (const u16*)(p.ws + (br ? OFF_NA : OFF_HY)) + (size_t)(mt * 256 + trow(0)) * 512 + tkc(); t.a1 = t.a0 + 16 * 512;
;   t.b0 = (const u16*)(p.ws + (br ? OFF_WBN : OFF_WBH)) + (size_t)(nt * 256 + perm_row(trow(0))) * 512 + tkc();
;   t.b1 = (const u16*)(p.ws + (br ? OFF_WBN : OFF_WBH)) + (size_t)(nt * 256 + perm_row(trow(1))) * 512 + tkc();
;   return t;
; }
; __device__ __forceinline__ void merge_phase(const Params& p, int first, int step, int n, char* lds) {
;     ...
;     cur = merge_ptrs(p, mt, nt, 1);
;     gemm_issue3(cur, lds);
; #pragma unroll
;     for (int i = 0; i < 8; ++i) {
;       const int m = mt * 256 + wm * 128 + i * 16 + lr;
;       const int n0 = nt * 256 + wn * 64 + lq * 16;
;       union { uint4 v[2]; u16 e[16]; } gh, gn;
;       gh.v[0] = *(const uint4*)(gates + (size_t)m * 2048 + n0); gh.v[1] = *(const uint4*)(gates + (size_t)m * 2048 + n0 + 8);
;       gn.v[0] = *(const uint4*)(gates + (size_t)m * 2048 + 1024 + n0); gn.v[1] = *(const uint4*)(gates + (size_t)m * 2048 + 1024 + n0 + 8);
.LBB0_859:
	s_lshl_b32 s54, s71, 6
	v_mov_b32_e32 v128, v153
	s_barrier
	s_and_b32 s54, s54, 0xffffff00
	v_mov_b32_e32 v199, v153
	v_ashrrev_i32_e32 v129, 1, v128
	v_bfe_u32 v198, v128, 2, 4
	v_and_b32_e32 v155, 0xffffffe0, v129
	v_or_b32_e32 v128, s54, v198
	v_add_u32_e32 v128, v128, v155
	v_lshrrev_b32_e32 v130, 4, v199
	v_sub_u32_e32 v200, 0, v130
	v_ashrrev_i32_e32 v129, 31, v128
	v_xor_b32_e32 v130, v199, v200
	v_lshlrev_b64 v[128:129], 10, v[128:129]
	v_lshlrev_b32_e32 v130, 4, v130
	v_lshl_add_u64 v[128:129], s[22:23], 0, v[128:129]
	v_and_b32_e32 v156, 48, v130
	v_lshl_add_u64 v[158:159], v[128:129], 0, v[156:157]
	v_mov_b32_e32 v128, v153
	s_lshl_b32 s55, s71, 8
	s_and_b32 s55, s55, 0x300
	v_ashrrev_i32_e32 v129, 1, v128
	v_and_b32_e32 v201, 0xffffffc0, v129
	v_and_b32_e32 v202, 48, v128
	v_lshrrev_b32_e32 v129, 2, v129
	v_bfe_u32 v204, v128, 2, 2
	v_mov_b32_e32 v205, v153
	v_and_b32_e32 v203, 8, v129
	v_or_b32_e32 v128, v202, v204
	v_add_u32_e32 v129, s55, v201
	v_or3_b32 v128, v129, v128, v203
	v_lshrrev_b32_e32 v130, 4, v205
	v_sub_u32_e32 v206, 0, v130
	v_ashrrev_i32_e32 v129, 31, v128
	v_xor_b32_e32 v130, v205, v206
	v_lshlrev_b64 v[128:129], 10, v[128:129]
	v_lshlrev_b32_e32 v130, 4, v130
	v_lshl_add_u64 v[128:129], s[24:25], 0, v[128:129]
	v_and_b32_e32 v156, 48, v130
	v_lshl_add_u64 v[160:161], v[128:129], 0, v[156:157]
	v_mov_b32_e32 v128, v153
	v_mov_b32_e32 v211, v153
	v_ashrrev_i32_e32 v129, 1, v128
	v_and_b32_e32 v208, 48, v128
	v_bfe_u32 v210, v128, 2, 2
	v_and_b32_e32 v207, 0xffffffc0, v129
	v_lshrrev_b32_e32 v129, 2, v129
	v_or3_b32 v128, v208, v210, s55
	v_and_b32_e32 v209, 8, v129
	v_add_u32_e32 v128, v207, v128
	v_or3_b32 v128, v128, v209, 4
	v_lshrrev_b32_e32 v130, 4, v211
	v_sub_u32_e32 v212, 0, v130
	v_ashrrev_i32_e32 v129, 31, v128
	v_xor_b32_e32 v130, v211, v212
	v_lshlrev_b64 v[128:129], 10, v[128:129]
	v_lshlrev_b32_e32 v130, 4, v130
	v_add_u32_e32 v166, s54, v149
	v_lshl_add_u64 v[128:129], s[24:25], 0, v[128:129]
	v_and_b32_e32 v156, 48, v130
	v_ashrrev_i32_e32 v167, 31, v166
	v_lshl_add_u64 v[164:165], v[128:129], 0, v[156:157]
	v_or_b32_e32 v168, s55, v151
	v_lshlrev_b64 v[128:129], 12, v[166:167]
	v_lshl_add_u64 v[128:129], s[12:13], 0, v[128:129]
	v_lshlrev_b32_e32 v156, 1, v168
	v_mov_b32_e32 v130, v153
	v_lshl_add_u64 v[170:171], v[128:129], 0, v[156:157]
	global_load_dwordx4 v[136:139], v[170:171], off offset:2048
	global_load_dwordx4 v[132:135], v[170:171], off offset:2064
	global_load_dwordx4 v[144:147], v[170:171], off
	global_load_dwordx4 v[140:143], v[170:171], off offset:16
	v_lshlrev_b32_e32 v128, 5, v130
	v_lshlrev_b32_e32 v129, 4, v130
	v_and_b32_e32 v128, 0xfffff800, v128
	v_and_b32_e32 v129, 0x3f0, v129
	v_add3_u32 v130, 0, v128, v129
	v_add_u32_e32 v129, 0x400, v130
	v_readfirstlane_b32 s54, v130
	v_add_u32_e32 v128, 0x4000, v130
	s_mov_b32 m0, s54
	v_readfirstlane_b32 s54, v129
	v_lshl_add_u64 v[162:163], v[158:159], 0, s[30:31]
	global_load_lds_dwordx4 v[158:159], off
	s_mov_b32 m0, s54
	v_readfirstlane_b32 s54, v128
	v_add_u32_e32 v128, 0x4400, v130
	global_load_lds_dwordx4 v[162:163], off
	s_mov_b32 m0, s54
	v_readfirstlane_b32 s54, v128
	v_add_u32_e32 v131, 0x8000, v130
	global_load_lds_dwordx4 v[160:161], off
	s_mov_b32 m0, s54
	v_readfirstlane_b32 s54, v131
	v_add_u32_e32 v131, 0x8400, v130
	global_load_lds_dwordx4 v[164:165], off
	v_add_u32_e32 v172, 0xc000, v130
	v_lshl_add_u64 v[128:129], v[158:159], 0, 64
	s_mov_b32 m0, s54
	v_readfirstlane_b32 s54, v131
	global_load_lds_dwordx4 v[128:129], off
	v_lshl_add_u64 v[128:129], v[158:159], 0, s[34:35]
	s_mov_b32 m0, s54
	v_readfirstlane_b32 s54, v172
	v_add_u32_e32 v131, 0xc400, v130
	global_load_lds_dwordx4 v[128:129], off
	v_lshl_add_u64 v[128:129], v[160:161], 0, 64
	s_mov_b32 m0, s54
	v_readfirstlane_b32 s54, v131
	v_add_u32_e32 v131, 0x10000, v130
	global_load_lds_dwordx4 v[128:129], off
	v_lshl_add_u64 v[128:129], v[164:165], 0, 64
	s_mov_b32 m0, s54
	v_readfirstlane_b32 s54, v131
	v_add_u32_e32 v131, 0x10400, v130
	global_load_lds_dwordx4 v[128:129], off
	v_add_u32_e32 v172, 0x14000, v130
	v_lshl_add_u64 v[128:129], v[158:159], 0, s[36:37]
	s_mov_b32 m0, s54
	v_readfirstlane_b32 s54, v131
	global_load_lds_dwordx4 v[128:129], off
	v_lshl_add_u64 v[128:129], v[158:159], 0, s[38:39]
	s_mov_b32 m0, s54
	v_readfirstlane_b32 s54, v172
	v_or_b32_e32 v172, 16, v166
	global_load_lds_dwordx4 v[128:129], off
	v_lshl_add_u64 v[128:129], v[160:161], 0, s[36:37]
	s_mov_b32 m0, s54
	v_ashrrev_i32_e32 v173, 31, v172
	global_load_lds_dwordx4 v[128:129], off
	v_lshlrev_b64 v[128:129], 12, v[172:173]
	v_lshl_add_u64 v[128:129], s[12:13], 0, v[128:129]
	v_lshl_add_u64 v[174:175], v[128:129], 0, v[156:157]
	global_load_dwordx4 v[180:183], v[174:175], off offset:2048
	global_load_dwordx4 v[184:187], v[174:175], off
	v_add_u32_e32 v130, 0x14400, v130
	v_lshl_add_u64 v[128:129], v[164:165], 0, s[36:37]
	v_readfirstlane_b32 s54, v130
	s_waitcnt vmcnt(0)
; __device__ __forceinline__ float frcp(float x) { return __builtin_amdgcn_rcpf(x); }
; __device__ __forceinline__ float bf2f(u16 h) { return __uint_as_float(((unsigned)h) << 16); }
; __device__ __forceinline__ void merge_phase(const Params& p, int first, int step, int n, char* lds) {
;     ...
;     for (int i = 0; i < 8; ++i) {
;       const int m = mt * 256 + wm * 128 + i * 16 + lr;
;       const int n0 = nt * 256 + wn * 64 + lq * 16;
;       union { uint4 v[2]; u16 e[16]; } gh, gn;
;       gh.v[0] = *(const uint4*)(gates + (size_t)m * 2048 + n0); gh.v[1] = *(const uint4*)(gates + (size_t)m * 2048 + n0 + 8);
;       gn.v[0] = *(const uint4*)(gates + (size_t)m * 2048 + 1024 + n0); gn.v[1] = *(const uint4*)(gates + (size_t)m * 2048 + 1024 + n0 + 8);
; #pragma unroll
;       for (int j = 0; j < 4; ++j)
; #pragma unroll
;         for (int e = 0; e < 4; ++e) acc[i][j][e] *= bf2f(gh.e[j * 4 + e]) * frcp(bf2f(gn.e[j * 4 + e]));
;     }
	v_lshlrev_b32_e32 v130, 16, v136
	v_and_b32_e32 v131, 0xffff0000, v136
	v_rcp_f32_e32 v130, v130
	v_rcp_f32_e32 v131, v131
	s_mov_b32 m0, s54
	v_and_b32_e32 v136, 0xffff0000, v139
	global_load_lds_dwordx4 v[128:129], off
	v_and_b32_e32 v129, 0xffff0000, v144
	v_lshlrev_b32_e32 v128, 16, v144
	v_pk_mul_f32 v[128:129], v[130:131], v[128:129]
	v_lshlrev_b32_e32 v130, 16, v137
	v_and_b32_e32 v131, 0xffff0000, v137
	v_rcp_f32_e32 v130, v130
	v_rcp_f32_e32 v131, v131
	v_pk_mul_f32 v[0:1], v[0:1], v[128:129]
	v_and_b32_e32 v129, 0xffff0000, v145
	v_lshlrev_b32_e32 v128, 16, v145
	v_pk_mul_f32 v[128:129], v[130:131], v[128:129]
	v_lshlrev_b32_e32 v130, 16, v138
	v_and_b32_e32 v131, 0xffff0000, v138
	v_rcp_f32_e32 v130, v130
	v_rcp_f32_e32 v131, v131
	v_pk_mul_f32 v[2:3], v[2:3], v[128:129]
	v_and_b32_e32 v129, 0xffff0000, v146
	v_lshlrev_b32_e32 v128, 16, v146
	v_pk_mul_f32 v[128:129], v[130:131], v[128:129]
	v_rcp_f32_e32 v145, v136
	v_pk_mul_f32 v[4:5], v[4:5], v[128:129]
	v_lshlrev_b32_e32 v128, 16, v139
	v_rcp_f32_e32 v144, v128
	global_load_dwordx4 v[128:131], v[174:175], off offset:2064
	global_load_dwordx4 v[136:139], v[174:175], off offset:16
	v_lshlrev_b32_e32 v146, 16, v132
	v_and_b32_e32 v132, 0xffff0000, v132
	v_and_b32_e32 v177, 0xffff0000, v147
	v_lshlrev_b32_e32 v176, 16, v147
	v_rcp_f32_e32 v146, v146
	v_rcp_f32_e32 v147, v132
	v_pk_mul_f32 v[144:145], v[144:145], v[176:177]
	v_lshlrev_b32_e32 v132, 16, v133
	v_and_b32_e32 v133, 0xffff0000, v133
	v_pk_mul_f32 v[6:7], v[6:7], v[144:145]
	v_and_b32_e32 v145, 0xffff0000, v140
	v_lshlrev_b32_e32 v144, 16, v140
	v_rcp_f32_e32 v132, v132
	v_rcp_f32_e32 v133, v133
	v_pk_mul_f32 v[144:145], v[146:147], v[144:145]
	v_lshlrev_b32_e32 v140, 16, v134
	v_and_b32_e32 v134, 0xffff0000, v134
	v_pk_mul_f32 v[16:17], v[16:17], v[144:145]
	v_and_b32_e32 v145, 0xffff0000, v141
	v_lshlrev_b32_e32 v144, 16, v141
	v_rcp_f32_e32 v140, v140
	v_rcp_f32_e32 v141, v134
	v_pk_mul_f32 v[132:133], v[132:133], v[144:145]
	v_or_b32_e32 v176, 32, v166
	v_pk_mul_f32 v[18:19], v[18:19], v[132:133]
	v_and_b32_e32 v133, 0xffff0000, v142
	v_lshlrev_b32_e32 v132, 16, v142
	v_ashrrev_i32_e32 v177, 31, v176
	v_pk_mul_f32 v[132:133], v[140:141], v[132:133]
	v_lshlrev_b64 v[140:141], 12, v[176:177]
	v_lshl_add_u64 v[140:141], s[12:13], 0, v[140:141]
	v_lshl_add_u64 v[178:179], v[140:141], 0, v[156:157]
	global_load_dwordx4 v[144:147], v[178:179], off offset:2048
	v_pk_mul_f32 v[12:13], v[12:13], v[132:133]
	v_lshlrev_b32_e32 v132, 16, v135
	v_and_b32_e32 v133, 0xffff0000, v135
	v_rcp_f32_e32 v132, v132
	v_rcp_f32_e32 v133, v133
	global_load_dwordx4 v[188:191], v[178:179], off
	v_and_b32_e32 v135, 0xffff0000, v143
	v_lshlrev_b32_e32 v134, 16, v143
	v_pk_mul_f32 v[132:133], v[132:133], v[134:135]
	v_lshlrev_b32_e32 v134, 16, v180
	v_and_b32_e32 v135, 0xffff0000, v180
	v_rcp_f32_e32 v134, v134
	v_rcp_f32_e32 v135, v135
	v_pk_mul_f32 v[14:15], v[14:15], v[132:133]
	v_and_b32_e32 v133, 0xffff0000, v184
	v_lshlrev_b32_e32 v132, 16, v184
	v_pk_mul_f32 v[132:133], v[134:135], v[132:133]
	v_lshlrev_b32_e32 v134, 16, v181
	v_and_b32_e32 v135, 0xffff0000, v181
	v_rcp_f32_e32 v134, v134
	v_rcp_f32_e32 v135, v135
	v_pk_mul_f32 v[20:21], v[20:21], v[132:133]
	v_and_b32_e32 v133, 0xffff0000, v185
	v_lshlrev_b32_e32 v132, 16, v185
	v_pk_mul_f32 v[132:133], v[134:135], v[132:133]
	v_lshlrev_b32_e32 v134, 16, v182
	v_and_b32_e32 v135, 0xffff0000, v182
	v_rcp_f32_e32 v134, v134
	v_rcp_f32_e32 v135, v135
	v_pk_mul_f32 v[22:23], v[22:23], v[132:133]
	v_and_b32_e32 v133, 0xffff0000, v186
	v_lshlrev_b32_e32 v132, 16, v186
	v_pk_mul_f32 v[132:133], v[134:135], v[132:133]
	v_and_b32_e32 v140, 0xffff0000, v183
	v_pk_mul_f32 v[28:29], v[28:29], v[132:133]
	v_lshlrev_b32_e32 v132, 16, v183
	v_rcp_f32_e32 v180, v132
	global_load_dwordx4 v[132:135], v[178:179], off offset:2064
	v_rcp_f32_e32 v181, v140
	global_load_dwordx4 v[140:143], v[178:179], off offset:16
	v_and_b32_e32 v183, 0xffff0000, v187
	v_lshlrev_b32_e32 v182, 16, v187
	v_pk_mul_f32 v[180:181], v[180:181], v[182:183]
	v_or_b32_e32 v184, 64, v166
	v_pk_mul_f32 v[30:31], v[30:31], v[180:181]
	s_waitcnt vmcnt(0)
	v_lshlrev_b32_e32 v182, 16, v128
	v_and_b32_e32 v128, 0xffff0000, v128
	v_rcp_f32_e32 v182, v182
	v_rcp_f32_e32 v183, v128
	v_lshlrev_b32_e32 v128, 16, v129
	v_and_b32_e32 v129, 0xffff0000, v129
	v_and_b32_e32 v181, 0xffff0000, v136
	v_lshlrev_b32_e32 v180, 16, v136
	v_rcp_f32_e32 v128, v128
	v_rcp_f32_e32 v129, v129
	v_pk_mul_f32 v[180:181], v[182:183], v[180:181]
	v_lshlrev_b32_e32 v136, 16, v130
	v_and_b32_e32 v130, 0xffff0000, v130
	v_pk_mul_f32 v[48:49], v[48:49], v[180:181]
	v_and_b32_e32 v181, 0xffff0000, v137
	v_lshlrev_b32_e32 v180, 16, v137
	v_rcp_f32_e32 v136, v136
	v_rcp_f32_e32 v137, v130
	v_pk_mul_f32 v[128:129], v[128:129], v[180:181]
	v_or_b32_e32 v180, 48, v166
	v_pk_mul_f32 v[50:51], v[50:51], v[128:129]
	v_and_b32_e32 v129, 0xffff0000, v138
	v_lshlrev_b32_e32 v128, 16, v138
	v_ashrrev_i32_e32 v181, 31, v180
	v_pk_mul_f32 v[128:129], v[136:137], v[128:129]
	v_lshlrev_b64 v[136:137], 12, v[180:181]
	v_lshl_add_u64 v[136:137], s[12:13], 0, v[136:137]
	v_lshl_add_u64 v[182:183], v[136:137], 0, v[156:157]
	global_load_dwordx4 v[192:195], v[182:183], off offset:2048
	global_load_dwordx4 v[214:217], v[182:183], off
	v_pk_mul_f32 v[40:41], v[40:41], v[128:129]
	v_lshlrev_b32_e32 v128, 16, v131
	v_and_b32_e32 v129, 0xffff0000, v131
	v_rcp_f32_e32 v128, v128
	v_rcp_f32_e32 v129, v129
	v_and_b32_e32 v131, 0xffff0000, v139
	v_lshlrev_b32_e32 v130, 16, v139
	v_and_b32_e32 v136, 0xffff0000, v147
	v_pk_mul_f32 v[128:129], v[128:129], v[130:131]
	v_lshlrev_b32_e32 v130, 16, v144
; __device__ __forceinline__ float frcp(float x) { return __builtin_amdgcn_rcpf(x); }
; __device__ __forceinline__ float bf2f(u16 h) { return __uint_as_float(((unsigned)h) << 16); }
; __device__ __forceinline__ void merge_phase(const Params& p, int first, int step, int n, char* lds) {
;     ...
;     for (int i = 0; i < 8; ++i) {
;       const int m = mt * 256 + wm * 128 + i * 16 + lr;
;       const int n0 = nt * 256 + wn * 64 + lq * 16;
;       union { uint4 v[2]; u16 e[16]; } gh, gn;
;       gh.v[0] = *(const uint4*)(gates + (size_t)m * 2048 + n0); gh.v[1] = *(const uint4*)(gates + (size_t)m * 2048 + n0 + 8);
;       gn.v[0] = *(const uint4*)(gates + (size_t)m * 2048 + 1024 + n0); gn.v[1] = *(const uint4*)(gates + (size_t)m * 2048 + 1024 + n0 + 8);
; #pragma unroll
;       for (int j = 0; j < 4; ++j)
; #pragma unroll
;         for (int e = 0; e < 4; ++e) acc[i][j][e] *= bf2f(gh.e[j * 4 + e]) * frcp(bf2f(gn.e[j * 4 + e]));
;     }
	v_and_b32_e32 v131, 0xffff0000, v144
	v_rcp_f32_e32 v130, v130
	v_rcp_f32_e32 v131, v131
	v_pk_mul_f32 v[42:43], v[42:43], v[128:129]
	v_and_b32_e32 v129, 0xffff0000, v188
	v_lshlrev_b32_e32 v128, 16, v188
	v_pk_mul_f32 v[128:129], v[130:131], v[128:129]
	v_lshlrev_b32_e32 v130, 16, v145
	v_and_b32_e32 v131, 0xffff0000, v145
	v_rcp_f32_e32 v130, v130
	v_rcp_f32_e32 v131, v131
	v_pk_mul_f32 v[52:53], v[52:53], v[128:129]
	v_and_b32_e32 v129, 0xffff0000, v189
	v_lshlrev_b32_e32 v128, 16, v189
	v_pk_mul_f32 v[128:129], v[130:131], v[128:129]
	v_lshlrev_b32_e32 v130, 16, v146
	v_and_b32_e32 v131, 0xffff0000, v146
	v_rcp_f32_e32 v130, v130
	v_rcp_f32_e32 v131, v131
	v_pk_mul_f32 v[54:55], v[54:55], v[128:129]
	v_and_b32_e32 v129, 0xffff0000, v190
	v_lshlrev_b32_e32 v128, 16, v190
	v_pk_mul_f32 v[128:129], v[130:131], v[128:129]
	v_rcp_f32_e32 v145, v136
	v_pk_mul_f32 v[56:57], v[56:57], v[128:129]
	v_lshlrev_b32_e32 v128, 16, v147
	v_rcp_f32_e32 v144, v128
	global_load_dwordx4 v[128:131], v[182:183], off offset:2064
	global_load_dwordx4 v[136:139], v[182:183], off offset:16
	v_and_b32_e32 v147, 0xffff0000, v191
	v_lshlrev_b32_e32 v146, 16, v191
	v_pk_mul_f32 v[144:145], v[144:145], v[146:147]
	v_lshlrev_b32_e32 v146, 16, v132
	v_and_b32_e32 v132, 0xffff0000, v132
	v_rcp_f32_e32 v146, v146
	v_rcp_f32_e32 v147, v132
	v_lshlrev_b32_e32 v132, 16, v133
	v_and_b32_e32 v133, 0xffff0000, v133
	v_pk_mul_f32 v[58:59], v[58:59], v[144:145]
	v_and_b32_e32 v145, 0xffff0000, v140
	v_lshlrev_b32_e32 v144, 16, v140
	v_rcp_f32_e32 v132, v132
	v_rcp_f32_e32 v133, v133
	v_pk_mul_f32 v[144:145], v[146:147], v[144:145]
	v_lshlrev_b32_e32 v140, 16, v134
	v_and_b32_e32 v134, 0xffff0000, v134
	v_pk_mul_f32 v[72:73], v[72:73], v[144:145]
	v_and_b32_e32 v145, 0xffff0000, v141
	v_lshlrev_b32_e32 v144, 16, v141
	v_rcp_f32_e32 v140, v140
	v_rcp_f32_e32 v141, v134
	v_pk_mul_f32 v[132:133], v[132:133], v[144:145]
	v_ashrrev_i32_e32 v185, 31, v184
	v_pk_mul_f32 v[74:75], v[74:75], v[132:133]
	v_and_b32_e32 v133, 0xffff0000, v142
	v_lshlrev_b32_e32 v132, 16, v142
	v_pk_mul_f32 v[132:133], v[140:141], v[132:133]
	v_lshlrev_b64 v[140:141], 12, v[184:185]
	v_lshl_add_u64 v[140:141], s[12:13], 0, v[140:141]
	v_lshl_add_u64 v[186:187], v[140:141], 0, v[156:157]
	global_load_dwordx4 v[218:221], v[186:187], off offset:2048
	v_pk_mul_f32 v[68:69], v[68:69], v[132:133]
	v_lshlrev_b32_e32 v132, 16, v135
	v_and_b32_e32 v133, 0xffff0000, v135
	v_rcp_f32_e32 v132, v132
	v_rcp_f32_e32 v133, v133
	global_load_dwordx4 v[222:225], v[186:187], off
	v_and_b32_e32 v135, 0xffff0000, v143
	v_lshlrev_b32_e32 v134, 16, v143
	v_pk_mul_f32 v[132:133], v[132:133], v[134:135]
	s_waitcnt vmcnt(0)
	v_lshlrev_b32_e32 v134, 16, v192
	v_and_b32_e32 v135, 0xffff0000, v192
	v_rcp_f32_e32 v134, v134
	v_rcp_f32_e32 v135, v135
	v_pk_mul_f32 v[70:71], v[70:71], v[132:133]
	v_and_b32_e32 v133, 0xffff0000, v214
	v_lshlrev_b32_e32 v132, 16, v214
	v_pk_mul_f32 v[132:133], v[134:135], v[132:133]
	v_lshlrev_b32_e32 v134, 16, v193
	v_and_b32_e32 v135, 0xffff0000, v193
	v_rcp_f32_e32 v134, v134
	v_rcp_f32_e32 v135, v135
	v_pk_mul_f32 v[76:77], v[76:77], v[132:133]
	v_and_b32_e32 v133, 0xffff0000, v215
	v_lshlrev_b32_e32 v132, 16, v215
	v_pk_mul_f32 v[132:133], v[134:135], v[132:133]
	v_lshlrev_b32_e32 v134, 16, v194
	v_and_b32_e32 v135, 0xffff0000, v194
	v_rcp_f32_e32 v134, v134
	v_rcp_f32_e32 v135, v135
	v_pk_mul_f32 v[78:79], v[78:79], v[132:133]
	v_and_b32_e32 v133, 0xffff0000, v216
	v_lshlrev_b32_e32 v132, 16, v216
	v_pk_mul_f32 v[132:133], v[134:135], v[132:133]
	global_load_dwordx4 v[142:145], v[186:187], off offset:16
	v_pk_mul_f32 v[80:81], v[80:81], v[132:133]
	v_lshlrev_b32_e32 v132, 16, v195
	v_rcp_f32_e32 v140, v132
	global_load_dwordx4 v[132:135], v[186:187], off offset:2064
	v_and_b32_e32 v141, 0xffff0000, v195
	v_rcp_f32_e32 v141, v141
	v_and_b32_e32 v147, 0xffff0000, v217
	v_lshlrev_b32_e32 v146, 16, v217
	v_or_b32_e32 v188, 0x50, v166
	v_pk_mul_f32 v[140:141], v[140:141], v[146:147]
	v_ashrrev_i32_e32 v189, 31, v188
	v_pk_mul_f32 v[82:83], v[82:83], v[140:141]
	v_lshlrev_b32_e32 v146, 16, v128
	v_and_b32_e32 v128, 0xffff0000, v128
	v_rcp_f32_e32 v146, v146
	v_rcp_f32_e32 v147, v128
	v_lshlrev_b32_e32 v128, 16, v129
	v_and_b32_e32 v129, 0xffff0000, v129
	v_and_b32_e32 v141, 0xffff0000, v136
	v_lshlrev_b32_e32 v140, 16, v136
	v_rcp_f32_e32 v128, v128
	v_rcp_f32_e32 v129, v129
	v_pk_mul_f32 v[140:141], v[146:147], v[140:141]
	v_lshlrev_b32_e32 v136, 16, v130
	v_and_b32_e32 v130, 0xffff0000, v130
	v_pk_mul_f32 v[100:101], v[100:101], v[140:141]
	v_and_b32_e32 v141, 0xffff0000, v137
	v_lshlrev_b32_e32 v140, 16, v137
	v_rcp_f32_e32 v136, v136
	v_rcp_f32_e32 v137, v130
	v_pk_mul_f32 v[128:129], v[128:129], v[140:141]
	v_lshlrev_b32_e32 v130, 16, v139
	v_pk_mul_f32 v[102:103], v[102:103], v[128:129]
	v_and_b32_e32 v129, 0xffff0000, v138
	v_lshlrev_b32_e32 v128, 16, v138
	v_pk_mul_f32 v[128:129], v[136:137], v[128:129]
	v_lshlrev_b64 v[136:137], 12, v[188:189]
	v_lshl_add_u64 v[136:137], s[12:13], 0, v[136:137]
	v_lshl_add_u64 v[190:191], v[136:137], 0, v[156:157]
	global_load_dwordx4 v[214:217], v[190:191], off offset:2048
	v_pk_mul_f32 v[96:97], v[96:97], v[128:129]
	v_lshlrev_b32_e32 v128, 16, v131
	v_and_b32_e32 v129, 0xffff0000, v131
	v_rcp_f32_e32 v128, v128
	v_rcp_f32_e32 v129, v129
	global_load_dwordx4 v[226:229], v[190:191], off
	v_and_b32_e32 v131, 0xffff0000, v139
	v_and_b32_e32 v136, 0xffff0000, v221
	v_pk_mul_f32 v[128:129], v[128:129], v[130:131]
	v_lshlrev_b32_e32 v130, 16, v218
	v_and_b32_e32 v131, 0xffff0000, v218
	v_rcp_f32_e32 v130, v130
	v_rcp_f32_e32 v131, v131
	v_pk_mul_f32 v[98:99], v[98:99], v[128:129]
	v_and_b32_e32 v129, 0xffff0000, v222
	v_lshlrev_b32_e32 v128, 16, v222
	v_pk_mul_f32 v[128:129], v[130:131], v[128:129]
	v_lshlrev_b32_e32 v130, 16, v219
	v_and_b32_e32 v131, 0xffff0000, v219
	v_rcp_f32_e32 v130, v130
	v_rcp_f32_e32 v131, v131
	v_pk_mul_f32 v[104:105], v[104:105], v[128:129]
	v_and_b32_e32 v129, 0xffff0000, v223
	v_lshlrev_b32_e32 v128, 16, v223
	v_pk_mul_f32 v[128:129], v[130:131], v[128:129]
	v_lshlrev_b32_e32 v130, 16, v220
	v_and_b32_e32 v131, 0xffff0000, v220
	v_rcp_f32_e32 v130, v130
	v_rcp_f32_e32 v131, v131
	v_pk_mul_f32 v[106:107], v[106:107], v[128:129]
	v_and_b32_e32 v129, 0xffff0000, v224
	v_lshlrev_b32_e32 v128, 16, v224
	v_pk_mul_f32 v[128:129], v[130:131], v[128:129]
	v_rcp_f32_e32 v141, v136
	v_pk_mul_f32 v[108:109], v[108:109], v[128:129]
	v_lshlrev_b32_e32 v128, 16, v221
	v_rcp_f32_e32 v140, v128
	global_load_dwordx4 v[128:131], v[190:191], off offset:2064
	global_load_dwordx4 v[136:139], v[190:191], off offset:16
	v_and_b32_e32 v147, 0xffff0000, v225
	v_lshlrev_b32_e32 v146, 16, v225
	v_pk_mul_f32 v[140:141], v[140:141], v[146:147]
	v_or_b32_e32 v192, 0x60, v166
	s_waitcnt vmcnt(0)
; __device__ __forceinline__ float frcp(float x) { return __builtin_amdgcn_rcpf(x); }
; __device__ __forceinline__ float bf2f(u16 h) { return __uint_as_float(((unsigned)h) << 16); }
; __device__ __forceinline__ void merge_phase(const Params& p, int first, int step, int n, char* lds) {
;     ...
;     for (int i = 0; i < 8; ++i) {
;       const int m = mt * 256 + wm * 128 + i * 16 + lr;
;       const int n0 = nt * 256 + wn * 64 + lq * 16;
;       union { uint4 v[2]; u16 e[16]; } gh, gn;
;       gh.v[0] = *(const uint4*)(gates + (size_t)m * 2048 + n0); gh.v[1] = *(const uint4*)(gates + (size_t)m * 2048 + n0 + 8);
;       gn.v[0] = *(const uint4*)(gates + (size_t)m * 2048 + 1024 + n0); gn.v[1] = *(const uint4*)(gates + (size_t)m * 2048 + 1024 + n0 + 8);
; #pragma unroll
;       for (int j = 0; j < 4; ++j)
; #pragma unroll
;         for (int e = 0; e < 4; ++e) acc[i][j][e] *= bf2f(gh.e[j * 4 + e]) * frcp(bf2f(gn.e[j * 4 + e]));
;     }
	v_lshlrev_b32_e32 v146, 16, v132
	v_and_b32_e32 v132, 0xffff0000, v132
	v_rcp_f32_e32 v146, v146
	v_rcp_f32_e32 v147, v132
	v_lshlrev_b32_e32 v132, 16, v133
	v_and_b32_e32 v133, 0xffff0000, v133
	v_rcp_f32_e32 v132, v132
	v_rcp_f32_e32 v133, v133
	v_pk_mul_f32 v[110:111], v[110:111], v[140:141]
	v_and_b32_e32 v141, 0xffff0000, v142
	v_lshlrev_b32_e32 v140, 16, v142
	v_pk_mul_f32 v[140:141], v[146:147], v[140:141]
	v_ashrrev_i32_e32 v193, 31, v192
	v_pk_mul_f32 v[120:121], v[120:121], v[140:141]
	v_and_b32_e32 v141, 0xffff0000, v143
	v_lshlrev_b32_e32 v140, 16, v143
	v_pk_mul_f32 v[132:133], v[132:133], v[140:141]
	v_lshlrev_b32_e32 v140, 16, v134
	v_and_b32_e32 v134, 0xffff0000, v134
	v_rcp_f32_e32 v140, v140
	v_rcp_f32_e32 v141, v134
	v_pk_mul_f32 v[122:123], v[122:123], v[132:133]
	v_and_b32_e32 v133, 0xffff0000, v144
	v_lshlrev_b32_e32 v132, 16, v144
	v_pk_mul_f32 v[132:133], v[140:141], v[132:133]
	v_and_b32_e32 v219, 0xffff0000, v145
	v_pk_mul_f32 v[116:117], v[116:117], v[132:133]
	v_lshlrev_b32_e32 v132, 16, v135
	v_rcp_f32_e32 v146, v132
	v_lshlrev_b64 v[132:133], 12, v[192:193]
	v_lshl_add_u64 v[132:133], s[12:13], 0, v[132:133]
	v_lshl_add_u64 v[194:195], v[132:133], 0, v[156:157]
	global_load_dwordx4 v[140:143], v[194:195], off offset:2048
	v_and_b32_e32 v132, 0xffff0000, v135
	v_rcp_f32_e32 v147, v132
	global_load_dwordx4 v[132:135], v[194:195], off
	v_lshlrev_b32_e32 v218, 16, v145
	v_and_b32_e32 v213, 0xffff0000, v217
	v_pk_mul_f32 v[144:145], v[146:147], v[218:219]
	v_lshlrev_b32_e32 v146, 16, v214
	v_and_b32_e32 v147, 0xffff0000, v214
	v_rcp_f32_e32 v146, v146
	v_rcp_f32_e32 v147, v147
	v_pk_mul_f32 v[118:119], v[118:119], v[144:145]
	v_and_b32_e32 v145, 0xffff0000, v226
	v_lshlrev_b32_e32 v144, 16, v226
	v_pk_mul_f32 v[144:145], v[146:147], v[144:145]
	v_lshlrev_b32_e32 v146, 16, v215
	v_and_b32_e32 v147, 0xffff0000, v215
	v_rcp_f32_e32 v146, v146
	v_rcp_f32_e32 v147, v147
	v_pk_mul_f32 v[124:125], v[124:125], v[144:145]
	v_and_b32_e32 v145, 0xffff0000, v227
	v_lshlrev_b32_e32 v144, 16, v227
	v_pk_mul_f32 v[144:145], v[146:147], v[144:145]
	v_lshlrev_b32_e32 v146, 16, v216
	v_and_b32_e32 v147, 0xffff0000, v216
	v_rcp_f32_e32 v146, v146
	v_rcp_f32_e32 v147, v147
	v_pk_mul_f32 v[126:127], v[126:127], v[144:145]
	v_and_b32_e32 v145, 0xffff0000, v228
	v_lshlrev_b32_e32 v144, 16, v228
	v_pk_mul_f32 v[144:145], v[146:147], v[144:145]
	v_rcp_f32_e32 v219, v213
	v_pk_mul_f32 v[112:113], v[112:113], v[144:145]
	v_lshlrev_b32_e32 v144, 16, v217
	v_rcp_f32_e32 v218, v144
	global_load_dwordx4 v[144:147], v[194:195], off offset:2064
	global_load_dwordx4 v[214:217], v[194:195], off offset:16
	v_and_b32_e32 v221, 0xffff0000, v229
	v_lshlrev_b32_e32 v220, 16, v229
	v_pk_mul_f32 v[218:219], v[218:219], v[220:221]
	s_and_b32 s47, s70, 0xffffff00
	v_pk_mul_f32 v[114:115], v[114:115], v[218:219]
	v_lshlrev_b32_e32 v213, 16, v128
	v_and_b32_e32 v128, 0xffff0000, v128
	v_rcp_f32_e32 v220, v213
	v_rcp_f32_e32 v221, v128
	v_lshlrev_b32_e32 v128, 16, v129
	v_and_b32_e32 v129, 0xffff0000, v129
	v_rcp_f32_e32 v128, v128
	v_rcp_f32_e32 v129, v129
	v_and_b32_e32 v219, 0xffff0000, v136
	v_lshlrev_b32_e32 v218, 16, v136
	v_pk_mul_f32 v[218:219], v[220:221], v[218:219]
	s_and_b32 s46, s69, 0x300
	v_pk_mul_f32 v[92:93], v[92:93], v[218:219]
	v_and_b32_e32 v219, 0xffff0000, v137
	v_lshlrev_b32_e32 v218, 16, v137
	v_pk_mul_f32 v[222:223], v[128:129], v[218:219]
	v_lshlrev_b32_e32 v128, 16, v130
	v_rcp_f32_e32 v224, v128
	v_and_b32_e32 v128, 0xffff0000, v130
	v_rcp_f32_e32 v225, v128
	v_or_b32_e32 v128, 0x70, v166
	v_ashrrev_i32_e32 v129, 31, v128
	v_lshlrev_b64 v[136:137], 12, v[128:129]
	v_lshl_add_u64 v[136:137], s[12:13], 0, v[136:137]
	v_lshl_add_u64 v[136:137], v[136:137], 0, v[156:157]
	global_load_dwordx4 v[218:221], v[136:137], off offset:2048
	v_pk_mul_f32 v[94:95], v[94:95], v[222:223]
	v_and_b32_e32 v223, 0xffff0000, v138
	v_lshlrev_b32_e32 v222, 16, v138
	v_pk_mul_f32 v[226:227], v[224:225], v[222:223]
	global_load_dwordx4 v[222:225], v[136:137], off
	v_lshlrev_b32_e32 v130, 16, v131
	v_and_b32_e32 v131, 0xffff0000, v131
	v_rcp_f32_e32 v130, v130
	v_rcp_f32_e32 v131, v131
	v_pk_mul_f32 v[88:89], v[88:89], v[226:227]
	v_and_b32_e32 v227, 0xffff0000, v139
	v_lshlrev_b32_e32 v226, 16, v139
	s_waitcnt vmcnt(0)
; __device__ __forceinline__ float frcp(float x) { return __builtin_amdgcn_rcpf(x); }
; __device__ __forceinline__ float bf2f(u16 h) { return __uint_as_float(((unsigned)h) << 16); }
; #define GEMM_WAITV(n) asm volatile("s_waitcnt vmcnt(" #n ")" ::: "memory")
; template <bool SWAP>
; __device__ __forceinline__ void gemm_main(f32x4 (&acc)[8][4], const TP& t, int nk, char* lds) {
;     ...
; #pragma unroll 1
;   for (int kt = 0; kt < nk - 3; ++kt) {
;     GEMM_WAITV(8);
;     GEMM_STEP(kt, true)
; __device__ __forceinline__ void merge_phase(const Params& p, int first, int step, int n, char* lds) {
;     ...
;     for (int i = 0; i < 8; ++i) {
;       const int m = mt * 256 + wm * 128 + i * 16 + lr;
;       const int n0 = nt * 256 + wn * 64 + lq * 16;
;       union { uint4 v[2]; u16 e[16]; } gh, gn;
;       gh.v[0] = *(const uint4*)(gates + (size_t)m * 2048 + n0); gh.v[1] = *(const uint4*)(gates + (size_t)m * 2048 + n0 + 8);
;       gn.v[0] = *(const uint4*)(gates + (size_t)m * 2048 + 1024 + n0); gn.v[1] = *(const uint4*)(gates + (size_t)m * 2048 + 1024 + n0 + 8);
; #pragma unroll
;       for (int j = 0; j < 4; ++j)
; #pragma unroll
;         for (int e = 0; e < 4; ++e) acc[i][j][e] *= bf2f(gh.e[j * 4 + e]) * frcp(bf2f(gn.e[j * 4 + e]));
;     }
;     gemm_main<true>(acc, cur, 16, lds);
	v_lshlrev_b32_e32 v138, 16, v140
	v_and_b32_e32 v139, 0xffff0000, v140
	v_rcp_f32_e32 v138, v138
	v_rcp_f32_e32 v139, v139
	v_pk_mul_f32 v[130:131], v[130:131], v[226:227]
	v_and_b32_e32 v229, 0xffff0000, v134
	v_pk_mul_f32 v[90:91], v[90:91], v[130:131]
	v_and_b32_e32 v131, 0xffff0000, v132
	v_lshlrev_b32_e32 v130, 16, v132
	v_lshlrev_b32_e32 v132, 16, v141
	v_pk_mul_f32 v[130:131], v[138:139], v[130:131]
	v_rcp_f32_e32 v138, v132
	v_and_b32_e32 v132, 0xffff0000, v141
	v_rcp_f32_e32 v139, v132
	v_pk_mul_f32 v[84:85], v[84:85], v[130:131]
	v_and_b32_e32 v131, 0xffff0000, v133
	v_lshlrev_b32_e32 v130, 16, v133
	v_pk_mul_f32 v[130:131], v[138:139], v[130:131]
	v_lshlrev_b32_e32 v138, 16, v142
	v_pk_mul_f32 v[86:87], v[86:87], v[130:131]
	global_load_dwordx4 v[130:133], v[136:137], off offset:2064
	v_rcp_f32_e32 v226, v138
	v_and_b32_e32 v138, 0xffff0000, v142
	v_rcp_f32_e32 v227, v138
	global_load_dwordx4 v[138:141], v[136:137], off offset:16
	v_lshlrev_b32_e32 v228, 16, v134
	v_lshlrev_b32_e32 v134, 16, v143
	v_rcp_f32_e32 v142, v134
	v_and_b32_e32 v134, 0xffff0000, v143
	v_rcp_f32_e32 v143, v134
	v_pk_mul_f32 v[226:227], v[226:227], v[228:229]
	s_mov_b32 s54, 0x18000
	v_pk_mul_f32 v[64:65], v[64:65], v[226:227]
	v_and_b32_e32 v227, 0xffff0000, v135
	v_lshlrev_b32_e32 v226, 16, v135
	v_pk_mul_f32 v[134:135], v[142:143], v[226:227]
	v_lshlrev_b32_e32 v142, 16, v144
	v_and_b32_e32 v143, 0xffff0000, v144
	v_rcp_f32_e32 v142, v142
	v_rcp_f32_e32 v143, v143
	v_pk_mul_f32 v[66:67], v[66:67], v[134:135]
	v_and_b32_e32 v135, 0xffff0000, v214
	v_lshlrev_b32_e32 v134, 16, v214
	v_pk_mul_f32 v[134:135], v[142:143], v[134:135]
	v_lshlrev_b32_e32 v142, 16, v145
	v_and_b32_e32 v143, 0xffff0000, v145
	v_rcp_f32_e32 v142, v142
	v_rcp_f32_e32 v143, v143
	v_pk_mul_f32 v[60:61], v[60:61], v[134:135]
	v_and_b32_e32 v135, 0xffff0000, v215
	v_lshlrev_b32_e32 v134, 16, v215
	v_pk_mul_f32 v[134:135], v[142:143], v[134:135]
	v_lshlrev_b32_e32 v142, 16, v146
	v_and_b32_e32 v143, 0xffff0000, v146
	v_rcp_f32_e32 v142, v142
	v_rcp_f32_e32 v143, v143
	v_pk_mul_f32 v[62:63], v[62:63], v[134:135]
	v_and_b32_e32 v135, 0xffff0000, v216
	v_lshlrev_b32_e32 v134, 16, v216
	v_pk_mul_f32 v[134:135], v[142:143], v[134:135]
	v_lshlrev_b32_e32 v142, 16, v147
	v_and_b32_e32 v143, 0xffff0000, v147
	v_rcp_f32_e32 v142, v142
	v_rcp_f32_e32 v143, v143
	v_pk_mul_f32 v[44:45], v[44:45], v[134:135]
	v_and_b32_e32 v135, 0xffff0000, v217
	v_lshlrev_b32_e32 v134, 16, v217
	v_pk_mul_f32 v[134:135], v[142:143], v[134:135]
	v_lshlrev_b32_e32 v142, 16, v218
	v_and_b32_e32 v143, 0xffff0000, v218
	v_rcp_f32_e32 v142, v142
	v_rcp_f32_e32 v143, v143
	v_pk_mul_f32 v[46:47], v[46:47], v[134:135]
	v_and_b32_e32 v135, 0xffff0000, v222
	v_lshlrev_b32_e32 v134, 16, v222
	v_pk_mul_f32 v[134:135], v[142:143], v[134:135]
	v_lshlrev_b32_e32 v142, 16, v219
	v_and_b32_e32 v143, 0xffff0000, v219
	v_rcp_f32_e32 v142, v142
	v_rcp_f32_e32 v143, v143
	v_pk_mul_f32 v[36:37], v[36:37], v[134:135]
	v_and_b32_e32 v135, 0xffff0000, v223
	v_lshlrev_b32_e32 v134, 16, v223
	v_pk_mul_f32 v[134:135], v[142:143], v[134:135]
	v_lshlrev_b32_e32 v142, 16, v220
	v_and_b32_e32 v143, 0xffff0000, v220
	v_rcp_f32_e32 v142, v142
	v_rcp_f32_e32 v143, v143
	v_pk_mul_f32 v[38:39], v[38:39], v[134:135]
	v_and_b32_e32 v135, 0xffff0000, v224
	v_lshlrev_b32_e32 v134, 16, v224
	v_pk_mul_f32 v[134:135], v[142:143], v[134:135]
	v_lshlrev_b32_e32 v142, 16, v221
	v_and_b32_e32 v143, 0xffff0000, v221
	v_rcp_f32_e32 v142, v142
	v_rcp_f32_e32 v143, v143
	v_pk_mul_f32 v[32:33], v[32:33], v[134:135]
	v_and_b32_e32 v135, 0xffff0000, v225
	v_lshlrev_b32_e32 v134, 16, v225
	v_pk_mul_f32 v[134:135], v[142:143], v[134:135]
	s_waitcnt vmcnt(0)
	v_lshlrev_b32_e32 v142, 16, v130
	v_and_b32_e32 v130, 0xffff0000, v130
	v_rcp_f32_e32 v142, v142
	v_rcp_f32_e32 v143, v130
	v_lshlrev_b32_e32 v130, 16, v131
	v_and_b32_e32 v131, 0xffff0000, v131
	v_rcp_f32_e32 v130, v130
	v_rcp_f32_e32 v131, v131
	v_pk_mul_f32 v[34:35], v[34:35], v[134:135]
	v_and_b32_e32 v135, 0xffff0000, v138
	v_lshlrev_b32_e32 v134, 16, v138
	v_pk_mul_f32 v[134:135], v[142:143], v[134:135]
	v_bitop3_b32 v145, v211, 3, v212 bitop3:0x48
	v_pk_mul_f32 v[24:25], v[24:25], v[134:135]
	v_and_b32_e32 v135, 0xffff0000, v139
	v_lshlrev_b32_e32 v134, 16, v139
	v_pk_mul_f32 v[130:131], v[130:131], v[134:135]
	v_lshlrev_b32_e32 v134, 16, v132
	v_and_b32_e32 v132, 0xffff0000, v132
	v_rcp_f32_e32 v134, v134
	v_rcp_f32_e32 v135, v132
	v_lshlrev_b32_e32 v132, 16, v133
	v_and_b32_e32 v133, 0xffff0000, v133
	v_rcp_f32_e32 v132, v132
	v_rcp_f32_e32 v133, v133
	v_pk_mul_f32 v[26:27], v[26:27], v[130:131]
	v_and_b32_e32 v131, 0xffff0000, v140
	v_lshlrev_b32_e32 v130, 16, v140
	v_pk_mul_f32 v[130:131], v[134:135], v[130:131]
	v_bitop3_b32 v134, v205, 3, v206 bitop3:0x48
	v_pk_mul_f32 v[8:9], v[8:9], v[130:131]
	v_and_b32_e32 v131, 0xffff0000, v141
	v_lshlrev_b32_e32 v130, 16, v141
	v_pk_mul_f32 v[130:131], v[132:133], v[130:131]
	s_nop 0
	v_pk_mul_f32 v[10:11], v[10:11], v[130:131]
	v_mov_b32_e32 v130, v153
	s_nop 0
	v_lshlrev_b32_e32 v133, 2, v130
	v_and_b32_e32 v133, 48, v133
	v_sub_u32_e32 v133, 0, v133
	v_and_b32_e32 v138, 15, v130
	v_lshlrev_b32_e32 v131, 5, v130
	v_lshlrev_b32_e32 v132, 4, v130
	v_bitop3_b32 v139, v130, 48, v133 bitop3:0x48
	v_ashrrev_i32_e32 v140, 1, v130
	v_lshlrev_b32_e32 v130, 6, v130
	v_and_b32_e32 v142, 0x33c0, v130
	v_add_u32_e32 v130, s47, v155
	v_and_b32_e32 v131, 0xfffff800, v131
	v_and_b32_e32 v132, 0x3f0, v132
	v_or_b32_e32 v130, v130, v198
	v_add3_u32 v144, 0, v131, v132
	v_ashrrev_i32_e32 v131, 31, v130
	v_lshlrev_b64 v[130:131], 10, v[130:131]
	v_bitop3_b32 v132, v199, 3, v200 bitop3:0x48
	v_lshl_or_b32 v130, v132, 4, v130
	v_add_u32_e32 v132, s46, v201
	v_or_b32_e32 v132, v132, v202
	v_and_or_b32 v133, v140, s68, v138
	v_or3_b32 v132, v132, v203, v204
	v_lshl_or_b32 v141, v133, 6, v139
	v_ashrrev_i32_e32 v133, 31, v132
	v_lshlrev_b64 v[132:133], 10, v[132:133]
	v_lshl_or_b32 v132, v134, 4, v132
	v_add_u32_e32 v134, s46, v207
	v_or3_b32 v134, v134, v208, v209
	v_or3_b32 v134, v134, v210, 4
	v_ashrrev_i32_e32 v135, 31, v134
	v_lshlrev_b64 v[134:135], 10, v[134:135]
	v_lshl_or_b32 v134, v145, 4, v134
	v_or_b32_e32 v143, v142, v139
	v_lshl_add_u64 v[130:131], s[48:49], 0, v[130:131]
	v_lshl_add_u64 v[132:133], s[26:27], 0, v[132:133]
	v_lshl_add_u64 v[134:135], s[26:27], 0, v[134:135]
	s_mov_b64 s[46:47], 0
	v_readfirstlane_b32 s98, v144
	s_waitcnt vmcnt(8)
	s_barrier
	s_cmp_lt_u32 s98, 0x2000
	s_cbranch_scc1 .Lmg2_top
	s_barrier
; #define GEMM_WAITV(n) asm volatile("s_waitcnt vmcnt(" #n ")" ::: "memory")
; template <bool SWAP>
; __device__ __forceinline__ void gemm_main(f32x4 (&acc)[8][4], const TP& t, int nk, char* lds) {
;     ...
; #pragma unroll 1
;   for (int kt = 0; kt < nk - 3; ++kt) {
;     GEMM_WAITV(8);
;     GEMM_STEP(kt, true)
;   }
.Lmg2_top:
	s_add_i32 s55, s54, 0xfffe8000
	s_and_b32 s55, s55, 0x18000
	v_add_u32_e32 v235, s55, v141
	v_add_u32_e32 v236, s55, v143
	ds_read_b128 v[214:217], v235
	ds_read_b128 v[198:201], v236 offset:16384
	ds_read_b128 v[202:205], v236 offset:17408
	ds_read_b128 v[206:209], v236 offset:18432
	ds_read_b128 v[210:213], v236 offset:19456
	ds_read_b128 v[218:221], v235 offset:1024
	ds_read_b128 v[222:225], v235 offset:2048
	ds_read_b128 v[226:229], v235 offset:3072
	s_and_b32 s99, s54, 0x18000
	s_add_i32 s99, s99, s98
	s_mov_b32 m0, s99
	v_lshl_add_u64 v[146:147], v[130:131], 0, s[46:47]
	v_lshl_add_u64 v[238:239], v[146:147], 0, s[42:43]
	global_load_lds_dwordx4 v[238:239], off
	s_add_i32 m0, s99, 0x400
	v_lshl_add_u64 v[238:239], v[146:147], 0, s[44:45]
	global_load_lds_dwordx4 v[238:239], off
	s_waitcnt lgkmcnt(0)
	s_barrier
	s_setprio 1
	v_mfma_f32_16x16x32_bf16 v[0:3], v[198:201], v[214:217], v[0:3]
	v_mfma_f32_16x16x32_bf16 v[4:7], v[202:205], v[214:217], v[4:7]
	v_mfma_f32_16x16x32_bf16 v[16:19], v[206:209], v[214:217], v[16:19]
	v_mfma_f32_16x16x32_bf16 v[12:15], v[210:213], v[214:217], v[12:15]
	v_mfma_f32_16x16x32_bf16 v[20:23], v[198:201], v[218:221], v[20:23]
	v_mfma_f32_16x16x32_bf16 v[28:31], v[202:205], v[218:221], v[28:31]
	v_mfma_f32_16x16x32_bf16 v[48:51], v[206:209], v[218:221], v[48:51]
	v_mfma_f32_16x16x32_bf16 v[40:43], v[210:213], v[218:221], v[40:43]
	v_mfma_f32_16x16x32_bf16 v[52:55], v[198:201], v[222:225], v[52:55]
	v_mfma_f32_16x16x32_bf16 v[56:59], v[202:205], v[222:225], v[56:59]
	v_mfma_f32_16x16x32_bf16 v[72:75], v[206:209], v[222:225], v[72:75]
	v_mfma_f32_16x16x32_bf16 v[68:71], v[210:213], v[222:225], v[68:71]
	v_mfma_f32_16x16x32_bf16 v[76:79], v[198:201], v[226:229], v[76:79]
	v_mfma_f32_16x16x32_bf16 v[80:83], v[202:205], v[226:229], v[80:83]
	v_mfma_f32_16x16x32_bf16 v[100:103], v[206:209], v[226:229], v[100:103]
	v_mfma_f32_16x16x32_bf16 v[96:99], v[210:213], v[226:229], v[96:99]
	s_setprio 0
	s_barrier
	ds_read_b128 v[214:217], v235 offset:4096
	ds_read_b128 v[218:221], v235 offset:5120
	ds_read_b128 v[222:225], v235 offset:6144
	ds_read_b128 v[226:229], v235 offset:7168
	s_add_i32 m0, s99, 0x4000
	v_lshl_add_u64 v[238:239], v[132:133], 0, s[46:47]
	global_load_lds_dwordx4 v[238:239], off
	s_add_i32 m0, s99, 0x4400
	v_lshl_add_u64 v[238:239], v[134:135], 0, s[46:47]
	global_load_lds_dwordx4 v[238:239], off
	s_add_u32 s46, s46, 64
	s_addc_u32 s47, s47, 0
	s_add_i32 s54, s54, 0x8000
	s_waitcnt vmcnt(8)
	s_waitcnt lgkmcnt(0)
	s_barrier
	s_setprio 1
	v_mfma_f32_16x16x32_bf16 v[104:107], v[198:201], v[214:217], v[104:107]
	v_mfma_f32_16x16x32_bf16 v[108:111], v[202:205], v[214:217], v[108:111]
	v_mfma_f32_16x16x32_bf16 v[120:123], v[206:209], v[214:217], v[120:123]
	v_mfma_f32_16x16x32_bf16 v[116:119], v[210:213], v[214:217], v[116:119]
	v_mfma_f32_16x16x32_bf16 v[124:127], v[198:201], v[218:221], v[124:127]
	v_mfma_f32_16x16x32_bf16 v[112:115], v[202:205], v[218:221], v[112:115]
	v_mfma_f32_16x16x32_bf16 v[92:95], v[206:209], v[218:221], v[92:95]
	v_mfma_f32_16x16x32_bf16 v[88:91], v[210:213], v[218:221], v[88:91]
	v_mfma_f32_16x16x32_bf16 v[84:87], v[198:201], v[222:225], v[84:87]
	v_mfma_f32_16x16x32_bf16 v[64:67], v[202:205], v[222:225], v[64:67]
	v_mfma_f32_16x16x32_bf16 v[60:63], v[206:209], v[222:225], v[60:63]
	v_mfma_f32_16x16x32_bf16 v[44:47], v[210:213], v[222:225], v[44:47]
	v_mfma_f32_16x16x32_bf16 v[36:39], v[198:201], v[226:229], v[36:39]
	v_mfma_f32_16x16x32_bf16 v[32:35], v[202:205], v[226:229], v[32:35]
	v_mfma_f32_16x16x32_bf16 v[24:27], v[206:209], v[226:229], v[24:27]
	v_mfma_f32_16x16x32_bf16 v[8:11], v[210:213], v[226:229], v[8:11]
	s_setprio 0
	s_barrier
	s_cmpk_lg_i32 s46, 0x340
	s_cbranch_scc1 .Lmg2_top
	v_add_u32_e32 v235, 0x8000, v141
	v_add_u32_e32 v236, 0x8000, v143
	ds_read_b128 v[214:217], v235
	ds_read_b128 v[198:201], v236 offset:16384
	ds_read_b128 v[202:205], v236 offset:17408
	ds_read_b128 v[206:209], v236 offset:18432
	ds_read_b128 v[210:213], v236 offset:19456
	ds_read_b128 v[218:221], v235 offset:1024
	ds_read_b128 v[222:225], v235 offset:2048
	ds_read_b128 v[226:229], v235 offset:3072
	s_waitcnt lgkmcnt(0)
	s_barrier
	s_setprio 1
	v_mfma_f32_16x16x32_bf16 v[0:3], v[198:201], v[214:217], v[0:3]
	v_mfma_f32_16x16x32_bf16 v[4:7], v[202:205], v[214:217], v[4:7]
	v_mfma_f32_16x16x32_bf16 v[16:19], v[206:209], v[214:217], v[16:19]
	v_mfma_f32_16x16x32_bf16 v[12:15], v[210:213], v[214:217], v[12:15]
	v_mfma_f32_16x16x32_bf16 v[20:23], v[198:201], v[218:221], v[20:23]
	v_mfma_f32_16x16x32_bf16 v[28:31], v[202:205], v[218:221], v[28:31]
	v_mfma_f32_16x16x32_bf16 v[48:51], v[206:209], v[218:221], v[48:51]
	v_mfma_f32_16x16x32_bf16 v[40:43], v[210:213], v[218:221], v[40:43]
	v_mfma_f32_16x16x32_bf16 v[52:55], v[198:201], v[222:225], v[52:55]
	v_mfma_f32_16x16x32_bf16 v[56:59], v[202:205], v[222:225], v[56:59]
	v_mfma_f32_16x16x32_bf16 v[72:75], v[206:209], v[222:225], v[72:75]
	v_mfma_f32_16x16x32_bf16 v[68:71], v[210:213], v[222:225], v[68:71]
	v_mfma_f32_16x16x32_bf16 v[76:79], v[198:201], v[226:229], v[76:79]
	v_mfma_f32_16x16x32_bf16 v[80:83], v[202:205], v[226:229], v[80:83]
	v_mfma_f32_16x16x32_bf16 v[100:103], v[206:209], v[226:229], v[100:103]
	v_mfma_f32_16x16x32_bf16 v[96:99], v[210:213], v[226:229], v[96:99]
	s_setprio 0
	s_barrier
	ds_read_b128 v[214:217], v235 offset:4096
	ds_read_b128 v[218:221], v235 offset:5120
	ds_read_b128 v[222:225], v235 offset:6144
	ds_read_b128 v[226:229], v235 offset:7168
	s_waitcnt vmcnt(4)
	s_waitcnt lgkmcnt(0)
	s_barrier
; #define GEMM_WAITV(n) asm volatile("s_waitcnt vmcnt(" #n ")" ::: "memory")
; template <bool SWAP>
; __device__ __forceinline__ void gemm_main(f32x4 (&acc)[8][4], const TP& t, int nk, char* lds) {
;     ...
; #pragma unroll 1
;   for (int kt = 0; kt < nk - 3; ++kt) {
;     GEMM_WAITV(8);
;     GEMM_STEP(kt, true)
;   }
; #pragma unroll 1
;   for (int kt = nk - 3; kt < nk; ++kt) {
;     const int rem = nk - kt;
;     if (rem == 3) GEMM_WAITV(8); else if (rem == 2) GEMM_WAITV(4); else GEMM_WAITV(0);
;     GEMM_STEP(kt, false)
;   }
;   __builtin_amdgcn_s_barrier();
	s_setprio 1
	v_mfma_f32_16x16x32_bf16 v[104:107], v[198:201], v[214:217], v[104:107]
	v_mfma_f32_16x16x32_bf16 v[108:111], v[202:205], v[214:217], v[108:111]
	v_mfma_f32_16x16x32_bf16 v[120:123], v[206:209], v[214:217], v[120:123]
	v_mfma_f32_16x16x32_bf16 v[116:119], v[210:213], v[214:217], v[116:119]
	v_mfma_f32_16x16x32_bf16 v[124:127], v[198:201], v[218:221], v[124:127]
	v_mfma_f32_16x16x32_bf16 v[112:115], v[202:205], v[218:221], v[112:115]
	v_mfma_f32_16x16x32_bf16 v[92:95], v[206:209], v[218:221], v[92:95]
	v_mfma_f32_16x16x32_bf16 v[88:91], v[210:213], v[218:221], v[88:91]
	v_mfma_f32_16x16x32_bf16 v[84:87], v[198:201], v[222:225], v[84:87]
	v_mfma_f32_16x16x32_bf16 v[64:67], v[202:205], v[222:225], v[64:67]
	v_mfma_f32_16x16x32_bf16 v[60:63], v[206:209], v[222:225], v[60:63]
	v_mfma_f32_16x16x32_bf16 v[44:47], v[210:213], v[222:225], v[44:47]
	v_mfma_f32_16x16x32_bf16 v[36:39], v[198:201], v[226:229], v[36:39]
	v_mfma_f32_16x16x32_bf16 v[32:35], v[202:205], v[226:229], v[32:35]
	v_mfma_f32_16x16x32_bf16 v[24:27], v[206:209], v[226:229], v[24:27]
	v_mfma_f32_16x16x32_bf16 v[8:11], v[210:213], v[226:229], v[8:11]
	s_setprio 0
	s_barrier
	v_add_u32_e32 v235, 0x10000, v141
	v_add_u32_e32 v236, 0x10000, v143
	ds_read_b128 v[214:217], v235
	ds_read_b128 v[198:201], v236 offset:16384
	ds_read_b128 v[202:205], v236 offset:17408
	ds_read_b128 v[206:209], v236 offset:18432
	ds_read_b128 v[210:213], v236 offset:19456
	ds_read_b128 v[218:221], v235 offset:1024
	ds_read_b128 v[222:225], v235 offset:2048
	ds_read_b128 v[226:229], v235 offset:3072
	s_waitcnt lgkmcnt(0)
	s_barrier
	s_setprio 1
	v_mfma_f32_16x16x32_bf16 v[0:3], v[198:201], v[214:217], v[0:3]
	v_mfma_f32_16x16x32_bf16 v[4:7], v[202:205], v[214:217], v[4:7]
	v_mfma_f32_16x16x32_bf16 v[16:19], v[206:209], v[214:217], v[16:19]
	v_mfma_f32_16x16x32_bf16 v[12:15], v[210:213], v[214:217], v[12:15]
	v_mfma_f32_16x16x32_bf16 v[20:23], v[198:201], v[218:221], v[20:23]
	v_mfma_f32_16x16x32_bf16 v[28:31], v[202:205], v[218:221], v[28:31]
	v_mfma_f32_16x16x32_bf16 v[48:51], v[206:209], v[218:221], v[48:51]
	v_mfma_f32_16x16x32_bf16 v[40:43], v[210:213], v[218:221], v[40:43]
	v_mfma_f32_16x16x32_bf16 v[52:55], v[198:201], v[222:225], v[52:55]
	v_mfma_f32_16x16x32_bf16 v[56:59], v[202:205], v[222:225], v[56:59]
	v_mfma_f32_16x16x32_bf16 v[72:75], v[206:209], v[222:225], v[72:75]
	v_mfma_f32_16x16x32_bf16 v[68:71], v[210:213], v[222:225], v[68:71]
	v_mfma_f32_16x16x32_bf16 v[76:79], v[198:201], v[226:229], v[76:79]
	v_mfma_f32_16x16x32_bf16 v[80:83], v[202:205], v[226:229], v[80:83]
	v_mfma_f32_16x16x32_bf16 v[100:103], v[206:209], v[226:229], v[100:103]
	v_mfma_f32_16x16x32_bf16 v[96:99], v[210:213], v[226:229], v[96:99]
	s_setprio 0
	s_barrier
	ds_read_b128 v[214:217], v235 offset:4096
	ds_read_b128 v[218:221], v235 offset:5120
	ds_read_b128 v[222:225], v235 offset:6144
	ds_read_b128 v[226:229], v235 offset:7168
	s_waitcnt vmcnt(0)
	s_waitcnt lgkmcnt(0)
	s_barrier
	s_setprio 1
	v_mfma_f32_16x16x32_bf16 v[104:107], v[198:201], v[214:217], v[104:107]
	v_mfma_f32_16x16x32_bf16 v[108:111], v[202:205], v[214:217], v[108:111]
	v_mfma_f32_16x16x32_bf16 v[120:123], v[206:209], v[214:217], v[120:123]
	v_mfma_f32_16x16x32_bf16 v[116:119], v[210:213], v[214:217], v[116:119]
	v_mfma_f32_16x16x32_bf16 v[124:127], v[198:201], v[218:221], v[124:127]
	v_mfma_f32_16x16x32_bf16 v[112:115], v[202:205], v[218:221], v[112:115]
	v_mfma_f32_16x16x32_bf16 v[92:95], v[206:209], v[218:221], v[92:95]
	v_mfma_f32_16x16x32_bf16 v[88:91], v[210:213], v[218:221], v[88:91]
	v_mfma_f32_16x16x32_bf16 v[84:87], v[198:201], v[222:225], v[84:87]
	v_mfma_f32_16x16x32_bf16 v[64:67], v[202:205], v[222:225], v[64:67]
	v_mfma_f32_16x16x32_bf16 v[60:63], v[206:209], v[222:225], v[60:63]
	v_mfma_f32_16x16x32_bf16 v[44:47], v[210:213], v[222:225], v[44:47]
	v_mfma_f32_16x16x32_bf16 v[36:39], v[198:201], v[226:229], v[36:39]
	v_mfma_f32_16x16x32_bf16 v[32:35], v[202:205], v[226:229], v[32:35]
	v_mfma_f32_16x16x32_bf16 v[24:27], v[206:209], v[226:229], v[24:27]
	v_mfma_f32_16x16x32_bf16 v[8:11], v[210:213], v[226:229], v[8:11]
	s_setprio 0
	s_barrier
; #define GEMM_WAITV(n) asm volatile("s_waitcnt vmcnt(" #n ")" ::: "memory")
; template <bool SWAP>
; __device__ __forceinline__ void gemm_main(f32x4 (&acc)[8][4], const TP& t, int nk, char* lds) {
;     ...
; #pragma unroll 1
;   for (int kt = nk - 3; kt < nk; ++kt) {
;     const int rem = nk - kt;
;     if (rem == 3) GEMM_WAITV(8); else if (rem == 2) GEMM_WAITV(4); else GEMM_WAITV(0);
;     GEMM_STEP(kt, false)
;   }
;   __builtin_amdgcn_s_barrier();
	v_add_u32_e32 v235, 0x18000, v141
	v_add_u32_e32 v236, 0x18000, v143
	ds_read_b128 v[214:217], v235
	ds_read_b128 v[198:201], v236 offset:16384
	ds_read_b128 v[202:205], v236 offset:17408
	ds_read_b128 v[206:209], v236 offset:18432
	ds_read_b128 v[210:213], v236 offset:19456
	ds_read_b128 v[218:221], v235 offset:1024
	ds_read_b128 v[222:225], v235 offset:2048
	ds_read_b128 v[226:229], v235 offset:3072
	s_waitcnt lgkmcnt(0)
	s_barrier
	s_setprio 1
	v_mfma_f32_16x16x32_bf16 v[0:3], v[198:201], v[214:217], v[0:3]
	v_mfma_f32_16x16x32_bf16 v[4:7], v[202:205], v[214:217], v[4:7]
	v_mfma_f32_16x16x32_bf16 v[16:19], v[206:209], v[214:217], v[16:19]
	v_mfma_f32_16x16x32_bf16 v[12:15], v[210:213], v[214:217], v[12:15]
	v_mfma_f32_16x16x32_bf16 v[20:23], v[198:201], v[218:221], v[20:23]
	v_mfma_f32_16x16x32_bf16 v[28:31], v[202:205], v[218:221], v[28:31]
	v_mfma_f32_16x16x32_bf16 v[48:51], v[206:209], v[218:221], v[48:51]
	v_mfma_f32_16x16x32_bf16 v[40:43], v[210:213], v[218:221], v[40:43]
	v_mfma_f32_16x16x32_bf16 v[52:55], v[198:201], v[222:225], v[52:55]
	v_mfma_f32_16x16x32_bf16 v[56:59], v[202:205], v[222:225], v[56:59]
	v_mfma_f32_16x16x32_bf16 v[72:75], v[206:209], v[222:225], v[72:75]
	v_mfma_f32_16x16x32_bf16 v[68:71], v[210:213], v[222:225], v[68:71]
	v_mfma_f32_16x16x32_bf16 v[76:79], v[198:201], v[226:229], v[76:79]
	v_mfma_f32_16x16x32_bf16 v[80:83], v[202:205], v[226:229], v[80:83]
	v_mfma_f32_16x16x32_bf16 v[100:103], v[206:209], v[226:229], v[100:103]
	v_mfma_f32_16x16x32_bf16 v[96:99], v[210:213], v[226:229], v[96:99]
	s_setprio 0
	s_barrier
	ds_read_b128 v[214:217], v235 offset:4096
	ds_read_b128 v[218:221], v235 offset:5120
	ds_read_b128 v[222:225], v235 offset:6144
	ds_read_b128 v[226:229], v235 offset:7168
	s_waitcnt lgkmcnt(0)
	s_barrier
	s_setprio 1
	v_mfma_f32_16x16x32_bf16 v[104:107], v[198:201], v[214:217], v[104:107]
	v_mfma_f32_16x16x32_bf16 v[108:111], v[202:205], v[214:217], v[108:111]
	v_mfma_f32_16x16x32_bf16 v[120:123], v[206:209], v[214:217], v[120:123]
	v_mfma_f32_16x16x32_bf16 v[116:119], v[210:213], v[214:217], v[116:119]
	v_mfma_f32_16x16x32_bf16 v[124:127], v[198:201], v[218:221], v[124:127]
	v_mfma_f32_16x16x32_bf16 v[112:115], v[202:205], v[218:221], v[112:115]
	v_mfma_f32_16x16x32_bf16 v[92:95], v[206:209], v[218:221], v[92:95]
	v_mfma_f32_16x16x32_bf16 v[88:91], v[210:213], v[218:221], v[88:91]
	v_mfma_f32_16x16x32_bf16 v[84:87], v[198:201], v[222:225], v[84:87]
	v_mfma_f32_16x16x32_bf16 v[64:67], v[202:205], v[222:225], v[64:67]
	v_mfma_f32_16x16x32_bf16 v[60:63], v[206:209], v[222:225], v[60:63]
	v_mfma_f32_16x16x32_bf16 v[44:47], v[210:213], v[222:225], v[44:47]
	v_mfma_f32_16x16x32_bf16 v[36:39], v[198:201], v[226:229], v[36:39]
	v_mfma_f32_16x16x32_bf16 v[32:35], v[202:205], v[226:229], v[32:35]
	v_mfma_f32_16x16x32_bf16 v[24:27], v[206:209], v[226:229], v[24:27]
	v_mfma_f32_16x16x32_bf16 v[8:11], v[210:213], v[226:229], v[8:11]
	s_setprio 0
	s_barrier
	s_cmp_ge_u32 s98, 0x2000
	s_cbranch_scc1 .Lmg2_done
	s_barrier

; #define GEMM_WAITV(n) asm volatile("s_waitcnt vmcnt(" #n ")" ::: "memory")
; template <bool SWAP>
; __device__ __forceinline__ void gemm_main(f32x4 (&acc)[8][4], const TP& t, int nk, char* lds) {
;     ...
; #pragma unroll 1
;   for (int kt = 0; kt < nk - 3; ++kt) {
;     GEMM_WAITV(8);
;     GEMM_STEP(kt, true)
; template <class MK, class SW, class EPI>
; __device__ __forceinline__ void gemm_phase(int first, int step, int n, int nk, MK mk, SW swapf, EPI epi, char* lds) {
;     ...
;   for (int it = first; it < n; it += step) {
;     const bool has_next = (it + step < n);
;     const TP nxt = mk(has_next ? it + step : it);
;     f32x4 acc[8][4];
;     zero_acc(acc);
;     if (swapf(it)) gemm_main<true>(acc, cur, nk, lds); else gemm_main<false>(acc, cur, nk, lds);
; __device__ __forceinline__ void zero_acc(f32x4 (&acc)[8][4]) {
; #pragma unroll
;   for (int i = 0; i < 8; ++i)
; #pragma unroll
;     for (int j = 0; j < 4; ++j) acc[i][j] = (f32x4){0.f, 0.f, 0.f, 0.f};
.LBB0_938:
	v_mov_b32_e32 v139, v153
	v_mov_b32_e32 v134, v153
	v_mov_b32_e32 v138, v153
	v_mov_b32_e32 v135, v153
	v_mov_b32_e32 v137, v153
	v_mov_b32_e32 v136, v153
	v_mov_b32_e32 v0, v153
	s_mov_b32 s56, s38
	v_lshlrev_b32_e32 v3, 2, v0
	v_and_b32_e32 v3, 48, v3
	v_sub_u32_e32 v3, 0, v3
	v_and_b32_e32 v140, 15, v0
	v_lshlrev_b32_e32 v1, 5, v0
	v_lshlrev_b32_e32 v2, 4, v0
	v_bitop3_b32 v141, v0, 48, v3 bitop3:0x48
	v_ashrrev_i32_e32 v142, 1, v0
	v_lshlrev_b32_e32 v0, 6, v0
	v_and_b32_e32 v1, 0xfffff800, v1
	v_and_b32_e32 v2, 0x3f0, v2
	v_and_or_b32 v3, v142, s54, v140
	v_and_b32_e32 v143, 0x33c0, v0
	v_mov_b32_e32 v0, 0
	v_lshl_or_b32 v144, v3, 6, v141
	v_or_b32_e32 v149, v143, v141
	v_add3_u32 v151, 0, v1, v2
	v_lshl_add_u64 v[128:129], v[146:147], 0, s[26:27]
	v_lshl_add_u64 v[130:131], v[156:157], 0, s[28:29]
	v_lshl_add_u64 v[132:133], v[158:159], 0, s[28:29]
	s_mov_b32 s36, 0x18000
	v_mov_b32_e32 v1, v0
	v_mov_b32_e32 v2, v0
	v_mov_b32_e32 v3, v0
	v_mov_b32_e32 v4, v0
	v_mov_b32_e32 v5, v0
	v_mov_b32_e32 v6, v0
	v_mov_b32_e32 v7, v0
	v_mov_b32_e32 v8, v0
	v_mov_b32_e32 v9, v0
	v_mov_b32_e32 v10, v0
	v_mov_b32_e32 v11, v0
	v_mov_b32_e32 v12, v0
	v_mov_b32_e32 v13, v0
	v_mov_b32_e32 v14, v0
	v_mov_b32_e32 v15, v0
	v_mov_b32_e32 v16, v0
	v_mov_b32_e32 v17, v0
	v_mov_b32_e32 v18, v0
	v_mov_b32_e32 v19, v0
	v_mov_b32_e32 v20, v0
	v_mov_b32_e32 v21, v0
	v_mov_b32_e32 v22, v0
	v_mov_b32_e32 v23, v0
	v_mov_b32_e32 v24, v0
	v_mov_b32_e32 v25, v0
	v_mov_b32_e32 v26, v0
	v_mov_b32_e32 v27, v0
	v_mov_b32_e32 v28, v0
	v_mov_b32_e32 v29, v0
	v_mov_b32_e32 v30, v0
	v_mov_b32_e32 v31, v0
	v_mov_b32_e32 v32, v0
	v_mov_b32_e32 v33, v0
	v_mov_b32_e32 v34, v0
	v_mov_b32_e32 v35, v0
	v_mov_b32_e32 v36, v0
	v_mov_b32_e32 v37, v0
	v_mov_b32_e32 v38, v0
	v_mov_b32_e32 v39, v0
	v_mov_b32_e32 v40, v0
	v_mov_b32_e32 v41, v0
	v_mov_b32_e32 v42, v0
	v_mov_b32_e32 v43, v0
	v_mov_b32_e32 v44, v0
	v_mov_b32_e32 v45, v0
	v_mov_b32_e32 v46, v0
	v_mov_b32_e32 v47, v0
	v_mov_b32_e32 v48, v0
	v_mov_b32_e32 v49, v0
	v_mov_b32_e32 v50, v0
	v_mov_b32_e32 v51, v0
	v_mov_b32_e32 v52, v0
	v_mov_b32_e32 v53, v0
	v_mov_b32_e32 v54, v0
	v_mov_b32_e32 v55, v0
	v_mov_b32_e32 v56, v0
	v_mov_b32_e32 v57, v0
	v_mov_b32_e32 v58, v0
	v_mov_b32_e32 v59, v0
	v_mov_b32_e32 v60, v0
	v_mov_b32_e32 v61, v0
	v_mov_b32_e32 v62, v0
	v_mov_b32_e32 v63, v0
	v_mov_b32_e32 v64, v0
	v_mov_b32_e32 v65, v0
	v_mov_b32_e32 v66, v0
	v_mov_b32_e32 v67, v0
	v_mov_b32_e32 v68, v0
	v_mov_b32_e32 v69, v0
	v_mov_b32_e32 v70, v0
	v_mov_b32_e32 v71, v0
	v_mov_b32_e32 v72, v0
	v_mov_b32_e32 v73, v0
	v_mov_b32_e32 v74, v0
	v_mov_b32_e32 v75, v0
	v_mov_b32_e32 v76, v0
	v_mov_b32_e32 v77, v0
	v_mov_b32_e32 v78, v0
	v_mov_b32_e32 v79, v0
	v_mov_b32_e32 v80, v0
	v_mov_b32_e32 v81, v0
	v_mov_b32_e32 v82, v0
	v_mov_b32_e32 v83, v0
	v_mov_b32_e32 v84, v0
	v_mov_b32_e32 v85, v0
	v_mov_b32_e32 v86, v0
	v_mov_b32_e32 v87, v0
	v_mov_b32_e32 v88, v0
	v_mov_b32_e32 v89, v0
	v_mov_b32_e32 v90, v0
	v_mov_b32_e32 v91, v0
	v_mov_b32_e32 v92, v0
	v_mov_b32_e32 v93, v0
	v_mov_b32_e32 v94, v0
	v_mov_b32_e32 v95, v0
	v_mov_b32_e32 v96, v0
	v_mov_b32_e32 v97, v0
	v_mov_b32_e32 v98, v0
	v_mov_b32_e32 v99, v0
	v_mov_b32_e32 v100, v0
	v_mov_b32_e32 v101, v0
	v_mov_b32_e32 v102, v0
	v_mov_b32_e32 v103, v0
	v_mov_b32_e32 v104, v0
	v_mov_b32_e32 v105, v0
	v_mov_b32_e32 v106, v0
	v_mov_b32_e32 v107, v0
	v_mov_b32_e32 v108, v0
	v_mov_b32_e32 v109, v0
	v_mov_b32_e32 v110, v0
	v_mov_b32_e32 v111, v0
	v_mov_b32_e32 v112, v0
	v_mov_b32_e32 v113, v0
	v_mov_b32_e32 v114, v0
	v_mov_b32_e32 v115, v0
	v_mov_b32_e32 v116, v0
	v_mov_b32_e32 v117, v0
	v_mov_b32_e32 v118, v0
	v_mov_b32_e32 v119, v0
	v_mov_b32_e32 v120, v0
	v_mov_b32_e32 v121, v0
	v_mov_b32_e32 v122, v0
	v_mov_b32_e32 v123, v0
	v_mov_b32_e32 v124, v0
	v_mov_b32_e32 v125, v0
	v_mov_b32_e32 v126, v0
	v_mov_b32_e32 v127, v0
	v_readfirstlane_b32 s98, v151
	s_waitcnt vmcnt(8)
	s_barrier
	s_cmp_lt_u32 s98, 0x2000
	s_cbranch_scc1 .Lg3_top
	s_barrier
.Lg3_top:
	s_add_i32 s37, s36, 0xfffe8000
	s_and_b32 s37, s37, 0x18000
	v_add_u32_e32 v235, s37, v144
	v_add_u32_e32 v236, s37, v149
	ds_read_b128 v[174:177], v235
	ds_read_b128 v[156:159], v236 offset:16384
	ds_read_b128 v[160:163], v236 offset:17408
	ds_read_b128 v[164:167], v236 offset:18432
	ds_read_b128 v[170:173], v236 offset:19456
	ds_read_b128 v[178:181], v235 offset:1024
	ds_read_b128 v[182:185], v235 offset:2048
	ds_read_b128 v[186:189], v235 offset:3072
	s_and_b32 s99, s36, 0x18000
	s_add_i32 s99, s99, s98
	s_mov_b32 m0, s99
	v_lshl_add_u64 v[238:239], v[128:129], 0, s[30:31]
	global_load_lds_dwordx4 v[238:239], off
	s_add_i32 m0, s99, 0x400
	s_nop 0
	global_load_lds_dwordx4 v[128:129], off
	s_waitcnt lgkmcnt(0)
	s_barrier
	s_setprio 1
	v_mfma_f32_16x16x32_bf16 v[124:127], v[156:159], v[174:177], v[124:127]
	v_mfma_f32_16x16x32_bf16 v[120:123], v[160:163], v[174:177], v[120:123]
	v_mfma_f32_16x16x32_bf16 v[116:119], v[164:167], v[174:177], v[116:119]
	v_mfma_f32_16x16x32_bf16 v[112:115], v[170:173], v[174:177], v[112:115]
	v_mfma_f32_16x16x32_bf16 v[108:111], v[156:159], v[178:181], v[108:111]
	v_mfma_f32_16x16x32_bf16 v[104:107], v[160:163], v[178:181], v[104:107]
	v_mfma_f32_16x16x32_bf16 v[100:103], v[164:167], v[178:181], v[100:103]
	v_mfma_f32_16x16x32_bf16 v[96:99], v[170:173], v[178:181], v[96:99]
	v_mfma_f32_16x16x32_bf16 v[92:95], v[156:159], v[182:185], v[92:95]
	v_mfma_f32_16x16x32_bf16 v[88:91], v[160:163], v[182:185], v[88:91]
	v_mfma_f32_16x16x32_bf16 v[84:87], v[164:167], v[182:185], v[84:87]
	v_mfma_f32_16x16x32_bf16 v[80:83], v[170:173], v[182:185], v[80:83]
	v_mfma_f32_16x16x32_bf16 v[76:79], v[156:159], v[186:189], v[76:79]
	v_mfma_f32_16x16x32_bf16 v[72:75], v[160:163], v[186:189], v[72:75]
	v_mfma_f32_16x16x32_bf16 v[68:71], v[164:167], v[186:189], v[68:71]
	v_mfma_f32_16x16x32_bf16 v[64:67], v[170:173], v[186:189], v[64:67]
	s_setprio 0
	s_barrier
; #define GEMM_WAITV(n) asm volatile("s_waitcnt vmcnt(" #n ")" ::: "memory")
; template <bool SWAP>
; __device__ __forceinline__ void gemm_main(f32x4 (&acc)[8][4], const TP& t, int nk, char* lds) {
;     ...
; #pragma unroll 1
;   for (int kt = 0; kt < nk - 3; ++kt) {
;     GEMM_WAITV(8);
;     GEMM_STEP(kt, true)
;   }
; #pragma unroll 1
;   for (int kt = nk - 3; kt < nk; ++kt) {
;     const int rem = nk - kt;
;     if (rem == 3) GEMM_WAITV(8); else if (rem == 2) GEMM_WAITV(4); else GEMM_WAITV(0);
;     GEMM_STEP(kt, false)
;   }
;   __builtin_amdgcn_s_barrier();
	ds_read_b128 v[174:177], v235 offset:4096
	ds_read_b128 v[178:181], v235 offset:5120
	ds_read_b128 v[182:185], v235 offset:6144
	ds_read_b128 v[186:189], v235 offset:7168
	s_add_i32 m0, s99, 0x4000
	s_nop 0
	global_load_lds_dwordx4 v[130:131], off
	s_add_i32 m0, s99, 0x4400
	s_nop 0
	global_load_lds_dwordx4 v[132:133], off
	v_lshl_add_u64 v[128:129], v[128:129], 0, 64
	v_lshl_add_u64 v[130:131], v[130:131], 0, 64
	v_lshl_add_u64 v[132:133], v[132:133], 0, 64
	s_add_i32 s36, s36, 0x8000
	s_waitcnt vmcnt(8)
	s_waitcnt lgkmcnt(0)
	s_barrier
	s_setprio 1
	v_mfma_f32_16x16x32_bf16 v[60:63], v[156:159], v[174:177], v[60:63]
	v_mfma_f32_16x16x32_bf16 v[56:59], v[160:163], v[174:177], v[56:59]
	v_mfma_f32_16x16x32_bf16 v[52:55], v[164:167], v[174:177], v[52:55]
	v_mfma_f32_16x16x32_bf16 v[48:51], v[170:173], v[174:177], v[48:51]
	v_mfma_f32_16x16x32_bf16 v[44:47], v[156:159], v[178:181], v[44:47]
	v_mfma_f32_16x16x32_bf16 v[40:43], v[160:163], v[178:181], v[40:43]
	v_mfma_f32_16x16x32_bf16 v[36:39], v[164:167], v[178:181], v[36:39]
	v_mfma_f32_16x16x32_bf16 v[32:35], v[170:173], v[178:181], v[32:35]
	v_mfma_f32_16x16x32_bf16 v[28:31], v[156:159], v[182:185], v[28:31]
	v_mfma_f32_16x16x32_bf16 v[24:27], v[160:163], v[182:185], v[24:27]
	v_mfma_f32_16x16x32_bf16 v[20:23], v[164:167], v[182:185], v[20:23]
	v_mfma_f32_16x16x32_bf16 v[16:19], v[170:173], v[182:185], v[16:19]
	v_mfma_f32_16x16x32_bf16 v[12:15], v[156:159], v[186:189], v[12:15]
	v_mfma_f32_16x16x32_bf16 v[8:11], v[160:163], v[186:189], v[8:11]
	v_mfma_f32_16x16x32_bf16 v[4:7], v[164:167], v[186:189], v[4:7]
	v_mfma_f32_16x16x32_bf16 v[0:3], v[170:173], v[186:189], v[0:3]
	s_setprio 0
	s_barrier
	s_cmp_lg_u32 s36, 0x100000
	s_cbranch_scc1 .Lg3_top
	v_add_u32_e32 v235, 0x8000, v144
	v_add_u32_e32 v236, 0x8000, v149
	ds_read_b128 v[174:177], v235
	ds_read_b128 v[156:159], v236 offset:16384
	ds_read_b128 v[160:163], v236 offset:17408
	ds_read_b128 v[164:167], v236 offset:18432
	ds_read_b128 v[170:173], v236 offset:19456
	ds_read_b128 v[178:181], v235 offset:1024
	ds_read_b128 v[182:185], v235 offset:2048
	ds_read_b128 v[186:189], v235 offset:3072
	s_waitcnt lgkmcnt(0)
	s_barrier
	s_setprio 1
	v_mfma_f32_16x16x32_bf16 v[124:127], v[156:159], v[174:177], v[124:127]
	v_mfma_f32_16x16x32_bf16 v[120:123], v[160:163], v[174:177], v[120:123]
	v_mfma_f32_16x16x32_bf16 v[116:119], v[164:167], v[174:177], v[116:119]
	v_mfma_f32_16x16x32_bf16 v[112:115], v[170:173], v[174:177], v[112:115]
	v_mfma_f32_16x16x32_bf16 v[108:111], v[156:159], v[178:181], v[108:111]
	v_mfma_f32_16x16x32_bf16 v[104:107], v[160:163], v[178:181], v[104:107]
	v_mfma_f32_16x16x32_bf16 v[100:103], v[164:167], v[178:181], v[100:103]
	v_mfma_f32_16x16x32_bf16 v[96:99], v[170:173], v[178:181], v[96:99]
	v_mfma_f32_16x16x32_bf16 v[92:95], v[156:159], v[182:185], v[92:95]
	v_mfma_f32_16x16x32_bf16 v[88:91], v[160:163], v[182:185], v[88:91]
	v_mfma_f32_16x16x32_bf16 v[84:87], v[164:167], v[182:185], v[84:87]
	v_mfma_f32_16x16x32_bf16 v[80:83], v[170:173], v[182:185], v[80:83]
	v_mfma_f32_16x16x32_bf16 v[76:79], v[156:159], v[186:189], v[76:79]
	v_mfma_f32_16x16x32_bf16 v[72:75], v[160:163], v[186:189], v[72:75]
	v_mfma_f32_16x16x32_bf16 v[68:71], v[164:167], v[186:189], v[68:71]
	v_mfma_f32_16x16x32_bf16 v[64:67], v[170:173], v[186:189], v[64:67]
	s_setprio 0
	s_barrier
	ds_read_b128 v[174:177], v235 offset:4096
	ds_read_b128 v[178:181], v235 offset:5120
	ds_read_b128 v[182:185], v235 offset:6144
	ds_read_b128 v[186:189], v235 offset:7168
	s_waitcnt vmcnt(4)
	s_waitcnt lgkmcnt(0)
	s_barrier
	s_setprio 1
	v_mfma_f32_16x16x32_bf16 v[60:63], v[156:159], v[174:177], v[60:63]
	v_mfma_f32_16x16x32_bf16 v[56:59], v[160:163], v[174:177], v[56:59]
	v_mfma_f32_16x16x32_bf16 v[52:55], v[164:167], v[174:177], v[52:55]
	v_mfma_f32_16x16x32_bf16 v[48:51], v[170:173], v[174:177], v[48:51]
	v_mfma_f32_16x16x32_bf16 v[44:47], v[156:159], v[178:181], v[44:47]
	v_mfma_f32_16x16x32_bf16 v[40:43], v[160:163], v[178:181], v[40:43]
	v_mfma_f32_16x16x32_bf16 v[36:39], v[164:167], v[178:181], v[36:39]
	v_mfma_f32_16x16x32_bf16 v[32:35], v[170:173], v[178:181], v[32:35]
	v_mfma_f32_16x16x32_bf16 v[28:31], v[156:159], v[182:185], v[28:31]
	v_mfma_f32_16x16x32_bf16 v[24:27], v[160:163], v[182:185], v[24:27]
	v_mfma_f32_16x16x32_bf16 v[20:23], v[164:167], v[182:185], v[20:23]
	v_mfma_f32_16x16x32_bf16 v[16:19], v[170:173], v[182:185], v[16:19]
	v_mfma_f32_16x16x32_bf16 v[12:15], v[156:159], v[186:189], v[12:15]
	v_mfma_f32_16x16x32_bf16 v[8:11], v[160:163], v[186:189], v[8:11]
	v_mfma_f32_16x16x32_bf16 v[4:7], v[164:167], v[186:189], v[4:7]
	v_mfma_f32_16x16x32_bf16 v[0:3], v[170:173], v[186:189], v[0:3]
	s_setprio 0
	s_barrier
	v_add_u32_e32 v235, 0x10000, v144
	v_add_u32_e32 v236, 0x10000, v149
	ds_read_b128 v[174:177], v235
	ds_read_b128 v[156:159], v236 offset:16384
	ds_read_b128 v[160:163], v236 offset:17408
	ds_read_b128 v[164:167], v236 offset:18432
	ds_read_b128 v[170:173], v236 offset:19456
	ds_read_b128 v[178:181], v235 offset:1024
	ds_read_b128 v[182:185], v235 offset:2048
	ds_read_b128 v[186:189], v235 offset:3072
	s_waitcnt lgkmcnt(0)
	s_barrier
; #define GEMM_WAITV(n) asm volatile("s_waitcnt vmcnt(" #n ")" ::: "memory")
; template <bool SWAP>
; __device__ __forceinline__ void gemm_main(f32x4 (&acc)[8][4], const TP& t, int nk, char* lds) {
;     ...
; #pragma unroll 1
;   for (int kt = nk - 3; kt < nk; ++kt) {
;     const int rem = nk - kt;
;     if (rem == 3) GEMM_WAITV(8); else if (rem == 2) GEMM_WAITV(4); else GEMM_WAITV(0);
;     GEMM_STEP(kt, false)
;   }
;   __builtin_amdgcn_s_barrier();
	s_setprio 1
	v_mfma_f32_16x16x32_bf16 v[124:127], v[156:159], v[174:177], v[124:127]
	v_mfma_f32_16x16x32_bf16 v[120:123], v[160:163], v[174:177], v[120:123]
	v_mfma_f32_16x16x32_bf16 v[116:119], v[164:167], v[174:177], v[116:119]
	v_mfma_f32_16x16x32_bf16 v[112:115], v[170:173], v[174:177], v[112:115]
	v_mfma_f32_16x16x32_bf16 v[108:111], v[156:159], v[178:181], v[108:111]
	v_mfma_f32_16x16x32_bf16 v[104:107], v[160:163], v[178:181], v[104:107]
	v_mfma_f32_16x16x32_bf16 v[100:103], v[164:167], v[178:181], v[100:103]
	v_mfma_f32_16x16x32_bf16 v[96:99], v[170:173], v[178:181], v[96:99]
	v_mfma_f32_16x16x32_bf16 v[92:95], v[156:159], v[182:185], v[92:95]
	v_mfma_f32_16x16x32_bf16 v[88:91], v[160:163], v[182:185], v[88:91]
	v_mfma_f32_16x16x32_bf16 v[84:87], v[164:167], v[182:185], v[84:87]
	v_mfma_f32_16x16x32_bf16 v[80:83], v[170:173], v[182:185], v[80:83]
	v_mfma_f32_16x16x32_bf16 v[76:79], v[156:159], v[186:189], v[76:79]
	v_mfma_f32_16x16x32_bf16 v[72:75], v[160:163], v[186:189], v[72:75]
	v_mfma_f32_16x16x32_bf16 v[68:71], v[164:167], v[186:189], v[68:71]
	v_mfma_f32_16x16x32_bf16 v[64:67], v[170:173], v[186:189], v[64:67]
	s_setprio 0
	s_barrier
	ds_read_b128 v[174:177], v235 offset:4096
	ds_read_b128 v[178:181], v235 offset:5120
	ds_read_b128 v[182:185], v235 offset:6144
	ds_read_b128 v[186:189], v235 offset:7168
	s_waitcnt vmcnt(0)
	s_waitcnt lgkmcnt(0)
	s_barrier
	s_setprio 1
	v_mfma_f32_16x16x32_bf16 v[60:63], v[156:159], v[174:177], v[60:63]
	v_mfma_f32_16x16x32_bf16 v[56:59], v[160:163], v[174:177], v[56:59]
	v_mfma_f32_16x16x32_bf16 v[52:55], v[164:167], v[174:177], v[52:55]
	v_mfma_f32_16x16x32_bf16 v[48:51], v[170:173], v[174:177], v[48:51]
	v_mfma_f32_16x16x32_bf16 v[44:47], v[156:159], v[178:181], v[44:47]
	v_mfma_f32_16x16x32_bf16 v[40:43], v[160:163], v[178:181], v[40:43]
	v_mfma_f32_16x16x32_bf16 v[36:39], v[164:167], v[178:181], v[36:39]
	v_mfma_f32_16x16x32_bf16 v[32:35], v[170:173], v[178:181], v[32:35]
	v_mfma_f32_16x16x32_bf16 v[28:31], v[156:159], v[182:185], v[28:31]
	v_mfma_f32_16x16x32_bf16 v[24:27], v[160:163], v[182:185], v[24:27]
	v_mfma_f32_16x16x32_bf16 v[20:23], v[164:167], v[182:185], v[20:23]
	v_mfma_f32_16x16x32_bf16 v[16:19], v[170:173], v[182:185], v[16:19]
	v_mfma_f32_16x16x32_bf16 v[12:15], v[156:159], v[186:189], v[12:15]
	v_mfma_f32_16x16x32_bf16 v[8:11], v[160:163], v[186:189], v[8:11]
	v_mfma_f32_16x16x32_bf16 v[4:7], v[164:167], v[186:189], v[4:7]
	v_mfma_f32_16x16x32_bf16 v[0:3], v[170:173], v[186:189], v[0:3]
	s_setprio 0
	s_barrier
	v_add_u32_e32 v235, 0x18000, v144
	v_add_u32_e32 v236, 0x18000, v149
	ds_read_b128 v[174:177], v235
	ds_read_b128 v[156:159], v236 offset:16384
	ds_read_b128 v[160:163], v236 offset:17408
	ds_read_b128 v[164:167], v236 offset:18432
	ds_read_b128 v[170:173], v236 offset:19456
	ds_read_b128 v[178:181], v235 offset:1024
	ds_read_b128 v[182:185], v235 offset:2048
	ds_read_b128 v[186:189], v235 offset:3072
	s_waitcnt lgkmcnt(0)
	s_barrier
	s_setprio 1
	v_mfma_f32_16x16x32_bf16 v[124:127], v[156:159], v[174:177], v[124:127]
	v_mfma_f32_16x16x32_bf16 v[120:123], v[160:163], v[174:177], v[120:123]
	v_mfma_f32_16x16x32_bf16 v[116:119], v[164:167], v[174:177], v[116:119]
	v_mfma_f32_16x16x32_bf16 v[112:115], v[170:173], v[174:177], v[112:115]
	v_mfma_f32_16x16x32_bf16 v[108:111], v[156:159], v[178:181], v[108:111]
	v_mfma_f32_16x16x32_bf16 v[104:107], v[160:163], v[178:181], v[104:107]
	v_mfma_f32_16x16x32_bf16 v[100:103], v[164:167], v[178:181], v[100:103]
	v_mfma_f32_16x16x32_bf16 v[96:99], v[170:173], v[178:181], v[96:99]
	v_mfma_f32_16x16x32_bf16 v[92:95], v[156:159], v[182:185], v[92:95]
	v_mfma_f32_16x16x32_bf16 v[88:91], v[160:163], v[182:185], v[88:91]
	v_mfma_f32_16x16x32_bf16 v[84:87], v[164:167], v[182:185], v[84:87]
	v_mfma_f32_16x16x32_bf16 v[80:83], v[170:173], v[182:185], v[80:83]
	v_mfma_f32_16x16x32_bf16 v[76:79], v[156:159], v[186:189], v[76:79]
	v_mfma_f32_16x16x32_bf16 v[72:75], v[160:163], v[186:189], v[72:75]
	v_mfma_f32_16x16x32_bf16 v[68:71], v[164:167], v[186:189], v[68:71]
	v_mfma_f32_16x16x32_bf16 v[64:67], v[170:173], v[186:189], v[64:67]
	s_setprio 0
	s_barrier
	ds_read_b128 v[174:177], v235 offset:4096
	ds_read_b128 v[178:181], v235 offset:5120
	ds_read_b128 v[182:185], v235 offset:6144
	ds_read_b128 v[186:189], v235 offset:7168
	s_waitcnt lgkmcnt(0)
	s_barrier
	s_setprio 1
	v_mfma_f32_16x16x32_bf16 v[60:63], v[156:159], v[174:177], v[60:63]
	v_mfma_f32_16x16x32_bf16 v[56:59], v[160:163], v[174:177], v[56:59]
	v_mfma_f32_16x16x32_bf16 v[52:55], v[164:167], v[174:177], v[52:55]
	v_mfma_f32_16x16x32_bf16 v[48:51], v[170:173], v[174:177], v[48:51]
	v_mfma_f32_16x16x32_bf16 v[44:47], v[156:159], v[178:181], v[44:47]
	v_mfma_f32_16x16x32_bf16 v[40:43], v[160:163], v[178:181], v[40:43]
	v_mfma_f32_16x16x32_bf16 v[36:39], v[164:167], v[178:181], v[36:39]
	v_mfma_f32_16x16x32_bf16 v[32:35], v[170:173], v[178:181], v[32:35]
	v_mfma_f32_16x16x32_bf16 v[28:31], v[156:159], v[182:185], v[28:31]
	v_mfma_f32_16x16x32_bf16 v[24:27], v[160:163], v[182:185], v[24:27]
	v_mfma_f32_16x16x32_bf16 v[20:23], v[164:167], v[182:185], v[20:23]
	v_mfma_f32_16x16x32_bf16 v[16:19], v[170:173], v[182:185], v[16:19]
	v_mfma_f32_16x16x32_bf16 v[12:15], v[156:159], v[186:189], v[12:15]
	v_mfma_f32_16x16x32_bf16 v[8:11], v[160:163], v[186:189], v[8:11]
	v_mfma_f32_16x16x32_bf16 v[4:7], v[164:167], v[186:189], v[4:7]
	v_mfma_f32_16x16x32_bf16 v[0:3], v[170:173], v[186:189], v[0:3]
	s_setprio 0
	s_barrier
	s_cmp_ge_u32 s98, 0x2000
	s_cbranch_scc1 .Lg3_done
	s_barrier

; __device__ __forceinline__ int trow(int j) { const int t = otid(); return ((t >> 6) * 2 + j) * 16 + ((t & 63) >> 2); }
; __device__ __forceinline__ int tkc() { const int l = otid() & 63; return ((l & 3) ^ ((0 - (l >> 4)) & 3)) * 8; }
; template <class MK, class SW, class EPI>
; __device__ __forceinline__ void gemm_phase(int first, int step, int n, int nk, MK mk, SW swapf, EPI epi, char* lds) {
;     ...
;   for (int it = first; it < n; it += step) {
;     const bool has_next = (it + step < n);
;     const TP nxt = mk(has_next ? it + step : it);
;     f32x4 acc[8][4];
;     zero_acc(acc);
;     if (swapf(it)) gemm_main<true>(acc, cur, nk, lds); else gemm_main<false>(acc, cur, nk, lds);
; __device__ __forceinline__ TP moe1_ptrs(const Params& p, int e, int mt, int nt) {
;   const u16* X = (const u16*)(p.ws + OFF_ACT1);
;   const int* idx = (const int*)(p.ws + OFF_IDX);
;   TP t;
;   {
;     const int r0 = mt * 256 + trow(0), r1 = mt * 256 + trow(1);
;     t.a0 = X + (size_t)((r0 >> 8) * 2048 + idx[e * 8192 + r0]) * 1024 + tkc();
;     t.a1 = X + (size_t)((r1 >> 8) * 2048 + idx[e * 8192 + r1]) * 1024 + tkc();
;   }
;   {
;     const int R0 = trow(0), R1 = trow(1);
;     const int P0 = (R0 & ~63) | (((R0 >> 2) & 3) * 16 + ((R0 >> 4) & 3) * 4 + (R0 & 3));
;     const int P1 = (R1 & ~63) | (((R1 >> 2) & 3) * 16 + ((R1 >> 4) & 3) * 4 + (R1 & 3));
;     const u16* wb = (const u16*)(p.ws + OFF_WGU) + (size_t)e * 5632 * 1024 + (size_t)(nt * 256) * 1024 + tkc();
;     t.b0 = wb + (size_t)P0 * 1024; t.b1 = wb + (size_t)P1 * 1024;
;   }
;   return t;
; }
.LBB0_1299:
	s_mov_b32 s27, s26
	s_add_i32 s26, s26, s3
	s_cmpk_gt_i32 s26, 0x15ff
	s_cselect_b64 s[16:17], -1, 0
	s_cmpk_lt_i32 s26, 0x1600
	s_cselect_b64 s[18:19], -1, 0
	s_and_b64 s[20:21], s[18:19], exec
	s_cselect_b32 s20, s26, s27
	s_mul_hi_i32 s21, s20, 0x2e8ba2e9
	s_lshr_b32 s22, s21, 31
	s_ashr_i32 s21, s21, 7
	s_add_i32 s28, s21, s22
	s_mul_i32 s21, s28, 0x2c0
	s_sub_i32 s20, s20, s21
	s_bfe_u32 s21, s20, 0x5001a
	s_add_i32 s21, s20, s21
	s_sext_i32_i16 s22, s21
	s_and_b32 s21, s21, 0xffe0
	v_mov_b32_e32 v0, v153
	s_sub_i32 s20, s20, s21
	s_sext_i32_i16 s20, s20
	v_ashrrev_i32_e32 v1, 1, v0
	v_bfe_u32 v0, v0, 2, 4
	s_lshl_b32 s20, s20, 8
	v_and_or_b32 v0, v1, s38, v0
	v_add_u32_e32 v134, s20, v0
	v_mov_b32_e32 v0, v153
	s_add_i32 s28, s28, s52
	v_ashrrev_i32_e32 v1, 1, v0
	v_bfe_u32 v0, v0, 2, 4
	v_and_or_b32 v0, v1, s38, v0
	v_add_u32_e32 v0, s20, v0
	s_lshl_b32 s20, s28, 13
	v_or_b32_e32 v147, 16, v0
	v_add_u32_e32 v0, s20, v134
	v_ashrrev_i32_e32 v1, 31, v0
	v_lshl_add_u64 v[0:1], v[0:1], 2, s[58:59]
	global_load_dword v154, v[0:1], off
	v_add_u32_e32 v0, s20, v147
	v_ashrrev_i32_e32 v1, 31, v0
	v_mov_b32_e32 v144, v153
	v_lshl_add_u64 v[0:1], v[0:1], 2, s[58:59]
	global_load_dword v155, v[0:1], off
	v_mov_b32_e32 v146, v153
	v_mov_b32_e32 v151, v153
	v_mov_b32_e32 v145, v153
	v_mov_b32_e32 v149, v153
	v_mov_b32_e32 v0, v153
	s_lshr_b32 s29, s22, 5
	v_lshlrev_b32_e32 v3, 2, v0
	v_and_b32_e32 v3, 48, v3
	v_sub_u32_e32 v3, 0, v3
	v_and_b32_e32 v156, 15, v0
	v_lshlrev_b32_e32 v1, 5, v0
	v_lshlrev_b32_e32 v2, 4, v0
	v_bitop3_b32 v157, v0, 48, v3 bitop3:0x48
	v_ashrrev_i32_e32 v158, 1, v0
	v_lshlrev_b32_e32 v0, 6, v0
	v_and_b32_e32 v1, 0xfffff800, v1
	v_and_b32_e32 v2, 0x3f0, v2
	v_and_or_b32 v3, v158, s2, v156
	v_and_b32_e32 v159, 0x33c0, v0
	v_mov_b32_e32 v0, 0
	v_lshl_or_b32 v160, v3, 6, v157
	v_or_b32_e32 v161, v159, v157
	v_add3_u32 v162, 0, v1, v2
	v_lshl_add_u64 v[136:137], v[136:137], 0, s[42:43]
	v_lshl_add_u64 v[138:139], v[138:139], 0, s[42:43]
	v_lshl_add_u64 v[140:141], v[140:141], 0, s[42:43]
	v_lshl_add_u64 v[142:143], v[142:143], 0, s[42:43]
	s_mov_b32 s20, 0x18000
	v_mov_b32_e32 v1, v0
	v_mov_b32_e32 v2, v0
	v_mov_b32_e32 v3, v0
	v_mov_b32_e32 v4, v0
	v_mov_b32_e32 v5, v0
	v_mov_b32_e32 v6, v0
	v_mov_b32_e32 v7, v0
	v_mov_b32_e32 v8, v0
	v_mov_b32_e32 v9, v0
	v_mov_b32_e32 v10, v0
	v_mov_b32_e32 v11, v0
	v_mov_b32_e32 v12, v0
	v_mov_b32_e32 v13, v0
	v_mov_b32_e32 v14, v0
	v_mov_b32_e32 v15, v0
	v_mov_b32_e32 v16, v0
	v_mov_b32_e32 v17, v0
	v_mov_b32_e32 v18, v0
	v_mov_b32_e32 v19, v0
	v_mov_b32_e32 v20, v0
	v_mov_b32_e32 v21, v0
	v_mov_b32_e32 v22, v0
	v_mov_b32_e32 v23, v0
	v_mov_b32_e32 v24, v0
	v_mov_b32_e32 v25, v0
	v_mov_b32_e32 v26, v0
	v_mov_b32_e32 v27, v0
	v_mov_b32_e32 v28, v0
	v_mov_b32_e32 v29, v0
	v_mov_b32_e32 v30, v0
	v_mov_b32_e32 v31, v0
	v_mov_b32_e32 v32, v0
	v_mov_b32_e32 v33, v0
	v_mov_b32_e32 v34, v0
	v_mov_b32_e32 v35, v0
	v_mov_b32_e32 v36, v0
	v_mov_b32_e32 v37, v0
	v_mov_b32_e32 v38, v0
	v_mov_b32_e32 v39, v0
	v_mov_b32_e32 v40, v0
	v_mov_b32_e32 v41, v0
	v_mov_b32_e32 v42, v0
	v_mov_b32_e32 v43, v0
	v_mov_b32_e32 v44, v0
	v_mov_b32_e32 v45, v0
	v_mov_b32_e32 v46, v0
	v_mov_b32_e32 v47, v0
	v_mov_b32_e32 v48, v0
	v_mov_b32_e32 v49, v0
	v_mov_b32_e32 v50, v0
	v_mov_b32_e32 v51, v0
	v_mov_b32_e32 v52, v0
	v_mov_b32_e32 v53, v0
	v_mov_b32_e32 v54, v0
	v_mov_b32_e32 v55, v0
	v_mov_b32_e32 v56, v0
	v_mov_b32_e32 v57, v0
	v_mov_b32_e32 v58, v0
	v_mov_b32_e32 v59, v0
	v_mov_b32_e32 v60, v0
	v_mov_b32_e32 v61, v0
	v_mov_b32_e32 v62, v0
	v_mov_b32_e32 v63, v0
	v_mov_b32_e32 v64, v0
	v_mov_b32_e32 v65, v0
	v_mov_b32_e32 v66, v0
	v_mov_b32_e32 v67, v0
	v_mov_b32_e32 v68, v0
	v_mov_b32_e32 v69, v0
	v_mov_b32_e32 v70, v0
	v_mov_b32_e32 v71, v0
	v_mov_b32_e32 v72, v0
	v_mov_b32_e32 v73, v0
	v_mov_b32_e32 v74, v0
	v_mov_b32_e32 v75, v0
	v_mov_b32_e32 v76, v0
	v_mov_b32_e32 v77, v0
	v_mov_b32_e32 v78, v0
	v_mov_b32_e32 v79, v0
	v_mov_b32_e32 v80, v0
	v_mov_b32_e32 v81, v0
	v_mov_b32_e32 v82, v0
	v_mov_b32_e32 v83, v0
	v_mov_b32_e32 v84, v0
	v_mov_b32_e32 v85, v0
	v_mov_b32_e32 v86, v0
	v_mov_b32_e32 v87, v0
	v_mov_b32_e32 v88, v0
	v_mov_b32_e32 v89, v0
	v_mov_b32_e32 v90, v0
	v_mov_b32_e32 v91, v0
	v_mov_b32_e32 v92, v0
	v_mov_b32_e32 v93, v0
	v_mov_b32_e32 v94, v0
	v_mov_b32_e32 v95, v0
	v_mov_b32_e32 v96, v0
	v_mov_b32_e32 v97, v0
	v_mov_b32_e32 v98, v0
	v_mov_b32_e32 v99, v0
	v_mov_b32_e32 v100, v0
	v_mov_b32_e32 v101, v0
	v_mov_b32_e32 v102, v0
	v_mov_b32_e32 v103, v0
	v_mov_b32_e32 v104, v0
	v_mov_b32_e32 v105, v0
	v_mov_b32_e32 v106, v0
	v_mov_b32_e32 v107, v0
	v_mov_b32_e32 v108, v0
	v_mov_b32_e32 v109, v0
	v_mov_b32_e32 v110, v0
	v_mov_b32_e32 v111, v0
	v_mov_b32_e32 v112, v0
	v_mov_b32_e32 v113, v0
	v_mov_b32_e32 v114, v0
	v_mov_b32_e32 v115, v0
	v_mov_b32_e32 v116, v0
	v_mov_b32_e32 v117, v0
	v_mov_b32_e32 v118, v0
	v_mov_b32_e32 v119, v0
	v_mov_b32_e32 v120, v0
	v_mov_b32_e32 v121, v0
	v_mov_b32_e32 v122, v0
	v_mov_b32_e32 v123, v0
	v_mov_b32_e32 v124, v0
	v_mov_b32_e32 v125, v0
	v_mov_b32_e32 v126, v0
	v_mov_b32_e32 v127, v0
	v_readfirstlane_b32 s98, v162
	s_waitcnt vmcnt(8)
	s_barrier
	s_cmp_lt_u32 s98, 0x2000
	s_cbranch_scc1 .Lmoe1_top
	s_barrier
; #define GEMM_WAITV(n) asm volatile("s_waitcnt vmcnt(" #n ")" ::: "memory")
; template <bool SWAP>
; __device__ __forceinline__ void gemm_main(f32x4 (&acc)[8][4], const TP& t, int nk, char* lds) {
;     ...
; #pragma unroll 1
;   for (int kt = 0; kt < nk - 3; ++kt) {
;     GEMM_WAITV(8);
;     GEMM_STEP(kt, true)
;   }
; #pragma unroll 1
;   for (int kt = nk - 3; kt < nk; ++kt) {
;     const int rem = nk - kt;
;     if (rem == 3) GEMM_WAITV(8); else if (rem == 2) GEMM_WAITV(4); else GEMM_WAITV(0);
;     GEMM_STEP(kt, false)
;   }
;   __builtin_amdgcn_s_barrier();
.Lmoe1_top:
	s_add_i32 s21, s20, 0xfffe8000
	s_and_b32 s21, s21, 0x18000
	v_add_u32_e32 v235, s21, v160
	v_add_u32_e32 v236, s21, v161
	ds_read_b128 v[182:185], v235
	ds_read_b128 v[164:167], v236 offset:16384
	ds_read_b128 v[170:173], v236 offset:17408
	ds_read_b128 v[174:177], v236 offset:18432
	ds_read_b128 v[178:181], v236 offset:19456
	ds_read_b128 v[186:189], v235 offset:1024
	ds_read_b128 v[190:193], v235 offset:2048
	ds_read_b128 v[194:197], v235 offset:3072
	s_and_b32 s99, s20, 0x18000
	s_add_i32 s99, s99, s98
	s_mov_b32 m0, s99
	s_nop 0
	global_load_lds_dwordx4 v[136:137], off
	s_add_i32 m0, s99, 0x400
	s_nop 0
	global_load_lds_dwordx4 v[138:139], off
	s_waitcnt lgkmcnt(0)
	s_barrier
	s_setprio 1
	v_mfma_f32_16x16x32_bf16 v[124:127], v[164:167], v[182:185], v[124:127]
	v_mfma_f32_16x16x32_bf16 v[120:123], v[170:173], v[182:185], v[120:123]
	v_mfma_f32_16x16x32_bf16 v[116:119], v[174:177], v[182:185], v[116:119]
	v_mfma_f32_16x16x32_bf16 v[112:115], v[178:181], v[182:185], v[112:115]
	v_mfma_f32_16x16x32_bf16 v[108:111], v[164:167], v[186:189], v[108:111]
	v_mfma_f32_16x16x32_bf16 v[104:107], v[170:173], v[186:189], v[104:107]
	v_mfma_f32_16x16x32_bf16 v[100:103], v[174:177], v[186:189], v[100:103]
	v_mfma_f32_16x16x32_bf16 v[96:99], v[178:181], v[186:189], v[96:99]
	v_mfma_f32_16x16x32_bf16 v[92:95], v[164:167], v[190:193], v[92:95]
	v_mfma_f32_16x16x32_bf16 v[88:91], v[170:173], v[190:193], v[88:91]
	v_mfma_f32_16x16x32_bf16 v[84:87], v[174:177], v[190:193], v[84:87]
	v_mfma_f32_16x16x32_bf16 v[80:83], v[178:181], v[190:193], v[80:83]
	v_mfma_f32_16x16x32_bf16 v[76:79], v[164:167], v[194:197], v[76:79]
	v_mfma_f32_16x16x32_bf16 v[72:75], v[170:173], v[194:197], v[72:75]
	v_mfma_f32_16x16x32_bf16 v[68:71], v[174:177], v[194:197], v[68:71]
	v_mfma_f32_16x16x32_bf16 v[64:67], v[178:181], v[194:197], v[64:67]
	s_setprio 0
	s_barrier
	ds_read_b128 v[182:185], v235 offset:4096
	ds_read_b128 v[186:189], v235 offset:5120
	ds_read_b128 v[190:193], v235 offset:6144
	ds_read_b128 v[194:197], v235 offset:7168
	s_add_i32 m0, s99, 0x4000
	s_nop 0
	global_load_lds_dwordx4 v[140:141], off
	s_add_i32 m0, s99, 0x4400
	s_nop 0
	global_load_lds_dwordx4 v[142:143], off
	v_lshl_add_u64 v[136:137], v[136:137], 0, 64
	v_lshl_add_u64 v[138:139], v[138:139], 0, 64
	v_lshl_add_u64 v[140:141], v[140:141], 0, 64
	v_lshl_add_u64 v[142:143], v[142:143], 0, 64
	s_add_i32 s20, s20, 0x8000
	s_waitcnt vmcnt(8)
	s_waitcnt lgkmcnt(0)
	s_barrier
	s_setprio 1
	v_mfma_f32_16x16x32_bf16 v[60:63], v[164:167], v[182:185], v[60:63]
	v_mfma_f32_16x16x32_bf16 v[56:59], v[170:173], v[182:185], v[56:59]
	v_mfma_f32_16x16x32_bf16 v[52:55], v[174:177], v[182:185], v[52:55]
	v_mfma_f32_16x16x32_bf16 v[48:51], v[178:181], v[182:185], v[48:51]
	v_mfma_f32_16x16x32_bf16 v[44:47], v[164:167], v[186:189], v[44:47]
	v_mfma_f32_16x16x32_bf16 v[40:43], v[170:173], v[186:189], v[40:43]
	v_mfma_f32_16x16x32_bf16 v[36:39], v[174:177], v[186:189], v[36:39]
	v_mfma_f32_16x16x32_bf16 v[32:35], v[178:181], v[186:189], v[32:35]
	v_mfma_f32_16x16x32_bf16 v[28:31], v[164:167], v[190:193], v[28:31]
	v_mfma_f32_16x16x32_bf16 v[24:27], v[170:173], v[190:193], v[24:27]
	v_mfma_f32_16x16x32_bf16 v[20:23], v[174:177], v[190:193], v[20:23]
	v_mfma_f32_16x16x32_bf16 v[16:19], v[178:181], v[190:193], v[16:19]
	v_mfma_f32_16x16x32_bf16 v[12:15], v[164:167], v[194:197], v[12:15]
	v_mfma_f32_16x16x32_bf16 v[8:11], v[170:173], v[194:197], v[8:11]
	v_mfma_f32_16x16x32_bf16 v[4:7], v[174:177], v[194:197], v[4:7]
	v_mfma_f32_16x16x32_bf16 v[0:3], v[178:181], v[194:197], v[0:3]
	s_setprio 0
	s_barrier
	s_cmp_lg_u32 s20, 0x100000
	s_cbranch_scc1 .Lmoe1_top
	v_add_u32_e32 v235, 0x8000, v160
	v_add_u32_e32 v236, 0x8000, v161
	ds_read_b128 v[182:185], v235
	ds_read_b128 v[164:167], v236 offset:16384
	ds_read_b128 v[170:173], v236 offset:17408
	ds_read_b128 v[174:177], v236 offset:18432
	ds_read_b128 v[178:181], v236 offset:19456
	ds_read_b128 v[186:189], v235 offset:1024
	ds_read_b128 v[190:193], v235 offset:2048
	ds_read_b128 v[194:197], v235 offset:3072
	s_waitcnt lgkmcnt(0)
	s_barrier
	s_setprio 1
	v_mfma_f32_16x16x32_bf16 v[124:127], v[164:167], v[182:185], v[124:127]
	v_mfma_f32_16x16x32_bf16 v[120:123], v[170:173], v[182:185], v[120:123]
	v_mfma_f32_16x16x32_bf16 v[116:119], v[174:177], v[182:185], v[116:119]
	v_mfma_f32_16x16x32_bf16 v[112:115], v[178:181], v[182:185], v[112:115]
	v_mfma_f32_16x16x32_bf16 v[108:111], v[164:167], v[186:189], v[108:111]
	v_mfma_f32_16x16x32_bf16 v[104:107], v[170:173], v[186:189], v[104:107]
	v_mfma_f32_16x16x32_bf16 v[100:103], v[174:177], v[186:189], v[100:103]
	v_mfma_f32_16x16x32_bf16 v[96:99], v[178:181], v[186:189], v[96:99]
	v_mfma_f32_16x16x32_bf16 v[92:95], v[164:167], v[190:193], v[92:95]
	v_mfma_f32_16x16x32_bf16 v[88:91], v[170:173], v[190:193], v[88:91]
	v_mfma_f32_16x16x32_bf16 v[84:87], v[174:177], v[190:193], v[84:87]
	v_mfma_f32_16x16x32_bf16 v[80:83], v[178:181], v[190:193], v[80:83]
	v_mfma_f32_16x16x32_bf16 v[76:79], v[164:167], v[194:197], v[76:79]
	v_mfma_f32_16x16x32_bf16 v[72:75], v[170:173], v[194:197], v[72:75]
	v_mfma_f32_16x16x32_bf16 v[68:71], v[174:177], v[194:197], v[68:71]
	v_mfma_f32_16x16x32_bf16 v[64:67], v[178:181], v[194:197], v[64:67]
	s_setprio 0
	s_barrier
	ds_read_b128 v[182:185], v235 offset:4096
	ds_read_b128 v[186:189], v235 offset:5120
	ds_read_b128 v[190:193], v235 offset:6144
	ds_read_b128 v[194:197], v235 offset:7168
	s_waitcnt vmcnt(4)
	s_waitcnt lgkmcnt(0)
	s_barrier
; #define GEMM_WAITV(n) asm volatile("s_waitcnt vmcnt(" #n ")" ::: "memory")
; template <bool SWAP>
; __device__ __forceinline__ void gemm_main(f32x4 (&acc)[8][4], const TP& t, int nk, char* lds) {
;     ...
; #pragma unroll 1
;   for (int kt = 0; kt < nk - 3; ++kt) {
;     GEMM_WAITV(8);
;     GEMM_STEP(kt, true)
;   }
; #pragma unroll 1
;   for (int kt = nk - 3; kt < nk; ++kt) {
;     const int rem = nk - kt;
;     if (rem == 3) GEMM_WAITV(8); else if (rem == 2) GEMM_WAITV(4); else GEMM_WAITV(0);
;     GEMM_STEP(kt, false)
;   }
;   __builtin_amdgcn_s_barrier();
	s_setprio 1
	v_mfma_f32_16x16x32_bf16 v[60:63], v[164:167], v[182:185], v[60:63]
	v_mfma_f32_16x16x32_bf16 v[56:59], v[170:173], v[182:185], v[56:59]
	v_mfma_f32_16x16x32_bf16 v[52:55], v[174:177], v[182:185], v[52:55]
	v_mfma_f32_16x16x32_bf16 v[48:51], v[178:181], v[182:185], v[48:51]
	v_mfma_f32_16x16x32_bf16 v[44:47], v[164:167], v[186:189], v[44:47]
	v_mfma_f32_16x16x32_bf16 v[40:43], v[170:173], v[186:189], v[40:43]
	v_mfma_f32_16x16x32_bf16 v[36:39], v[174:177], v[186:189], v[36:39]
	v_mfma_f32_16x16x32_bf16 v[32:35], v[178:181], v[186:189], v[32:35]
	v_mfma_f32_16x16x32_bf16 v[28:31], v[164:167], v[190:193], v[28:31]
	v_mfma_f32_16x16x32_bf16 v[24:27], v[170:173], v[190:193], v[24:27]
	v_mfma_f32_16x16x32_bf16 v[20:23], v[174:177], v[190:193], v[20:23]
	v_mfma_f32_16x16x32_bf16 v[16:19], v[178:181], v[190:193], v[16:19]
	v_mfma_f32_16x16x32_bf16 v[12:15], v[164:167], v[194:197], v[12:15]
	v_mfma_f32_16x16x32_bf16 v[8:11], v[170:173], v[194:197], v[8:11]
	v_mfma_f32_16x16x32_bf16 v[4:7], v[174:177], v[194:197], v[4:7]
	v_mfma_f32_16x16x32_bf16 v[0:3], v[178:181], v[194:197], v[0:3]
	s_setprio 0
	s_barrier
	v_add_u32_e32 v235, 0x10000, v160
	v_add_u32_e32 v236, 0x10000, v161
	ds_read_b128 v[182:185], v235
	ds_read_b128 v[164:167], v236 offset:16384
	ds_read_b128 v[170:173], v236 offset:17408
	ds_read_b128 v[174:177], v236 offset:18432
	ds_read_b128 v[178:181], v236 offset:19456
	ds_read_b128 v[186:189], v235 offset:1024
	ds_read_b128 v[190:193], v235 offset:2048
	ds_read_b128 v[194:197], v235 offset:3072
	s_waitcnt lgkmcnt(0)
	s_barrier
	s_setprio 1
	v_mfma_f32_16x16x32_bf16 v[124:127], v[164:167], v[182:185], v[124:127]
	v_mfma_f32_16x16x32_bf16 v[120:123], v[170:173], v[182:185], v[120:123]
	v_mfma_f32_16x16x32_bf16 v[116:119], v[174:177], v[182:185], v[116:119]
	v_mfma_f32_16x16x32_bf16 v[112:115], v[178:181], v[182:185], v[112:115]
	v_mfma_f32_16x16x32_bf16 v[108:111], v[164:167], v[186:189], v[108:111]
	v_mfma_f32_16x16x32_bf16 v[104:107], v[170:173], v[186:189], v[104:107]
	v_mfma_f32_16x16x32_bf16 v[100:103], v[174:177], v[186:189], v[100:103]
	v_mfma_f32_16x16x32_bf16 v[96:99], v[178:181], v[186:189], v[96:99]
	v_mfma_f32_16x16x32_bf16 v[92:95], v[164:167], v[190:193], v[92:95]
	v_mfma_f32_16x16x32_bf16 v[88:91], v[170:173], v[190:193], v[88:91]
	v_mfma_f32_16x16x32_bf16 v[84:87], v[174:177], v[190:193], v[84:87]
	v_mfma_f32_16x16x32_bf16 v[80:83], v[178:181], v[190:193], v[80:83]
	v_mfma_f32_16x16x32_bf16 v[76:79], v[164:167], v[194:197], v[76:79]
	v_mfma_f32_16x16x32_bf16 v[72:75], v[170:173], v[194:197], v[72:75]
	v_mfma_f32_16x16x32_bf16 v[68:71], v[174:177], v[194:197], v[68:71]
	v_mfma_f32_16x16x32_bf16 v[64:67], v[178:181], v[194:197], v[64:67]
	s_setprio 0
	s_barrier
	ds_read_b128 v[182:185], v235 offset:4096
	ds_read_b128 v[186:189], v235 offset:5120
	ds_read_b128 v[190:193], v235 offset:6144
	ds_read_b128 v[194:197], v235 offset:7168
	s_waitcnt vmcnt(0)
	s_waitcnt lgkmcnt(0)
	s_barrier
	s_setprio 1
	v_mfma_f32_16x16x32_bf16 v[60:63], v[164:167], v[182:185], v[60:63]
	v_mfma_f32_16x16x32_bf16 v[56:59], v[170:173], v[182:185], v[56:59]
	v_mfma_f32_16x16x32_bf16 v[52:55], v[174:177], v[182:185], v[52:55]
	v_mfma_f32_16x16x32_bf16 v[48:51], v[178:181], v[182:185], v[48:51]
	v_mfma_f32_16x16x32_bf16 v[44:47], v[164:167], v[186:189], v[44:47]
	v_mfma_f32_16x16x32_bf16 v[40:43], v[170:173], v[186:189], v[40:43]
	v_mfma_f32_16x16x32_bf16 v[36:39], v[174:177], v[186:189], v[36:39]
	v_mfma_f32_16x16x32_bf16 v[32:35], v[178:181], v[186:189], v[32:35]
	v_mfma_f32_16x16x32_bf16 v[28:31], v[164:167], v[190:193], v[28:31]
	v_mfma_f32_16x16x32_bf16 v[24:27], v[170:173], v[190:193], v[24:27]
	v_mfma_f32_16x16x32_bf16 v[20:23], v[174:177], v[190:193], v[20:23]
	v_mfma_f32_16x16x32_bf16 v[16:19], v[178:181], v[190:193], v[16:19]
	v_mfma_f32_16x16x32_bf16 v[12:15], v[164:167], v[194:197], v[12:15]
	v_mfma_f32_16x16x32_bf16 v[8:11], v[170:173], v[194:197], v[8:11]
	v_mfma_f32_16x16x32_bf16 v[4:7], v[174:177], v[194:197], v[4:7]
	v_mfma_f32_16x16x32_bf16 v[0:3], v[178:181], v[194:197], v[0:3]
	s_setprio 0
	s_barrier
; #define GEMM_WAITV(n) asm volatile("s_waitcnt vmcnt(" #n ")" ::: "memory")
; template <bool SWAP>
; __device__ __forceinline__ void gemm_main(f32x4 (&acc)[8][4], const TP& t, int nk, char* lds) {
;     ...
; #pragma unroll 1
;   for (int kt = nk - 3; kt < nk; ++kt) {
;     const int rem = nk - kt;
;     if (rem == 3) GEMM_WAITV(8); else if (rem == 2) GEMM_WAITV(4); else GEMM_WAITV(0);
;     GEMM_STEP(kt, false)
;   }
;   __builtin_amdgcn_s_barrier();
	v_add_u32_e32 v235, 0x18000, v160
	v_add_u32_e32 v236, 0x18000, v161
	ds_read_b128 v[182:185], v235
	ds_read_b128 v[164:167], v236 offset:16384
	ds_read_b128 v[170:173], v236 offset:17408
	ds_read_b128 v[174:177], v236 offset:18432
	ds_read_b128 v[178:181], v236 offset:19456
	ds_read_b128 v[186:189], v235 offset:1024
	ds_read_b128 v[190:193], v235 offset:2048
	ds_read_b128 v[194:197], v235 offset:3072
	s_waitcnt lgkmcnt(0)
	s_barrier
	s_setprio 1
	v_mfma_f32_16x16x32_bf16 v[124:127], v[164:167], v[182:185], v[124:127]
	v_mfma_f32_16x16x32_bf16 v[120:123], v[170:173], v[182:185], v[120:123]
	v_mfma_f32_16x16x32_bf16 v[116:119], v[174:177], v[182:185], v[116:119]
	v_mfma_f32_16x16x32_bf16 v[112:115], v[178:181], v[182:185], v[112:115]
	v_mfma_f32_16x16x32_bf16 v[108:111], v[164:167], v[186:189], v[108:111]
	v_mfma_f32_16x16x32_bf16 v[104:107], v[170:173], v[186:189], v[104:107]
	v_mfma_f32_16x16x32_bf16 v[100:103], v[174:177], v[186:189], v[100:103]
	v_mfma_f32_16x16x32_bf16 v[96:99], v[178:181], v[186:189], v[96:99]
	v_mfma_f32_16x16x32_bf16 v[92:95], v[164:167], v[190:193], v[92:95]
	v_mfma_f32_16x16x32_bf16 v[88:91], v[170:173], v[190:193], v[88:91]
	v_mfma_f32_16x16x32_bf16 v[84:87], v[174:177], v[190:193], v[84:87]
	v_mfma_f32_16x16x32_bf16 v[80:83], v[178:181], v[190:193], v[80:83]
	v_mfma_f32_16x16x32_bf16 v[76:79], v[164:167], v[194:197], v[76:79]
	v_mfma_f32_16x16x32_bf16 v[72:75], v[170:173], v[194:197], v[72:75]
	v_mfma_f32_16x16x32_bf16 v[68:71], v[174:177], v[194:197], v[68:71]
	v_mfma_f32_16x16x32_bf16 v[64:67], v[178:181], v[194:197], v[64:67]
	s_setprio 0
	s_barrier
	ds_read_b128 v[182:185], v235 offset:4096
	ds_read_b128 v[186:189], v235 offset:5120
	ds_read_b128 v[190:193], v235 offset:6144
	ds_read_b128 v[194:197], v235 offset:7168
	s_waitcnt lgkmcnt(0)
	s_barrier
	s_setprio 1
	v_mfma_f32_16x16x32_bf16 v[60:63], v[164:167], v[182:185], v[60:63]
	v_mfma_f32_16x16x32_bf16 v[56:59], v[170:173], v[182:185], v[56:59]
	v_mfma_f32_16x16x32_bf16 v[52:55], v[174:177], v[182:185], v[52:55]
	v_mfma_f32_16x16x32_bf16 v[48:51], v[178:181], v[182:185], v[48:51]
	v_mfma_f32_16x16x32_bf16 v[44:47], v[164:167], v[186:189], v[44:47]
	v_mfma_f32_16x16x32_bf16 v[40:43], v[170:173], v[186:189], v[40:43]
	v_mfma_f32_16x16x32_bf16 v[36:39], v[174:177], v[186:189], v[36:39]
	v_mfma_f32_16x16x32_bf16 v[32:35], v[178:181], v[186:189], v[32:35]
	v_mfma_f32_16x16x32_bf16 v[28:31], v[164:167], v[190:193], v[28:31]
	v_mfma_f32_16x16x32_bf16 v[24:27], v[170:173], v[190:193], v[24:27]
	v_mfma_f32_16x16x32_bf16 v[20:23], v[174:177], v[190:193], v[20:23]
	v_mfma_f32_16x16x32_bf16 v[16:19], v[178:181], v[190:193], v[16:19]
	v_mfma_f32_16x16x32_bf16 v[12:15], v[164:167], v[194:197], v[12:15]
	v_mfma_f32_16x16x32_bf16 v[8:11], v[170:173], v[194:197], v[8:11]
	v_mfma_f32_16x16x32_bf16 v[4:7], v[174:177], v[194:197], v[4:7]
	v_mfma_f32_16x16x32_bf16 v[0:3], v[178:181], v[194:197], v[0:3]
	s_setprio 0
	s_barrier
	s_cmp_ge_u32 s98, 0x2000
	s_cbranch_scc1 .Lmoe1_done
	s_barrier

; __device__ __forceinline__ int trow(int j) { const int t = otid(); return ((t >> 6) * 2 + j) * 16 + ((t & 63) >> 2); }
; __device__ __forceinline__ int tkc() { const int l = otid() & 63; return ((l & 3) ^ ((0 - (l >> 4)) & 3)) * 8; }
; #define GEMM_WAITV(n) asm volatile("s_waitcnt vmcnt(" #n ")" ::: "memory")
; __device__ __forceinline__ int perm_row(int R) { return (R & ~63) | (((R >> 2) & 3) * 16 + ((R >> 4) & 3) * 4 + (R & 3)); }
; template <bool SWAP>
; __device__ __forceinline__ void gemm_main(f32x4 (&acc)[8][4], const TP& t, int nk, char* lds) {
;     ...
; #pragma unroll 1
;   for (int kt = 0; kt < nk - 3; ++kt) {
;     GEMM_WAITV(8);
;     GEMM_STEP(kt, true)
; template <class MK, class SW, class EPI>
; __device__ __forceinline__ void gemm_phase(int first, int step, int n, int nk, MK mk, SW swapf, EPI epi, char* lds) {
;     ...
;   for (int it = first; it < n; it += step) {
;     const bool has_next = (it + step < n);
;     const TP nxt = mk(has_next ? it + step : it);
;     f32x4 acc[8][4];
;     zero_acc(acc);
;     if (swapf(it)) gemm_main<true>(acc, cur, nk, lds); else gemm_main<false>(acc, cur, nk, lds);
; __device__ __forceinline__ TP moe2_ptrs(const Params& p, int e, int el, int mt, int nt) {
;   TP t;
;   t.a0 = (const u16*)(p.ws + OFF_H) + (size_t)el * 8192 * 2816 + (size_t)(mt * 256 + trow(0)) * 2816 + tkc(); t.a1 = t.a0 + 16 * 2816;
;   t.b0 = (const u16*)(p.ws + OFF_WD) + (size_t)e * 1024 * 2816 + (size_t)(nt * 256 + perm_row(trow(0))) * 2816 + tkc();
;   t.b1 = (const u16*)(p.ws + OFF_WD) + (size_t)e * 1024 * 2816 + (size_t)(nt * 256 + perm_row(trow(1))) * 2816 + tkc();
;   return t;
; }
.LBB0_1368:
	v_mov_b32_e32 v146, v153
	v_mov_b32_e32 v134, v153
	v_mov_b32_e32 v145, v153
	v_mov_b32_e32 v142, v153
	v_mov_b32_e32 v144, v153
	v_mov_b32_e32 v143, v153
	v_mov_b32_e32 v0, v153
	s_mov_b64 s[14:15], 0x160c0
	v_lshlrev_b32_e32 v3, 2, v0
	v_and_b32_e32 v3, 48, v3
	v_sub_u32_e32 v3, 0, v3
	v_and_b32_e32 v147, 15, v0
	v_lshlrev_b32_e32 v1, 5, v0
	v_lshlrev_b32_e32 v2, 4, v0
	v_bitop3_b32 v149, v0, 48, v3 bitop3:0x48
	v_ashrrev_i32_e32 v151, 1, v0
	v_lshlrev_b32_e32 v0, 6, v0
	v_and_b32_e32 v1, 0xfffff800, v1
	v_and_b32_e32 v2, 0x3f0, v2
	v_and_or_b32 v3, v151, s2, v147
	v_and_b32_e32 v154, 0x33c0, v0
	v_mov_b32_e32 v0, 0
	s_mov_b32 s22, s18
	v_lshl_or_b32 v155, v3, 6, v149
	v_or_b32_e32 v156, v154, v149
	v_add3_u32 v157, 0, v1, v2
	v_lshl_add_u64 v[136:137], v[136:137], 0, s[14:15]
	v_lshl_add_u64 v[138:139], v[138:139], 0, s[42:43]
	v_lshl_add_u64 v[140:141], v[140:141], 0, s[42:43]
	s_mov_b32 s14, 0x18000
	v_mov_b32_e32 v1, v0
	v_mov_b32_e32 v2, v0
	v_mov_b32_e32 v3, v0
	v_mov_b32_e32 v4, v0
	v_mov_b32_e32 v5, v0
	v_mov_b32_e32 v6, v0
	v_mov_b32_e32 v7, v0
	v_mov_b32_e32 v8, v0
	v_mov_b32_e32 v9, v0
	v_mov_b32_e32 v10, v0
	v_mov_b32_e32 v11, v0
	v_mov_b32_e32 v12, v0
	v_mov_b32_e32 v13, v0
	v_mov_b32_e32 v14, v0
	v_mov_b32_e32 v15, v0
	v_mov_b32_e32 v16, v0
	v_mov_b32_e32 v17, v0
	v_mov_b32_e32 v18, v0
	v_mov_b32_e32 v19, v0
	v_mov_b32_e32 v20, v0
	v_mov_b32_e32 v21, v0
	v_mov_b32_e32 v22, v0
	v_mov_b32_e32 v23, v0
	v_mov_b32_e32 v24, v0
	v_mov_b32_e32 v25, v0
	v_mov_b32_e32 v26, v0
	v_mov_b32_e32 v27, v0
	v_mov_b32_e32 v28, v0
	v_mov_b32_e32 v29, v0
	v_mov_b32_e32 v30, v0
	v_mov_b32_e32 v31, v0
	v_mov_b32_e32 v32, v0
	v_mov_b32_e32 v33, v0
	v_mov_b32_e32 v34, v0
	v_mov_b32_e32 v35, v0
	v_mov_b32_e32 v36, v0
	v_mov_b32_e32 v37, v0
	v_mov_b32_e32 v38, v0
	v_mov_b32_e32 v39, v0
	v_mov_b32_e32 v40, v0
	v_mov_b32_e32 v41, v0
	v_mov_b32_e32 v42, v0
	v_mov_b32_e32 v43, v0
	v_mov_b32_e32 v44, v0
	v_mov_b32_e32 v45, v0
	v_mov_b32_e32 v46, v0
	v_mov_b32_e32 v47, v0
	v_mov_b32_e32 v48, v0
	v_mov_b32_e32 v49, v0
	v_mov_b32_e32 v50, v0
	v_mov_b32_e32 v51, v0
	v_mov_b32_e32 v52, v0
	v_mov_b32_e32 v53, v0
	v_mov_b32_e32 v54, v0
	v_mov_b32_e32 v55, v0
	v_mov_b32_e32 v56, v0
	v_mov_b32_e32 v57, v0
	v_mov_b32_e32 v58, v0
	v_mov_b32_e32 v59, v0
	v_mov_b32_e32 v60, v0
	v_mov_b32_e32 v61, v0
	v_mov_b32_e32 v62, v0
	v_mov_b32_e32 v63, v0
	v_mov_b32_e32 v64, v0
	v_mov_b32_e32 v65, v0
	v_mov_b32_e32 v66, v0
	v_mov_b32_e32 v67, v0
	v_mov_b32_e32 v68, v0
	v_mov_b32_e32 v69, v0
	v_mov_b32_e32 v70, v0
	v_mov_b32_e32 v71, v0
	v_mov_b32_e32 v72, v0
	v_mov_b32_e32 v73, v0
	v_mov_b32_e32 v74, v0
	v_mov_b32_e32 v75, v0
	v_mov_b32_e32 v76, v0
	v_mov_b32_e32 v77, v0
	v_mov_b32_e32 v78, v0
	v_mov_b32_e32 v79, v0
	v_mov_b32_e32 v80, v0
	v_mov_b32_e32 v81, v0
	v_mov_b32_e32 v82, v0
	v_mov_b32_e32 v83, v0
	v_mov_b32_e32 v84, v0
	v_mov_b32_e32 v85, v0
	v_mov_b32_e32 v86, v0
	v_mov_b32_e32 v87, v0
	v_mov_b32_e32 v88, v0
	v_mov_b32_e32 v89, v0
	v_mov_b32_e32 v90, v0
	v_mov_b32_e32 v91, v0
	v_mov_b32_e32 v92, v0
	v_mov_b32_e32 v93, v0
	v_mov_b32_e32 v94, v0
	v_mov_b32_e32 v95, v0
	v_mov_b32_e32 v96, v0
	v_mov_b32_e32 v97, v0
	v_mov_b32_e32 v98, v0
	v_mov_b32_e32 v99, v0
	v_mov_b32_e32 v100, v0
	v_mov_b32_e32 v101, v0
	v_mov_b32_e32 v102, v0
	v_mov_b32_e32 v103, v0
	v_mov_b32_e32 v104, v0
	v_mov_b32_e32 v105, v0
	v_mov_b32_e32 v106, v0
	v_mov_b32_e32 v107, v0
	v_mov_b32_e32 v108, v0
	v_mov_b32_e32 v109, v0
	v_mov_b32_e32 v110, v0
	v_mov_b32_e32 v111, v0
	v_mov_b32_e32 v112, v0
	v_mov_b32_e32 v113, v0
	v_mov_b32_e32 v114, v0
	v_mov_b32_e32 v115, v0
	v_mov_b32_e32 v116, v0
	v_mov_b32_e32 v117, v0
	v_mov_b32_e32 v118, v0
	v_mov_b32_e32 v119, v0
	v_mov_b32_e32 v120, v0
	v_mov_b32_e32 v121, v0
	v_mov_b32_e32 v122, v0
	v_mov_b32_e32 v123, v0
	v_mov_b32_e32 v124, v0
	v_mov_b32_e32 v125, v0
	v_mov_b32_e32 v126, v0
	v_mov_b32_e32 v127, v0
	s_mov_b32 s18, 0xfffea000
	s_mov_b32 s19, -1
	v_readfirstlane_b32 s98, v157
	s_waitcnt vmcnt(8)
	s_barrier
	s_cmp_lt_u32 s98, 0x2000
	s_cbranch_scc1 .Lmoe2_top
	s_barrier
.Lmoe2_top:
	s_add_i32 s15, s14, 0xfffe8000
	s_and_b32 s15, s15, 0x18000
	v_add_u32_e32 v235, s15, v155
	v_add_u32_e32 v236, s15, v156
	ds_read_b128 v[178:181], v235
	ds_read_b128 v[158:161], v236 offset:16384
	ds_read_b128 v[162:165], v236 offset:17408
	ds_read_b128 v[170:173], v236 offset:18432
	ds_read_b128 v[174:177], v236 offset:19456
	ds_read_b128 v[182:185], v235 offset:1024
	ds_read_b128 v[186:189], v235 offset:2048
	ds_read_b128 v[190:193], v235 offset:3072
	s_and_b32 s99, s14, 0x18000
	s_add_i32 s99, s99, s98
	s_mov_b32 m0, s99
	v_lshl_add_u64 v[238:239], v[136:137], 0, s[18:19]
	global_load_lds_dwordx4 v[238:239], off
	s_add_i32 m0, s99, 0x400
	s_nop 0
	global_load_lds_dwordx4 v[136:137], off
	s_waitcnt lgkmcnt(0)
	s_barrier
	s_setprio 1
	v_mfma_f32_16x16x32_bf16 v[124:127], v[158:161], v[178:181], v[124:127]
	v_mfma_f32_16x16x32_bf16 v[120:123], v[162:165], v[178:181], v[120:123]
	v_mfma_f32_16x16x32_bf16 v[116:119], v[170:173], v[178:181], v[116:119]
	v_mfma_f32_16x16x32_bf16 v[112:115], v[174:177], v[178:181], v[112:115]
	v_mfma_f32_16x16x32_bf16 v[108:111], v[158:161], v[182:185], v[108:111]
	v_mfma_f32_16x16x32_bf16 v[104:107], v[162:165], v[182:185], v[104:107]
	v_mfma_f32_16x16x32_bf16 v[100:103], v[170:173], v[182:185], v[100:103]
	v_mfma_f32_16x16x32_bf16 v[96:99], v[174:177], v[182:185], v[96:99]
	v_mfma_f32_16x16x32_bf16 v[92:95], v[158:161], v[186:189], v[92:95]
	v_mfma_f32_16x16x32_bf16 v[88:91], v[162:165], v[186:189], v[88:91]
	v_mfma_f32_16x16x32_bf16 v[84:87], v[170:173], v[186:189], v[84:87]
	v_mfma_f32_16x16x32_bf16 v[80:83], v[174:177], v[186:189], v[80:83]
	v_mfma_f32_16x16x32_bf16 v[76:79], v[158:161], v[190:193], v[76:79]
	v_mfma_f32_16x16x32_bf16 v[72:75], v[162:165], v[190:193], v[72:75]
	v_mfma_f32_16x16x32_bf16 v[68:71], v[170:173], v[190:193], v[68:71]
	v_mfma_f32_16x16x32_bf16 v[64:67], v[174:177], v[190:193], v[64:67]
	s_setprio 0
	s_barrier
; #define GEMM_WAITV(n) asm volatile("s_waitcnt vmcnt(" #n ")" ::: "memory")
; template <bool SWAP>
; __device__ __forceinline__ void gemm_main(f32x4 (&acc)[8][4], const TP& t, int nk, char* lds) {
;     ...
; #pragma unroll 1
;   for (int kt = 0; kt < nk - 3; ++kt) {
;     GEMM_WAITV(8);
;     GEMM_STEP(kt, true)
;   }
; #pragma unroll 1
;   for (int kt = nk - 3; kt < nk; ++kt) {
;     const int rem = nk - kt;
;     if (rem == 3) GEMM_WAITV(8); else if (rem == 2) GEMM_WAITV(4); else GEMM_WAITV(0);
;     GEMM_STEP(kt, false)
;   }
;   __builtin_amdgcn_s_barrier();
	ds_read_b128 v[178:181], v235 offset:4096
	ds_read_b128 v[182:185], v235 offset:5120
	ds_read_b128 v[186:189], v235 offset:6144
	ds_read_b128 v[190:193], v235 offset:7168
	s_add_i32 m0, s99, 0x4000
	s_nop 0
	global_load_lds_dwordx4 v[138:139], off
	s_add_i32 m0, s99, 0x4400
	s_nop 0
	global_load_lds_dwordx4 v[140:141], off
	v_lshl_add_u64 v[136:137], v[136:137], 0, 64
	v_lshl_add_u64 v[138:139], v[138:139], 0, 64
	v_lshl_add_u64 v[140:141], v[140:141], 0, 64
	s_add_i32 s14, s14, 0x8000
	s_waitcnt vmcnt(8)
	s_waitcnt lgkmcnt(0)
	s_barrier
	s_setprio 1
	v_mfma_f32_16x16x32_bf16 v[60:63], v[158:161], v[178:181], v[60:63]
	v_mfma_f32_16x16x32_bf16 v[56:59], v[162:165], v[178:181], v[56:59]
	v_mfma_f32_16x16x32_bf16 v[52:55], v[170:173], v[178:181], v[52:55]
	v_mfma_f32_16x16x32_bf16 v[48:51], v[174:177], v[178:181], v[48:51]
	v_mfma_f32_16x16x32_bf16 v[44:47], v[158:161], v[182:185], v[44:47]
	v_mfma_f32_16x16x32_bf16 v[40:43], v[162:165], v[182:185], v[40:43]
	v_mfma_f32_16x16x32_bf16 v[36:39], v[170:173], v[182:185], v[36:39]
	v_mfma_f32_16x16x32_bf16 v[32:35], v[174:177], v[182:185], v[32:35]
	v_mfma_f32_16x16x32_bf16 v[28:31], v[158:161], v[186:189], v[28:31]
	v_mfma_f32_16x16x32_bf16 v[24:27], v[162:165], v[186:189], v[24:27]
	v_mfma_f32_16x16x32_bf16 v[20:23], v[170:173], v[186:189], v[20:23]
	v_mfma_f32_16x16x32_bf16 v[16:19], v[174:177], v[186:189], v[16:19]
	v_mfma_f32_16x16x32_bf16 v[12:15], v[158:161], v[190:193], v[12:15]
	v_mfma_f32_16x16x32_bf16 v[8:11], v[162:165], v[190:193], v[8:11]
	v_mfma_f32_16x16x32_bf16 v[4:7], v[170:173], v[190:193], v[4:7]
	v_mfma_f32_16x16x32_bf16 v[0:3], v[174:177], v[190:193], v[0:3]
	s_setprio 0
	s_barrier
	s_cmp_lg_u32 s14, 0x2c0000
	s_cbranch_scc1 .Lmoe2_top
	v_add_u32_e32 v235, 0x8000, v155
	v_add_u32_e32 v236, 0x8000, v156
	ds_read_b128 v[178:181], v235
	ds_read_b128 v[158:161], v236 offset:16384
	ds_read_b128 v[162:165], v236 offset:17408
	ds_read_b128 v[170:173], v236 offset:18432
	ds_read_b128 v[174:177], v236 offset:19456
	ds_read_b128 v[182:185], v235 offset:1024
	ds_read_b128 v[186:189], v235 offset:2048
	ds_read_b128 v[190:193], v235 offset:3072
	s_waitcnt lgkmcnt(0)
	s_barrier
	s_setprio 1
	v_mfma_f32_16x16x32_bf16 v[124:127], v[158:161], v[178:181], v[124:127]
	v_mfma_f32_16x16x32_bf16 v[120:123], v[162:165], v[178:181], v[120:123]
	v_mfma_f32_16x16x32_bf16 v[116:119], v[170:173], v[178:181], v[116:119]
	v_mfma_f32_16x16x32_bf16 v[112:115], v[174:177], v[178:181], v[112:115]
	v_mfma_f32_16x16x32_bf16 v[108:111], v[158:161], v[182:185], v[108:111]
	v_mfma_f32_16x16x32_bf16 v[104:107], v[162:165], v[182:185], v[104:107]
	v_mfma_f32_16x16x32_bf16 v[100:103], v[170:173], v[182:185], v[100:103]
	v_mfma_f32_16x16x32_bf16 v[96:99], v[174:177], v[182:185], v[96:99]
	v_mfma_f32_16x16x32_bf16 v[92:95], v[158:161], v[186:189], v[92:95]
	v_mfma_f32_16x16x32_bf16 v[88:91], v[162:165], v[186:189], v[88:91]
	v_mfma_f32_16x16x32_bf16 v[84:87], v[170:173], v[186:189], v[84:87]
	v_mfma_f32_16x16x32_bf16 v[80:83], v[174:177], v[186:189], v[80:83]
	v_mfma_f32_16x16x32_bf16 v[76:79], v[158:161], v[190:193], v[76:79]
	v_mfma_f32_16x16x32_bf16 v[72:75], v[162:165], v[190:193], v[72:75]
	v_mfma_f32_16x16x32_bf16 v[68:71], v[170:173], v[190:193], v[68:71]
	v_mfma_f32_16x16x32_bf16 v[64:67], v[174:177], v[190:193], v[64:67]
	s_setprio 0
	s_barrier
	ds_read_b128 v[178:181], v235 offset:4096
	ds_read_b128 v[182:185], v235 offset:5120
	ds_read_b128 v[186:189], v235 offset:6144
	ds_read_b128 v[190:193], v235 offset:7168
	s_waitcnt vmcnt(4)
	s_waitcnt lgkmcnt(0)
	s_barrier
	s_setprio 1
	v_mfma_f32_16x16x32_bf16 v[60:63], v[158:161], v[178:181], v[60:63]
	v_mfma_f32_16x16x32_bf16 v[56:59], v[162:165], v[178:181], v[56:59]
	v_mfma_f32_16x16x32_bf16 v[52:55], v[170:173], v[178:181], v[52:55]
	v_mfma_f32_16x16x32_bf16 v[48:51], v[174:177], v[178:181], v[48:51]
	v_mfma_f32_16x16x32_bf16 v[44:47], v[158:161], v[182:185], v[44:47]
	v_mfma_f32_16x16x32_bf16 v[40:43], v[162:165], v[182:185], v[40:43]
	v_mfma_f32_16x16x32_bf16 v[36:39], v[170:173], v[182:185], v[36:39]
	v_mfma_f32_16x16x32_bf16 v[32:35], v[174:177], v[182:185], v[32:35]
	v_mfma_f32_16x16x32_bf16 v[28:31], v[158:161], v[186:189], v[28:31]
	v_mfma_f32_16x16x32_bf16 v[24:27], v[162:165], v[186:189], v[24:27]
	v_mfma_f32_16x16x32_bf16 v[20:23], v[170:173], v[186:189], v[20:23]
	v_mfma_f32_16x16x32_bf16 v[16:19], v[174:177], v[186:189], v[16:19]
	v_mfma_f32_16x16x32_bf16 v[12:15], v[158:161], v[190:193], v[12:15]
	v_mfma_f32_16x16x32_bf16 v[8:11], v[162:165], v[190:193], v[8:11]
	v_mfma_f32_16x16x32_bf16 v[4:7], v[170:173], v[190:193], v[4:7]
	v_mfma_f32_16x16x32_bf16 v[0:3], v[174:177], v[190:193], v[0:3]
	s_setprio 0
	s_barrier
	v_add_u32_e32 v235, 0x10000, v155
	v_add_u32_e32 v236, 0x10000, v156
	ds_read_b128 v[178:181], v235
	ds_read_b128 v[158:161], v236 offset:16384
	ds_read_b128 v[162:165], v236 offset:17408
	ds_read_b128 v[170:173], v236 offset:18432
	ds_read_b128 v[174:177], v236 offset:19456
	ds_read_b128 v[182:185], v235 offset:1024
	ds_read_b128 v[186:189], v235 offset:2048
	ds_read_b128 v[190:193], v235 offset:3072
	s_waitcnt lgkmcnt(0)
	s_barrier
; #define GEMM_WAITV(n) asm volatile("s_waitcnt vmcnt(" #n ")" ::: "memory")
; template <bool SWAP>
; __device__ __forceinline__ void gemm_main(f32x4 (&acc)[8][4], const TP& t, int nk, char* lds) {
;     ...
; #pragma unroll 1
;   for (int kt = 0; kt < nk - 3; ++kt) {
;     GEMM_WAITV(8);
;     GEMM_STEP(kt, true)
;   }
; #pragma unroll 1
;   for (int kt = nk - 3; kt < nk; ++kt) {
;     const int rem = nk - kt;
;     if (rem == 3) GEMM_WAITV(8); else if (rem == 2) GEMM_WAITV(4); else GEMM_WAITV(0);
;     GEMM_STEP(kt, false)
;   }
;   __builtin_amdgcn_s_barrier();
	s_setprio 1
	v_mfma_f32_16x16x32_bf16 v[124:127], v[158:161], v[178:181], v[124:127]
	v_mfma_f32_16x16x32_bf16 v[120:123], v[162:165], v[178:181], v[120:123]
	v_mfma_f32_16x16x32_bf16 v[116:119], v[170:173], v[178:181], v[116:119]
	v_mfma_f32_16x16x32_bf16 v[112:115], v[174:177], v[178:181], v[112:115]
	v_mfma_f32_16x16x32_bf16 v[108:111], v[158:161], v[182:185], v[108:111]
	v_mfma_f32_16x16x32_bf16 v[104:107], v[162:165], v[182:185], v[104:107]
	v_mfma_f32_16x16x32_bf16 v[100:103], v[170:173], v[182:185], v[100:103]
	v_mfma_f32_16x16x32_bf16 v[96:99], v[174:177], v[182:185], v[96:99]
	v_mfma_f32_16x16x32_bf16 v[92:95], v[158:161], v[186:189], v[92:95]
	v_mfma_f32_16x16x32_bf16 v[88:91], v[162:165], v[186:189], v[88:91]
	v_mfma_f32_16x16x32_bf16 v[84:87], v[170:173], v[186:189], v[84:87]
	v_mfma_f32_16x16x32_bf16 v[80:83], v[174:177], v[186:189], v[80:83]
	v_mfma_f32_16x16x32_bf16 v[76:79], v[158:161], v[190:193], v[76:79]
	v_mfma_f32_16x16x32_bf16 v[72:75], v[162:165], v[190:193], v[72:75]
	v_mfma_f32_16x16x32_bf16 v[68:71], v[170:173], v[190:193], v[68:71]
	v_mfma_f32_16x16x32_bf16 v[64:67], v[174:177], v[190:193], v[64:67]
	s_setprio 0
	s_barrier
	ds_read_b128 v[178:181], v235 offset:4096
	ds_read_b128 v[182:185], v235 offset:5120
	ds_read_b128 v[186:189], v235 offset:6144
	ds_read_b128 v[190:193], v235 offset:7168
	s_waitcnt vmcnt(0)
	s_waitcnt lgkmcnt(0)
	s_barrier
	s_setprio 1
	v_mfma_f32_16x16x32_bf16 v[60:63], v[158:161], v[178:181], v[60:63]
	v_mfma_f32_16x16x32_bf16 v[56:59], v[162:165], v[178:181], v[56:59]
	v_mfma_f32_16x16x32_bf16 v[52:55], v[170:173], v[178:181], v[52:55]
	v_mfma_f32_16x16x32_bf16 v[48:51], v[174:177], v[178:181], v[48:51]
	v_mfma_f32_16x16x32_bf16 v[44:47], v[158:161], v[182:185], v[44:47]
	v_mfma_f32_16x16x32_bf16 v[40:43], v[162:165], v[182:185], v[40:43]
	v_mfma_f32_16x16x32_bf16 v[36:39], v[170:173], v[182:185], v[36:39]
	v_mfma_f32_16x16x32_bf16 v[32:35], v[174:177], v[182:185], v[32:35]
	v_mfma_f32_16x16x32_bf16 v[28:31], v[158:161], v[186:189], v[28:31]
	v_mfma_f32_16x16x32_bf16 v[24:27], v[162:165], v[186:189], v[24:27]
	v_mfma_f32_16x16x32_bf16 v[20:23], v[170:173], v[186:189], v[20:23]
	v_mfma_f32_16x16x32_bf16 v[16:19], v[174:177], v[186:189], v[16:19]
	v_mfma_f32_16x16x32_bf16 v[12:15], v[158:161], v[190:193], v[12:15]
	v_mfma_f32_16x16x32_bf16 v[8:11], v[162:165], v[190:193], v[8:11]
	v_mfma_f32_16x16x32_bf16 v[4:7], v[170:173], v[190:193], v[4:7]
	v_mfma_f32_16x16x32_bf16 v[0:3], v[174:177], v[190:193], v[0:3]
	s_setprio 0
	s_barrier
	v_add_u32_e32 v235, 0x18000, v155
	v_add_u32_e32 v236, 0x18000, v156
	ds_read_b128 v[178:181], v235
	ds_read_b128 v[158:161], v236 offset:16384
	ds_read_b128 v[162:165], v236 offset:17408
	ds_read_b128 v[170:173], v236 offset:18432
	ds_read_b128 v[174:177], v236 offset:19456
	ds_read_b128 v[182:185], v235 offset:1024
	ds_read_b128 v[186:189], v235 offset:2048
	ds_read_b128 v[190:193], v235 offset:3072
	s_waitcnt lgkmcnt(0)
	s_barrier
	s_setprio 1
	v_mfma_f32_16x16x32_bf16 v[124:127], v[158:161], v[178:181], v[124:127]
	v_mfma_f32_16x16x32_bf16 v[120:123], v[162:165], v[178:181], v[120:123]
	v_mfma_f32_16x16x32_bf16 v[116:119], v[170:173], v[178:181], v[116:119]
	v_mfma_f32_16x16x32_bf16 v[112:115], v[174:177], v[178:181], v[112:115]
	v_mfma_f32_16x16x32_bf16 v[108:111], v[158:161], v[182:185], v[108:111]
	v_mfma_f32_16x16x32_bf16 v[104:107], v[162:165], v[182:185], v[104:107]
	v_mfma_f32_16x16x32_bf16 v[100:103], v[170:173], v[182:185], v[100:103]
	v_mfma_f32_16x16x32_bf16 v[96:99], v[174:177], v[182:185], v[96:99]
	v_mfma_f32_16x16x32_bf16 v[92:95], v[158:161], v[186:189], v[92:95]
	v_mfma_f32_16x16x32_bf16 v[88:91], v[162:165], v[186:189], v[88:91]
	v_mfma_f32_16x16x32_bf16 v[84:87], v[170:173], v[186:189], v[84:87]
	v_mfma_f32_16x16x32_bf16 v[80:83], v[174:177], v[186:189], v[80:83]
	v_mfma_f32_16x16x32_bf16 v[76:79], v[158:161], v[190:193], v[76:79]
	v_mfma_f32_16x16x32_bf16 v[72:75], v[162:165], v[190:193], v[72:75]
	v_mfma_f32_16x16x32_bf16 v[68:71], v[170:173], v[190:193], v[68:71]
	v_mfma_f32_16x16x32_bf16 v[64:67], v[174:177], v[190:193], v[64:67]
	s_setprio 0
	s_barrier
	ds_read_b128 v[178:181], v235 offset:4096
	ds_read_b128 v[182:185], v235 offset:5120
	ds_read_b128 v[186:189], v235 offset:6144
	ds_read_b128 v[190:193], v235 offset:7168
	s_waitcnt lgkmcnt(0)
	s_barrier
	s_setprio 1
	v_mfma_f32_16x16x32_bf16 v[60:63], v[158:161], v[178:181], v[60:63]
	v_mfma_f32_16x16x32_bf16 v[56:59], v[162:165], v[178:181], v[56:59]
	v_mfma_f32_16x16x32_bf16 v[52:55], v[170:173], v[178:181], v[52:55]
	v_mfma_f32_16x16x32_bf16 v[48:51], v[174:177], v[178:181], v[48:51]
	v_mfma_f32_16x16x32_bf16 v[44:47], v[158:161], v[182:185], v[44:47]
	v_mfma_f32_16x16x32_bf16 v[40:43], v[162:165], v[182:185], v[40:43]
	v_mfma_f32_16x16x32_bf16 v[36:39], v[170:173], v[182:185], v[36:39]
	v_mfma_f32_16x16x32_bf16 v[32:35], v[174:177], v[182:185], v[32:35]
	v_mfma_f32_16x16x32_bf16 v[28:31], v[158:161], v[186:189], v[28:31]
	v_mfma_f32_16x16x32_bf16 v[24:27], v[162:165], v[186:189], v[24:27]
	v_mfma_f32_16x16x32_bf16 v[20:23], v[170:173], v[186:189], v[20:23]
	v_mfma_f32_16x16x32_bf16 v[16:19], v[174:177], v[186:189], v[16:19]
	v_mfma_f32_16x16x32_bf16 v[12:15], v[158:161], v[190:193], v[12:15]
	v_mfma_f32_16x16x32_bf16 v[8:11], v[162:165], v[190:193], v[8:11]
	v_mfma_f32_16x16x32_bf16 v[4:7], v[170:173], v[190:193], v[4:7]
	v_mfma_f32_16x16x32_bf16 v[0:3], v[174:177], v[190:193], v[0:3]
	s_setprio 0
	s_barrier
	s_cmp_ge_u32 s98, 0x2000
	s_cbranch_scc1 .Lmoe2_done
	s_barrier
